# v30 + GEMM K-loops: every s_setprio deleted (A/B of the template's per-segment priority flips)
# speedup vs baseline: 1.0050x; 1.0022x over previous
.LBB0_161:
	s_ashr_i32 s23, s22, 31
	s_lshl_b64 s[8:9], s[22:23], 20
	v_readlane_b32 s20, v254, 38
	v_readlane_b32 s21, v254, 39
	s_add_u32 s8, s20, s8
	s_addc_u32 s9, s21, s9
	s_and_b64 s[20:21], s[40:41], exec
	s_cselect_b32 s13, s9, s43
	s_cselect_b32 s20, s8, s42
	s_ashr_i32 s19, s18, 31
	s_lshl_b64 s[28:29], s[18:19], 20
	v_readlane_b32 s30, v254, 22
	v_readlane_b32 s31, v254, 23
	s_add_u32 s28, s30, s28
	s_addc_u32 s29, s31, s29
	s_and_b64 s[30:31], s[40:41], exec
	s_cselect_b32 s19, s29, s45
	s_cselect_b32 s21, s28, s44
	s_add_u32 s42, s42, 0x80080
	s_addc_u32 s43, s43, 0
	s_add_u32 s23, s44, 0x100
	s_addc_u32 s25, s45, 0
	s_mov_b32 s30, -2
	v_readlane_b32 s52, v255, 20
	v_readlane_b32 s53, v255, 21
	v_readlane_b32 s72, v255, 22
	v_readlane_b32 s73, v255, 23
	s_mov_b64 s[74:75], 0x80
	s_add_u32 s31, s42, 0xfff80080
	s_addc_u32 s44, s43, -1
	s_add_i32 s47, 0, 0x10000
	s_cmp_eq_u32 s30, 28
	s_cselect_b32 s49, s13, s44
	s_cselect_b32 s48, s20, s31
	ds_read_b128 v[144:147], v1
	ds_read_b128 v[148:151], v141
	s_cselect_b32 s45, s19, s25
	s_cselect_b32 s44, s21, s23
	s_add_i32 s31, 0, 0x14000
	ds_read_b128 v[152:155], v1 offset:2048
	ds_read_b128 v[156:159], v141 offset:2048
	ds_read_b128 v[160:163], v1 offset:16384
	ds_read_b128 v[164:167], v141 offset:16384
	ds_read_b128 v[168:171], v1 offset:18432
	ds_read_b128 v[172:175], v141 offset:18432
	s_add_i32 m0, s34, 0xc000
	ds_read_b128 v[176:179], v142
	ds_read_b128 v[184:187], v142 offset:2048
	ds_read_b128 v[188:191], v143
	ds_read_b128 v[192:195], v143 offset:2048
	ds_read_b128 v[196:199], v142 offset:4096
	ds_read_b128 v[200:203], v142 offset:6144
	ds_read_b128 v[204:207], v143 offset:4096
	ds_read_b128 v[208:211], v143 offset:6144
	global_load_lds_dwordx4 v138, s[42:43]
	s_add_i32 m0, s34, 0xe000
	s_nop 0
	global_load_lds_dwordx4 v134, s[42:43]
	s_waitcnt vmcnt(8)
	s_waitcnt lgkmcnt(0)
	s_barrier
	v_mfma_f32_16x16x32_bf16 v[128:131], v[144:147], v[176:179], 0
	v_mfma_f32_16x16x32_bf16 v[124:127], v[152:155], v[176:179], 0
	v_mfma_f32_16x16x32_bf16 v[112:115], v[144:147], v[184:187], 0
	v_mfma_f32_16x16x32_bf16 v[108:111], v[152:155], v[184:187], 0
	v_mfma_f32_16x16x32_bf16 v[96:99], v[144:147], v[196:199], 0
	v_mfma_f32_16x16x32_bf16 v[92:95], v[152:155], v[196:199], 0
	v_mfma_f32_16x16x32_bf16 v[80:83], v[144:147], v[200:203], 0
	v_mfma_f32_16x16x32_bf16 v[76:79], v[152:155], v[200:203], 0
	v_mfma_f32_16x16x32_bf16 v[128:131], v[148:151], v[188:191], v[128:131]
	v_mfma_f32_16x16x32_bf16 v[124:127], v[156:159], v[188:191], v[124:127]
	v_mfma_f32_16x16x32_bf16 v[112:115], v[148:151], v[192:195], v[112:115]
	v_mfma_f32_16x16x32_bf16 v[108:111], v[156:159], v[192:195], v[108:111]
	v_mfma_f32_16x16x32_bf16 v[96:99], v[148:151], v[204:207], v[96:99]
	v_mfma_f32_16x16x32_bf16 v[92:95], v[156:159], v[204:207], v[92:95]
	v_mfma_f32_16x16x32_bf16 v[80:83], v[148:151], v[208:211], v[80:83]
	v_mfma_f32_16x16x32_bf16 v[76:79], v[156:159], v[208:211], v[76:79]
	v_mfma_f32_16x16x32_bf16 v[120:123], v[160:163], v[176:179], 0
	v_mfma_f32_16x16x32_bf16 v[116:119], v[168:171], v[176:179], 0
	v_mfma_f32_16x16x32_bf16 v[104:107], v[160:163], v[184:187], 0
	v_mfma_f32_16x16x32_bf16 v[100:103], v[168:171], v[184:187], 0
	v_mfma_f32_16x16x32_bf16 v[88:91], v[160:163], v[196:199], 0
	v_mfma_f32_16x16x32_bf16 v[84:87], v[168:171], v[196:199], 0
	v_mfma_f32_16x16x32_bf16 v[72:75], v[160:163], v[200:203], 0
	v_mfma_f32_16x16x32_bf16 v[68:71], v[168:171], v[200:203], 0
	v_mfma_f32_16x16x32_bf16 v[120:123], v[164:167], v[188:191], v[120:123]
	v_mfma_f32_16x16x32_bf16 v[116:119], v[172:175], v[188:191], v[116:119]
	v_mfma_f32_16x16x32_bf16 v[104:107], v[164:167], v[192:195], v[104:107]
	v_mfma_f32_16x16x32_bf16 v[100:103], v[172:175], v[192:195], v[100:103]
	v_mfma_f32_16x16x32_bf16 v[88:91], v[164:167], v[204:207], v[88:91]
	v_mfma_f32_16x16x32_bf16 v[84:87], v[172:175], v[204:207], v[84:87]
	v_mfma_f32_16x16x32_bf16 v[72:75], v[164:167], v[208:211], v[72:75]
	v_mfma_f32_16x16x32_bf16 v[68:71], v[172:175], v[208:211], v[68:71]
	s_barrier
	s_add_i32 s47, s47, s33
	s_mov_b32 m0, s47
	ds_read_b128 v[176:179], v142 offset:16384
	ds_read_b128 v[184:187], v142 offset:18432
	ds_read_b128 v[188:191], v143 offset:16384
	ds_read_b128 v[192:195], v143 offset:18432
	ds_read_b128 v[196:199], v142 offset:20480
	ds_read_b128 v[200:203], v142 offset:22528
	ds_read_b128 v[204:207], v143 offset:20480
	ds_read_b128 v[208:211], v143 offset:22528
	global_load_lds_dwordx4 v136, s[44:45]
	s_add_i32 m0, s47, 0x2000
	s_add_u32 s50, s44, 0x80000
	s_addc_u32 s51, s45, 0
	s_add_i32 s31, s31, s33
	global_load_lds_dwordx4 v132, s[44:45]
	s_mov_b32 m0, s31
	s_nop 0
	global_load_lds_dwordx4 v136, s[50:51]
	s_add_i32 m0, s31, 0x2000
	s_nop 0
	global_load_lds_dwordx4 v132, s[50:51]
	s_mov_b32 m0, s34
	s_nop 0
	global_load_lds_dwordx4 v138, s[48:49]
	s_mov_b32 m0, s35
	s_nop 0
	global_load_lds_dwordx4 v134, s[48:49]
	s_waitcnt vmcnt(8)
	s_waitcnt lgkmcnt(0)
	s_barrier
	v_mfma_f32_16x16x32_bf16 v[64:67], v[144:147], v[176:179], 0
	v_mfma_f32_16x16x32_bf16 v[60:63], v[152:155], v[176:179], 0
	v_mfma_f32_16x16x32_bf16 v[48:51], v[144:147], v[184:187], 0
	v_mfma_f32_16x16x32_bf16 v[44:47], v[152:155], v[184:187], 0
	v_mfma_f32_16x16x32_bf16 v[30:33], v[144:147], v[196:199], 0
	v_mfma_f32_16x16x32_bf16 v[26:29], v[152:155], v[196:199], 0
	v_mfma_f32_16x16x32_bf16 v[14:17], v[144:147], v[200:203], 0
	v_mfma_f32_16x16x32_bf16 v[10:13], v[152:155], v[200:203], 0
	v_mfma_f32_16x16x32_bf16 v[64:67], v[148:151], v[188:191], v[64:67]
	v_mfma_f32_16x16x32_bf16 v[60:63], v[156:159], v[188:191], v[60:63]
	v_mfma_f32_16x16x32_bf16 v[48:51], v[148:151], v[192:195], v[48:51]
	v_mfma_f32_16x16x32_bf16 v[44:47], v[156:159], v[192:195], v[44:47]
	v_mfma_f32_16x16x32_bf16 v[30:33], v[148:151], v[204:207], v[30:33]
	v_mfma_f32_16x16x32_bf16 v[26:29], v[156:159], v[204:207], v[26:29]
	v_mfma_f32_16x16x32_bf16 v[14:17], v[148:151], v[208:211], v[14:17]
	v_mfma_f32_16x16x32_bf16 v[10:13], v[156:159], v[208:211], v[10:13]
	v_mfma_f32_16x16x32_bf16 v[56:59], v[160:163], v[176:179], 0
	v_mfma_f32_16x16x32_bf16 v[52:55], v[168:171], v[176:179], 0
	v_mfma_f32_16x16x32_bf16 v[40:43], v[160:163], v[184:187], 0
	v_mfma_f32_16x16x32_bf16 v[36:39], v[168:171], v[184:187], 0
	v_mfma_f32_16x16x32_bf16 v[22:25], v[160:163], v[196:199], 0
	v_mfma_f32_16x16x32_bf16 v[18:21], v[168:171], v[196:199], 0
	v_mfma_f32_16x16x32_bf16 v[6:9], v[160:163], v[200:203], 0
	v_mfma_f32_16x16x32_bf16 v[2:5], v[168:171], v[200:203], 0
	v_mfma_f32_16x16x32_bf16 v[56:59], v[164:167], v[188:191], v[56:59]
	v_mfma_f32_16x16x32_bf16 v[52:55], v[172:175], v[188:191], v[52:55]
	v_mfma_f32_16x16x32_bf16 v[40:43], v[164:167], v[192:195], v[40:43]
	v_mfma_f32_16x16x32_bf16 v[36:39], v[172:175], v[192:195], v[36:39]
	v_mfma_f32_16x16x32_bf16 v[22:25], v[164:167], v[204:207], v[22:25]
	v_mfma_f32_16x16x32_bf16 v[18:21], v[172:175], v[204:207], v[18:21]
	v_mfma_f32_16x16x32_bf16 v[6:9], v[164:167], v[208:211], v[6:9]
	v_mfma_f32_16x16x32_bf16 v[2:5], v[172:175], v[208:211], v[2:5]
	s_barrier
	s_add_i32 s31, 0, 0x18000
	ds_read_b128 v[144:147], v1 offset:32768
	ds_read_b128 v[148:151], v141 offset:32768
	s_add_i32 s47, 0, 0x1c000
	ds_read_b128 v[152:155], v1 offset:34816
	ds_read_b128 v[156:159], v141 offset:34816
	ds_read_b128 v[160:163], v1 offset:49152
	ds_read_b128 v[164:167], v141 offset:49152
	ds_read_b128 v[168:171], v1 offset:51200
	ds_read_b128 v[172:175], v141 offset:51200
	s_mov_b64 s[100:101], s[48:49]
	s_add_u32 s48, s48, 0x80000
	s_addc_u32 s49, s49, 0
	s_mov_b32 m0, s54
	ds_read_b128 v[176:179], v142 offset:32768
	ds_read_b128 v[184:187], v142 offset:34816
	ds_read_b128 v[188:191], v143 offset:32768
	ds_read_b128 v[192:195], v143 offset:34816
	ds_read_b128 v[196:199], v142 offset:36864
	ds_read_b128 v[200:203], v142 offset:38912
	ds_read_b128 v[204:207], v143 offset:36864
	ds_read_b128 v[208:211], v143 offset:38912
	global_load_lds_dwordx4 v138, s[48:49]
	s_mov_b32 m0, s55
	s_nop 0
	global_load_lds_dwordx4 v134, s[48:49]
	s_waitcnt vmcnt(8)
	s_waitcnt lgkmcnt(0)
	s_barrier
	v_mfma_f32_16x16x32_bf16 v[128:131], v[144:147], v[176:179], v[128:131]
	v_mfma_f32_16x16x32_bf16 v[124:127], v[152:155], v[176:179], v[124:127]
	v_mfma_f32_16x16x32_bf16 v[112:115], v[144:147], v[184:187], v[112:115]
	v_mfma_f32_16x16x32_bf16 v[108:111], v[152:155], v[184:187], v[108:111]
	v_mfma_f32_16x16x32_bf16 v[96:99], v[144:147], v[196:199], v[96:99]
	v_mfma_f32_16x16x32_bf16 v[92:95], v[152:155], v[196:199], v[92:95]
	v_mfma_f32_16x16x32_bf16 v[80:83], v[144:147], v[200:203], v[80:83]
	v_mfma_f32_16x16x32_bf16 v[76:79], v[152:155], v[200:203], v[76:79]
	v_mfma_f32_16x16x32_bf16 v[128:131], v[148:151], v[188:191], v[128:131]
	v_mfma_f32_16x16x32_bf16 v[124:127], v[156:159], v[188:191], v[124:127]
	v_mfma_f32_16x16x32_bf16 v[112:115], v[148:151], v[192:195], v[112:115]
	v_mfma_f32_16x16x32_bf16 v[108:111], v[156:159], v[192:195], v[108:111]
	v_mfma_f32_16x16x32_bf16 v[96:99], v[148:151], v[204:207], v[96:99]
	v_mfma_f32_16x16x32_bf16 v[92:95], v[156:159], v[204:207], v[92:95]
	v_mfma_f32_16x16x32_bf16 v[80:83], v[148:151], v[208:211], v[80:83]
	v_mfma_f32_16x16x32_bf16 v[76:79], v[156:159], v[208:211], v[76:79]
	v_mfma_f32_16x16x32_bf16 v[120:123], v[160:163], v[176:179], v[120:123]
	v_mfma_f32_16x16x32_bf16 v[116:119], v[168:171], v[176:179], v[116:119]
	v_mfma_f32_16x16x32_bf16 v[104:107], v[160:163], v[184:187], v[104:107]
	v_mfma_f32_16x16x32_bf16 v[100:103], v[168:171], v[184:187], v[100:103]
	v_mfma_f32_16x16x32_bf16 v[88:91], v[160:163], v[196:199], v[88:91]
	v_mfma_f32_16x16x32_bf16 v[84:87], v[168:171], v[196:199], v[84:87]
	v_mfma_f32_16x16x32_bf16 v[72:75], v[160:163], v[200:203], v[72:75]
	v_mfma_f32_16x16x32_bf16 v[68:71], v[168:171], v[200:203], v[68:71]
	v_mfma_f32_16x16x32_bf16 v[120:123], v[164:167], v[188:191], v[120:123]
	v_mfma_f32_16x16x32_bf16 v[116:119], v[172:175], v[188:191], v[116:119]
	v_mfma_f32_16x16x32_bf16 v[104:107], v[164:167], v[192:195], v[104:107]
	v_mfma_f32_16x16x32_bf16 v[100:103], v[172:175], v[192:195], v[100:103]
	v_mfma_f32_16x16x32_bf16 v[88:91], v[164:167], v[204:207], v[88:91]
	v_mfma_f32_16x16x32_bf16 v[84:87], v[172:175], v[204:207], v[84:87]
	v_mfma_f32_16x16x32_bf16 v[72:75], v[164:167], v[208:211], v[72:75]
	v_mfma_f32_16x16x32_bf16 v[68:71], v[172:175], v[208:211], v[68:71]
	s_barrier
	s_add_i32 s31, s31, s33
	s_add_i32 m0, s31, 0xffffff80
	ds_read_b128 v[176:179], v142 offset:49152
	ds_read_b128 v[184:187], v142 offset:51200
	ds_read_b128 v[188:191], v143 offset:49152
	ds_read_b128 v[192:195], v143 offset:51200
	ds_read_b128 v[196:199], v142 offset:53248
	ds_read_b128 v[200:203], v142 offset:55296
	ds_read_b128 v[204:207], v143 offset:53248
	ds_read_b128 v[208:211], v143 offset:55296
	global_load_lds_dwordx4 v136, s[44:45] offset:128
	s_add_i32 m0, s31, 0x1f80
	s_mov_b64 s[98:99], s[44:45]
	s_add_u32 s44, s44, 0x80080
	s_addc_u32 s45, s45, 0
	s_add_i32 s31, s47, s33
	global_load_lds_dwordx4 v132, s[98:99] offset:128
	s_mov_b32 m0, s31
	s_nop 0
	global_load_lds_dwordx4 v136, s[44:45]
	s_add_i32 m0, s31, 0x2000
	s_nop 0
	global_load_lds_dwordx4 v132, s[44:45]
	s_add_i32 m0, s56, 0xffffff80
	s_nop 0
	global_load_lds_dwordx4 v138, s[100:101] offset:128
	s_add_i32 m0, s57, 0xffffff80
	s_nop 0
	global_load_lds_dwordx4 v134, s[100:101] offset:128
	s_waitcnt vmcnt(8)
	s_waitcnt lgkmcnt(0)
	s_barrier
	v_mfma_f32_16x16x32_bf16 v[64:67], v[144:147], v[176:179], v[64:67]
	v_mfma_f32_16x16x32_bf16 v[60:63], v[152:155], v[176:179], v[60:63]
	v_mfma_f32_16x16x32_bf16 v[48:51], v[144:147], v[184:187], v[48:51]
	v_mfma_f32_16x16x32_bf16 v[44:47], v[152:155], v[184:187], v[44:47]
	v_mfma_f32_16x16x32_bf16 v[30:33], v[144:147], v[196:199], v[30:33]
	v_mfma_f32_16x16x32_bf16 v[26:29], v[152:155], v[196:199], v[26:29]
	v_mfma_f32_16x16x32_bf16 v[14:17], v[144:147], v[200:203], v[14:17]
	v_mfma_f32_16x16x32_bf16 v[10:13], v[152:155], v[200:203], v[10:13]
	v_mfma_f32_16x16x32_bf16 v[64:67], v[148:151], v[188:191], v[64:67]
	v_mfma_f32_16x16x32_bf16 v[60:63], v[156:159], v[188:191], v[60:63]
	v_mfma_f32_16x16x32_bf16 v[48:51], v[148:151], v[192:195], v[48:51]
	v_mfma_f32_16x16x32_bf16 v[44:47], v[156:159], v[192:195], v[44:47]
	v_mfma_f32_16x16x32_bf16 v[30:33], v[148:151], v[204:207], v[30:33]
	v_mfma_f32_16x16x32_bf16 v[26:29], v[156:159], v[204:207], v[26:29]
	v_mfma_f32_16x16x32_bf16 v[14:17], v[148:151], v[208:211], v[14:17]
	v_mfma_f32_16x16x32_bf16 v[10:13], v[156:159], v[208:211], v[10:13]
	v_mfma_f32_16x16x32_bf16 v[56:59], v[160:163], v[176:179], v[56:59]
	v_mfma_f32_16x16x32_bf16 v[52:55], v[168:171], v[176:179], v[52:55]
	v_mfma_f32_16x16x32_bf16 v[40:43], v[160:163], v[184:187], v[40:43]
	v_mfma_f32_16x16x32_bf16 v[36:39], v[168:171], v[184:187], v[36:39]
	v_mfma_f32_16x16x32_bf16 v[22:25], v[160:163], v[196:199], v[22:25]
	v_mfma_f32_16x16x32_bf16 v[18:21], v[168:171], v[196:199], v[18:21]
	v_mfma_f32_16x16x32_bf16 v[6:9], v[160:163], v[200:203], v[6:9]
	v_mfma_f32_16x16x32_bf16 v[2:5], v[168:171], v[200:203], v[2:5]
	v_mfma_f32_16x16x32_bf16 v[56:59], v[164:167], v[188:191], v[56:59]
	v_mfma_f32_16x16x32_bf16 v[52:55], v[172:175], v[188:191], v[52:55]
	v_mfma_f32_16x16x32_bf16 v[40:43], v[164:167], v[192:195], v[40:43]
	v_mfma_f32_16x16x32_bf16 v[36:39], v[172:175], v[192:195], v[36:39]
	v_mfma_f32_16x16x32_bf16 v[22:25], v[164:167], v[204:207], v[22:25]
	v_mfma_f32_16x16x32_bf16 v[18:21], v[172:175], v[204:207], v[18:21]
	v_mfma_f32_16x16x32_bf16 v[6:9], v[164:167], v[208:211], v[6:9]
	v_mfma_f32_16x16x32_bf16 v[2:5], v[172:175], v[208:211], v[2:5]
	s_barrier
	s_add_i32 s30, s30, 2
	s_add_u32 s42, s42, 0x100
	s_addc_u32 s43, s43, 0
	s_add_u32 s23, s23, 0x100
	s_addc_u32 s25, s25, 0
	s_cmp_gt_u32 s30, 29
	s_cbranch_scc1 .Lpeel_done_P1
.LBB0_162:
	s_add_u32 s31, s42, 0xfff80080
	s_addc_u32 s44, s43, -1
	s_add_i32 s47, 0, 0x10000
	s_cmp_eq_u32 s30, 28
	s_cselect_b32 s49, s13, s44
	s_cselect_b32 s48, s20, s31
	ds_read_b128 v[144:147], v1
	ds_read_b128 v[148:151], v141
	s_cselect_b32 s45, s19, s25
	s_cselect_b32 s44, s21, s23
	s_add_i32 s31, 0, 0x14000
	ds_read_b128 v[152:155], v1 offset:2048
	ds_read_b128 v[156:159], v141 offset:2048
	ds_read_b128 v[160:163], v1 offset:16384
	ds_read_b128 v[164:167], v141 offset:16384
	ds_read_b128 v[168:171], v1 offset:18432
	ds_read_b128 v[172:175], v141 offset:18432
	s_add_i32 m0, s34, 0xc000
	ds_read_b128 v[176:179], v142
	ds_read_b128 v[184:187], v142 offset:2048
	ds_read_b128 v[188:191], v143
	ds_read_b128 v[192:195], v143 offset:2048
	ds_read_b128 v[196:199], v142 offset:4096
	ds_read_b128 v[200:203], v142 offset:6144
	ds_read_b128 v[204:207], v143 offset:4096
	ds_read_b128 v[208:211], v143 offset:6144
	global_load_lds_dwordx4 v138, s[42:43]
	s_add_i32 m0, s34, 0xe000
	s_nop 0
	global_load_lds_dwordx4 v134, s[42:43]
	s_waitcnt vmcnt(8)
	s_waitcnt lgkmcnt(0)
	s_barrier
	v_mfma_f32_16x16x32_bf16 v[128:131], v[144:147], v[176:179], v[128:131]
	v_mfma_f32_16x16x32_bf16 v[124:127], v[152:155], v[176:179], v[124:127]
	v_mfma_f32_16x16x32_bf16 v[112:115], v[144:147], v[184:187], v[112:115]
	v_mfma_f32_16x16x32_bf16 v[108:111], v[152:155], v[184:187], v[108:111]
	v_mfma_f32_16x16x32_bf16 v[96:99], v[144:147], v[196:199], v[96:99]
	v_mfma_f32_16x16x32_bf16 v[92:95], v[152:155], v[196:199], v[92:95]
	v_mfma_f32_16x16x32_bf16 v[80:83], v[144:147], v[200:203], v[80:83]
	v_mfma_f32_16x16x32_bf16 v[76:79], v[152:155], v[200:203], v[76:79]
	v_mfma_f32_16x16x32_bf16 v[128:131], v[148:151], v[188:191], v[128:131]
	v_mfma_f32_16x16x32_bf16 v[124:127], v[156:159], v[188:191], v[124:127]
	v_mfma_f32_16x16x32_bf16 v[112:115], v[148:151], v[192:195], v[112:115]
	v_mfma_f32_16x16x32_bf16 v[108:111], v[156:159], v[192:195], v[108:111]
	v_mfma_f32_16x16x32_bf16 v[96:99], v[148:151], v[204:207], v[96:99]
	v_mfma_f32_16x16x32_bf16 v[92:95], v[156:159], v[204:207], v[92:95]
	v_mfma_f32_16x16x32_bf16 v[80:83], v[148:151], v[208:211], v[80:83]
	v_mfma_f32_16x16x32_bf16 v[76:79], v[156:159], v[208:211], v[76:79]
	v_mfma_f32_16x16x32_bf16 v[120:123], v[160:163], v[176:179], v[120:123]
	v_mfma_f32_16x16x32_bf16 v[116:119], v[168:171], v[176:179], v[116:119]
	v_mfma_f32_16x16x32_bf16 v[104:107], v[160:163], v[184:187], v[104:107]
	v_mfma_f32_16x16x32_bf16 v[100:103], v[168:171], v[184:187], v[100:103]
	v_mfma_f32_16x16x32_bf16 v[88:91], v[160:163], v[196:199], v[88:91]
	v_mfma_f32_16x16x32_bf16 v[84:87], v[168:171], v[196:199], v[84:87]
	v_mfma_f32_16x16x32_bf16 v[72:75], v[160:163], v[200:203], v[72:75]
	v_mfma_f32_16x16x32_bf16 v[68:71], v[168:171], v[200:203], v[68:71]
	v_mfma_f32_16x16x32_bf16 v[120:123], v[164:167], v[188:191], v[120:123]
	v_mfma_f32_16x16x32_bf16 v[116:119], v[172:175], v[188:191], v[116:119]
	v_mfma_f32_16x16x32_bf16 v[104:107], v[164:167], v[192:195], v[104:107]
	v_mfma_f32_16x16x32_bf16 v[100:103], v[172:175], v[192:195], v[100:103]
	v_mfma_f32_16x16x32_bf16 v[88:91], v[164:167], v[204:207], v[88:91]
	v_mfma_f32_16x16x32_bf16 v[84:87], v[172:175], v[204:207], v[84:87]
	v_mfma_f32_16x16x32_bf16 v[72:75], v[164:167], v[208:211], v[72:75]
	v_mfma_f32_16x16x32_bf16 v[68:71], v[172:175], v[208:211], v[68:71]
	s_barrier
	s_add_i32 s47, s47, s33
	s_mov_b32 m0, s47
	ds_read_b128 v[176:179], v142 offset:16384
	ds_read_b128 v[184:187], v142 offset:18432
	ds_read_b128 v[188:191], v143 offset:16384
	ds_read_b128 v[192:195], v143 offset:18432
	ds_read_b128 v[196:199], v142 offset:20480
	ds_read_b128 v[200:203], v142 offset:22528
	ds_read_b128 v[204:207], v143 offset:20480
	ds_read_b128 v[208:211], v143 offset:22528
	global_load_lds_dwordx4 v136, s[44:45]
	s_add_i32 m0, s47, 0x2000
	s_add_u32 s50, s44, 0x80000
	s_addc_u32 s51, s45, 0
	s_add_i32 s31, s31, s33
	global_load_lds_dwordx4 v132, s[44:45]
	s_mov_b32 m0, s31
	s_nop 0
	global_load_lds_dwordx4 v136, s[50:51]
	s_add_i32 m0, s31, 0x2000
	s_nop 0
	global_load_lds_dwordx4 v132, s[50:51]
	s_mov_b32 m0, s34
	s_nop 0
	global_load_lds_dwordx4 v138, s[48:49]
	s_mov_b32 m0, s35
	s_nop 0
	global_load_lds_dwordx4 v134, s[48:49]
	s_waitcnt vmcnt(8)
	s_waitcnt lgkmcnt(0)
	s_barrier
	v_mfma_f32_16x16x32_bf16 v[64:67], v[144:147], v[176:179], v[64:67]
	v_mfma_f32_16x16x32_bf16 v[60:63], v[152:155], v[176:179], v[60:63]
	v_mfma_f32_16x16x32_bf16 v[48:51], v[144:147], v[184:187], v[48:51]
	v_mfma_f32_16x16x32_bf16 v[44:47], v[152:155], v[184:187], v[44:47]
	v_mfma_f32_16x16x32_bf16 v[30:33], v[144:147], v[196:199], v[30:33]
	v_mfma_f32_16x16x32_bf16 v[26:29], v[152:155], v[196:199], v[26:29]
	v_mfma_f32_16x16x32_bf16 v[14:17], v[144:147], v[200:203], v[14:17]
	v_mfma_f32_16x16x32_bf16 v[10:13], v[152:155], v[200:203], v[10:13]
	v_mfma_f32_16x16x32_bf16 v[64:67], v[148:151], v[188:191], v[64:67]
	v_mfma_f32_16x16x32_bf16 v[60:63], v[156:159], v[188:191], v[60:63]
	v_mfma_f32_16x16x32_bf16 v[48:51], v[148:151], v[192:195], v[48:51]
	v_mfma_f32_16x16x32_bf16 v[44:47], v[156:159], v[192:195], v[44:47]
	v_mfma_f32_16x16x32_bf16 v[30:33], v[148:151], v[204:207], v[30:33]
	v_mfma_f32_16x16x32_bf16 v[26:29], v[156:159], v[204:207], v[26:29]
	v_mfma_f32_16x16x32_bf16 v[14:17], v[148:151], v[208:211], v[14:17]
	v_mfma_f32_16x16x32_bf16 v[10:13], v[156:159], v[208:211], v[10:13]
	v_mfma_f32_16x16x32_bf16 v[56:59], v[160:163], v[176:179], v[56:59]
	v_mfma_f32_16x16x32_bf16 v[52:55], v[168:171], v[176:179], v[52:55]
	v_mfma_f32_16x16x32_bf16 v[40:43], v[160:163], v[184:187], v[40:43]
	v_mfma_f32_16x16x32_bf16 v[36:39], v[168:171], v[184:187], v[36:39]
	v_mfma_f32_16x16x32_bf16 v[22:25], v[160:163], v[196:199], v[22:25]
	v_mfma_f32_16x16x32_bf16 v[18:21], v[168:171], v[196:199], v[18:21]
	v_mfma_f32_16x16x32_bf16 v[6:9], v[160:163], v[200:203], v[6:9]
	v_mfma_f32_16x16x32_bf16 v[2:5], v[168:171], v[200:203], v[2:5]
	v_mfma_f32_16x16x32_bf16 v[56:59], v[164:167], v[188:191], v[56:59]
	v_mfma_f32_16x16x32_bf16 v[52:55], v[172:175], v[188:191], v[52:55]
	v_mfma_f32_16x16x32_bf16 v[40:43], v[164:167], v[192:195], v[40:43]
	v_mfma_f32_16x16x32_bf16 v[36:39], v[172:175], v[192:195], v[36:39]
	v_mfma_f32_16x16x32_bf16 v[22:25], v[164:167], v[204:207], v[22:25]
	v_mfma_f32_16x16x32_bf16 v[18:21], v[172:175], v[204:207], v[18:21]
	v_mfma_f32_16x16x32_bf16 v[6:9], v[164:167], v[208:211], v[6:9]
	v_mfma_f32_16x16x32_bf16 v[2:5], v[172:175], v[208:211], v[2:5]
	s_barrier
	s_add_i32 s31, 0, 0x18000
	ds_read_b128 v[144:147], v1 offset:32768
	ds_read_b128 v[148:151], v141 offset:32768
	s_add_i32 s47, 0, 0x1c000
	ds_read_b128 v[152:155], v1 offset:34816
	ds_read_b128 v[156:159], v141 offset:34816
	ds_read_b128 v[160:163], v1 offset:49152
	ds_read_b128 v[164:167], v141 offset:49152
	ds_read_b128 v[168:171], v1 offset:51200
	ds_read_b128 v[172:175], v141 offset:51200
	s_mov_b64 s[100:101], s[48:49]
	s_add_u32 s48, s48, 0x80000
	s_addc_u32 s49, s49, 0
	s_mov_b32 m0, s54
	ds_read_b128 v[176:179], v142 offset:32768
	ds_read_b128 v[184:187], v142 offset:34816
	ds_read_b128 v[188:191], v143 offset:32768
	ds_read_b128 v[192:195], v143 offset:34816
	ds_read_b128 v[196:199], v142 offset:36864
	ds_read_b128 v[200:203], v142 offset:38912
	ds_read_b128 v[204:207], v143 offset:36864
	ds_read_b128 v[208:211], v143 offset:38912
	global_load_lds_dwordx4 v138, s[48:49]
	s_mov_b32 m0, s55
	s_nop 0
	global_load_lds_dwordx4 v134, s[48:49]
	s_waitcnt vmcnt(8)
	s_waitcnt lgkmcnt(0)
	s_barrier
	v_mfma_f32_16x16x32_bf16 v[128:131], v[144:147], v[176:179], v[128:131]
	v_mfma_f32_16x16x32_bf16 v[124:127], v[152:155], v[176:179], v[124:127]
	v_mfma_f32_16x16x32_bf16 v[112:115], v[144:147], v[184:187], v[112:115]
	v_mfma_f32_16x16x32_bf16 v[108:111], v[152:155], v[184:187], v[108:111]
	v_mfma_f32_16x16x32_bf16 v[96:99], v[144:147], v[196:199], v[96:99]
	v_mfma_f32_16x16x32_bf16 v[92:95], v[152:155], v[196:199], v[92:95]
	v_mfma_f32_16x16x32_bf16 v[80:83], v[144:147], v[200:203], v[80:83]
	v_mfma_f32_16x16x32_bf16 v[76:79], v[152:155], v[200:203], v[76:79]
	v_mfma_f32_16x16x32_bf16 v[128:131], v[148:151], v[188:191], v[128:131]
	v_mfma_f32_16x16x32_bf16 v[124:127], v[156:159], v[188:191], v[124:127]
	v_mfma_f32_16x16x32_bf16 v[112:115], v[148:151], v[192:195], v[112:115]
	v_mfma_f32_16x16x32_bf16 v[108:111], v[156:159], v[192:195], v[108:111]
	v_mfma_f32_16x16x32_bf16 v[96:99], v[148:151], v[204:207], v[96:99]
	v_mfma_f32_16x16x32_bf16 v[92:95], v[156:159], v[204:207], v[92:95]
	v_mfma_f32_16x16x32_bf16 v[80:83], v[148:151], v[208:211], v[80:83]
	v_mfma_f32_16x16x32_bf16 v[76:79], v[156:159], v[208:211], v[76:79]
	v_mfma_f32_16x16x32_bf16 v[120:123], v[160:163], v[176:179], v[120:123]
	v_mfma_f32_16x16x32_bf16 v[116:119], v[168:171], v[176:179], v[116:119]
	v_mfma_f32_16x16x32_bf16 v[104:107], v[160:163], v[184:187], v[104:107]
	v_mfma_f32_16x16x32_bf16 v[100:103], v[168:171], v[184:187], v[100:103]
	v_mfma_f32_16x16x32_bf16 v[88:91], v[160:163], v[196:199], v[88:91]
	v_mfma_f32_16x16x32_bf16 v[84:87], v[168:171], v[196:199], v[84:87]
	v_mfma_f32_16x16x32_bf16 v[72:75], v[160:163], v[200:203], v[72:75]
	v_mfma_f32_16x16x32_bf16 v[68:71], v[168:171], v[200:203], v[68:71]
	v_mfma_f32_16x16x32_bf16 v[120:123], v[164:167], v[188:191], v[120:123]
	v_mfma_f32_16x16x32_bf16 v[116:119], v[172:175], v[188:191], v[116:119]
	v_mfma_f32_16x16x32_bf16 v[104:107], v[164:167], v[192:195], v[104:107]
	v_mfma_f32_16x16x32_bf16 v[100:103], v[172:175], v[192:195], v[100:103]
	v_mfma_f32_16x16x32_bf16 v[88:91], v[164:167], v[204:207], v[88:91]
	v_mfma_f32_16x16x32_bf16 v[84:87], v[172:175], v[204:207], v[84:87]
	v_mfma_f32_16x16x32_bf16 v[72:75], v[164:167], v[208:211], v[72:75]
	v_mfma_f32_16x16x32_bf16 v[68:71], v[172:175], v[208:211], v[68:71]
	s_barrier
	s_add_i32 s31, s31, s33
	s_add_i32 m0, s31, 0xffffff80
	ds_read_b128 v[176:179], v142 offset:49152
	ds_read_b128 v[184:187], v142 offset:51200
	ds_read_b128 v[188:191], v143 offset:49152
	ds_read_b128 v[192:195], v143 offset:51200
	ds_read_b128 v[196:199], v142 offset:53248
	ds_read_b128 v[200:203], v142 offset:55296
	ds_read_b128 v[204:207], v143 offset:53248
	ds_read_b128 v[208:211], v143 offset:55296
	global_load_lds_dwordx4 v136, s[44:45] offset:128
	s_add_i32 m0, s31, 0x1f80
	s_mov_b64 s[98:99], s[44:45]
	s_add_u32 s44, s44, 0x80080
	s_addc_u32 s45, s45, 0
	s_add_i32 s31, s47, s33
	global_load_lds_dwordx4 v132, s[98:99] offset:128
	s_mov_b32 m0, s31
	s_nop 0
	global_load_lds_dwordx4 v136, s[44:45]
	s_add_i32 m0, s31, 0x2000
	s_nop 0
	global_load_lds_dwordx4 v132, s[44:45]
	s_add_i32 m0, s56, 0xffffff80
	s_nop 0
	global_load_lds_dwordx4 v138, s[100:101] offset:128
	s_add_i32 m0, s57, 0xffffff80
	s_nop 0
	global_load_lds_dwordx4 v134, s[100:101] offset:128
	s_waitcnt vmcnt(8)
	s_waitcnt lgkmcnt(0)
	s_barrier
	v_mfma_f32_16x16x32_bf16 v[64:67], v[144:147], v[176:179], v[64:67]
	v_mfma_f32_16x16x32_bf16 v[60:63], v[152:155], v[176:179], v[60:63]
	v_mfma_f32_16x16x32_bf16 v[48:51], v[144:147], v[184:187], v[48:51]
	v_mfma_f32_16x16x32_bf16 v[44:47], v[152:155], v[184:187], v[44:47]
	v_mfma_f32_16x16x32_bf16 v[30:33], v[144:147], v[196:199], v[30:33]
	v_mfma_f32_16x16x32_bf16 v[26:29], v[152:155], v[196:199], v[26:29]
	v_mfma_f32_16x16x32_bf16 v[14:17], v[144:147], v[200:203], v[14:17]
	v_mfma_f32_16x16x32_bf16 v[10:13], v[152:155], v[200:203], v[10:13]
	v_mfma_f32_16x16x32_bf16 v[64:67], v[148:151], v[188:191], v[64:67]
	v_mfma_f32_16x16x32_bf16 v[60:63], v[156:159], v[188:191], v[60:63]
	v_mfma_f32_16x16x32_bf16 v[48:51], v[148:151], v[192:195], v[48:51]
	v_mfma_f32_16x16x32_bf16 v[44:47], v[156:159], v[192:195], v[44:47]
	v_mfma_f32_16x16x32_bf16 v[30:33], v[148:151], v[204:207], v[30:33]
	v_mfma_f32_16x16x32_bf16 v[26:29], v[156:159], v[204:207], v[26:29]
	v_mfma_f32_16x16x32_bf16 v[14:17], v[148:151], v[208:211], v[14:17]
	v_mfma_f32_16x16x32_bf16 v[10:13], v[156:159], v[208:211], v[10:13]
	v_mfma_f32_16x16x32_bf16 v[56:59], v[160:163], v[176:179], v[56:59]
	v_mfma_f32_16x16x32_bf16 v[52:55], v[168:171], v[176:179], v[52:55]
	v_mfma_f32_16x16x32_bf16 v[40:43], v[160:163], v[184:187], v[40:43]
	v_mfma_f32_16x16x32_bf16 v[36:39], v[168:171], v[184:187], v[36:39]
	v_mfma_f32_16x16x32_bf16 v[22:25], v[160:163], v[196:199], v[22:25]
	v_mfma_f32_16x16x32_bf16 v[18:21], v[168:171], v[196:199], v[18:21]
	v_mfma_f32_16x16x32_bf16 v[6:9], v[160:163], v[200:203], v[6:9]
	v_mfma_f32_16x16x32_bf16 v[2:5], v[168:171], v[200:203], v[2:5]
	v_mfma_f32_16x16x32_bf16 v[56:59], v[164:167], v[188:191], v[56:59]
	v_mfma_f32_16x16x32_bf16 v[52:55], v[172:175], v[188:191], v[52:55]
	v_mfma_f32_16x16x32_bf16 v[40:43], v[164:167], v[192:195], v[40:43]
	v_mfma_f32_16x16x32_bf16 v[36:39], v[172:175], v[192:195], v[36:39]
	v_mfma_f32_16x16x32_bf16 v[22:25], v[164:167], v[204:207], v[22:25]
	v_mfma_f32_16x16x32_bf16 v[18:21], v[172:175], v[204:207], v[18:21]
	v_mfma_f32_16x16x32_bf16 v[6:9], v[164:167], v[208:211], v[6:9]
	v_mfma_f32_16x16x32_bf16 v[2:5], v[172:175], v[208:211], v[2:5]
	s_barrier
	s_add_i32 s30, s30, 2
	s_add_u32 s42, s42, 0x100
	s_addc_u32 s43, s43, 0
	s_add_u32 s23, s23, 0x100
	s_addc_u32 s25, s25, 0
	s_cmp_gt_u32 s30, 29
	s_cbranch_scc0 .LBB0_162

.LBB0_907:
	s_and_b32 s9, 1, s12
	s_cmp_gt_i32 s12, 1
	s_cselect_b32 s24, 10, 12
	s_cmp_eq_u32 s9, 1
	s_cselect_b64 s[18:19], -1, 0
	s_and_b64 s[20:21], s[18:19], exec
	s_cselect_b32 s9, s24, 32
	s_add_i32 s20, s9, -2
	s_add_u32 s22, s22, 0x80080
	s_addc_u32 s23, s23, 0
	s_add_u32 s21, s28, 0x100
	s_addc_u32 s24, s29, 0
	s_mov_b32 s25, 0
	s_waitcnt vmcnt(0)
	v_readlane_b32 s43, v255, 20
	v_readlane_b32 s45, v255, 21
	v_readlane_b32 s66, v255, 22
	v_readlane_b32 s67, v255, 23
	s_mov_b64 s[68:69], 0x80
	s_add_i32 s30, s25, 2
	s_add_u32 s28, s22, 0xfff80080
	s_addc_u32 s29, s23, -1
	s_add_i32 s31, 0, 0x10000
	s_cmp_eq_u32 s20, s25
	s_cselect_b32 s41, s47, s29
	s_cselect_b32 s40, s46, s28
	s_cselect_b32 s29, s49, s24
	s_cselect_b32 s28, s48, s21
	s_add_i32 s25, 0, 0x14000
	ds_read_b128 v[132:135], v1
	ds_read_b128 v[136:139], v204
	ds_read_b128 v[140:143], v1 offset:2048
	ds_read_b128 v[144:147], v204 offset:2048
	ds_read_b128 v[148:151], v1 offset:16384
	ds_read_b128 v[152:155], v204 offset:16384
	ds_read_b128 v[156:159], v1 offset:18432
	ds_read_b128 v[160:163], v204 offset:18432
	s_add_i32 m0, s50, 0xc000
	ds_read_b128 v[164:167], v205
	ds_read_b128 v[168:171], v205 offset:2048
	ds_read_b128 v[172:175], v206
	ds_read_b128 v[176:179], v206 offset:2048
	ds_read_b128 v[190:193], v205 offset:4096
	ds_read_b128 v[194:197], v205 offset:6144
	ds_read_b128 v[198:201], v206 offset:4096
	ds_read_b128 v[232:235], v206 offset:6144
	global_load_lds_dwordx4 v188, s[22:23]
	s_add_i32 m0, s50, 0xe000
	s_nop 0
	global_load_lds_dwordx4 v186, s[22:23]
	s_waitcnt vmcnt(8)
	s_waitcnt lgkmcnt(0)
	s_barrier
	v_mfma_f32_16x16x32_bf16 v[68:71], v[132:135], v[164:167], 0
	v_mfma_f32_16x16x32_bf16 v[72:75], v[140:143], v[164:167], 0
	v_mfma_f32_16x16x32_bf16 v[84:87], v[132:135], v[168:171], 0
	v_mfma_f32_16x16x32_bf16 v[88:91], v[140:143], v[168:171], 0
	v_mfma_f32_16x16x32_bf16 v[100:103], v[132:135], v[190:193], 0
	v_mfma_f32_16x16x32_bf16 v[104:107], v[140:143], v[190:193], 0
	v_mfma_f32_16x16x32_bf16 v[116:119], v[132:135], v[194:197], 0
	v_mfma_f32_16x16x32_bf16 v[120:123], v[140:143], v[194:197], 0
	v_mfma_f32_16x16x32_bf16 v[68:71], v[136:139], v[172:175], v[68:71]
	v_mfma_f32_16x16x32_bf16 v[72:75], v[144:147], v[172:175], v[72:75]
	v_mfma_f32_16x16x32_bf16 v[84:87], v[136:139], v[176:179], v[84:87]
	v_mfma_f32_16x16x32_bf16 v[88:91], v[144:147], v[176:179], v[88:91]
	v_mfma_f32_16x16x32_bf16 v[100:103], v[136:139], v[198:201], v[100:103]
	v_mfma_f32_16x16x32_bf16 v[104:107], v[144:147], v[198:201], v[104:107]
	v_mfma_f32_16x16x32_bf16 v[116:119], v[136:139], v[232:235], v[116:119]
	v_mfma_f32_16x16x32_bf16 v[120:123], v[144:147], v[232:235], v[120:123]
	v_mfma_f32_16x16x32_bf16 v[76:79], v[148:151], v[164:167], 0
	v_mfma_f32_16x16x32_bf16 v[80:83], v[156:159], v[164:167], 0
	v_mfma_f32_16x16x32_bf16 v[92:95], v[148:151], v[168:171], 0
	v_mfma_f32_16x16x32_bf16 v[96:99], v[156:159], v[168:171], 0
	v_mfma_f32_16x16x32_bf16 v[108:111], v[148:151], v[190:193], 0
	v_mfma_f32_16x16x32_bf16 v[112:115], v[156:159], v[190:193], 0
	v_mfma_f32_16x16x32_bf16 v[124:127], v[148:151], v[194:197], 0
	v_mfma_f32_16x16x32_bf16 v[128:131], v[156:159], v[194:197], 0
	v_mfma_f32_16x16x32_bf16 v[76:79], v[152:155], v[172:175], v[76:79]
	v_mfma_f32_16x16x32_bf16 v[80:83], v[160:163], v[172:175], v[80:83]
	v_mfma_f32_16x16x32_bf16 v[92:95], v[152:155], v[176:179], v[92:95]
	v_mfma_f32_16x16x32_bf16 v[96:99], v[160:163], v[176:179], v[96:99]
	v_mfma_f32_16x16x32_bf16 v[108:111], v[152:155], v[198:201], v[108:111]
	v_mfma_f32_16x16x32_bf16 v[112:115], v[160:163], v[198:201], v[112:115]
	v_mfma_f32_16x16x32_bf16 v[124:127], v[152:155], v[232:235], v[124:127]
	v_mfma_f32_16x16x32_bf16 v[128:131], v[160:163], v[232:235], v[128:131]
	s_barrier
	s_add_i32 s31, s31, s33
	s_mov_b32 m0, s31
	ds_read_b128 v[164:167], v205 offset:16384
	ds_read_b128 v[168:171], v205 offset:18432
	ds_read_b128 v[172:175], v206 offset:16384
	ds_read_b128 v[176:179], v206 offset:18432
	ds_read_b128 v[190:193], v205 offset:20480
	ds_read_b128 v[194:197], v205 offset:22528
	ds_read_b128 v[198:201], v206 offset:20480
	ds_read_b128 v[232:235], v206 offset:22528
	global_load_lds_dwordx4 v34, s[28:29]
	s_add_i32 m0, s31, 0x2000
	s_add_u32 s34, s28, 0x80000
	s_addc_u32 s35, s29, 0
	s_add_i32 s25, s25, s33
	global_load_lds_dwordx4 v184, s[28:29]
	s_mov_b32 m0, s25
	s_nop 0
	global_load_lds_dwordx4 v34, s[34:35]
	s_add_i32 m0, s25, 0x2000
	s_nop 0
	global_load_lds_dwordx4 v184, s[34:35]
	s_mov_b32 m0, s50
	s_nop 0
	global_load_lds_dwordx4 v188, s[40:41]
	s_mov_b32 m0, s51
	s_nop 0
	global_load_lds_dwordx4 v186, s[40:41]
	s_waitcnt vmcnt(8)
	s_waitcnt lgkmcnt(0)
	s_barrier
	v_mfma_f32_16x16x32_bf16 v[2:5], v[132:135], v[164:167], 0
	v_mfma_f32_16x16x32_bf16 v[6:9], v[140:143], v[164:167], 0
	v_mfma_f32_16x16x32_bf16 v[18:21], v[132:135], v[168:171], 0
	v_mfma_f32_16x16x32_bf16 v[22:25], v[140:143], v[168:171], 0
	v_mfma_f32_16x16x32_bf16 v[36:39], v[132:135], v[190:193], 0
	v_mfma_f32_16x16x32_bf16 v[40:43], v[140:143], v[190:193], 0
	v_mfma_f32_16x16x32_bf16 v[52:55], v[132:135], v[194:197], 0
	v_mfma_f32_16x16x32_bf16 v[56:59], v[140:143], v[194:197], 0
	v_mfma_f32_16x16x32_bf16 v[2:5], v[136:139], v[172:175], v[2:5]
	v_mfma_f32_16x16x32_bf16 v[6:9], v[144:147], v[172:175], v[6:9]
	v_mfma_f32_16x16x32_bf16 v[18:21], v[136:139], v[176:179], v[18:21]
	v_mfma_f32_16x16x32_bf16 v[22:25], v[144:147], v[176:179], v[22:25]
	v_mfma_f32_16x16x32_bf16 v[36:39], v[136:139], v[198:201], v[36:39]
	v_mfma_f32_16x16x32_bf16 v[40:43], v[144:147], v[198:201], v[40:43]
	v_mfma_f32_16x16x32_bf16 v[52:55], v[136:139], v[232:235], v[52:55]
	v_mfma_f32_16x16x32_bf16 v[56:59], v[144:147], v[232:235], v[56:59]
	v_mfma_f32_16x16x32_bf16 v[10:13], v[148:151], v[164:167], 0
	v_mfma_f32_16x16x32_bf16 v[14:17], v[156:159], v[164:167], 0
	v_mfma_f32_16x16x32_bf16 v[26:29], v[148:151], v[168:171], 0
	v_mfma_f32_16x16x32_bf16 v[30:33], v[156:159], v[168:171], 0
	v_mfma_f32_16x16x32_bf16 v[44:47], v[148:151], v[190:193], 0
	v_mfma_f32_16x16x32_bf16 v[48:51], v[156:159], v[190:193], 0
	v_mfma_f32_16x16x32_bf16 v[60:63], v[148:151], v[194:197], 0
	v_mfma_f32_16x16x32_bf16 v[64:67], v[156:159], v[194:197], 0
	v_mfma_f32_16x16x32_bf16 v[10:13], v[152:155], v[172:175], v[10:13]
	v_mfma_f32_16x16x32_bf16 v[14:17], v[160:163], v[172:175], v[14:17]
	v_mfma_f32_16x16x32_bf16 v[26:29], v[152:155], v[176:179], v[26:29]
	v_mfma_f32_16x16x32_bf16 v[30:33], v[160:163], v[176:179], v[30:33]
	v_mfma_f32_16x16x32_bf16 v[44:47], v[152:155], v[198:201], v[44:47]
	v_mfma_f32_16x16x32_bf16 v[48:51], v[160:163], v[198:201], v[48:51]
	v_mfma_f32_16x16x32_bf16 v[60:63], v[152:155], v[232:235], v[60:63]
	v_mfma_f32_16x16x32_bf16 v[64:67], v[160:163], v[232:235], v[64:67]
	s_barrier
	s_add_i32 s25, 0, 0x18000
	s_add_i32 s31, 0, 0x1c000
	ds_read_b128 v[132:135], v1 offset:32768
	ds_read_b128 v[136:139], v204 offset:32768
	ds_read_b128 v[140:143], v1 offset:34816
	ds_read_b128 v[144:147], v204 offset:34816
	ds_read_b128 v[148:151], v1 offset:49152
	ds_read_b128 v[152:155], v204 offset:49152
	ds_read_b128 v[156:159], v1 offset:51200
	ds_read_b128 v[160:163], v204 offset:51200
	s_add_u32 s34, s40, 0x80000
	s_addc_u32 s35, s41, 0
	s_mov_b32 m0, s52
	ds_read_b128 v[164:167], v205 offset:32768
	ds_read_b128 v[168:171], v205 offset:34816
	ds_read_b128 v[172:175], v206 offset:32768
	ds_read_b128 v[176:179], v206 offset:34816
	ds_read_b128 v[190:193], v205 offset:36864
	ds_read_b128 v[194:197], v205 offset:38912
	ds_read_b128 v[198:201], v206 offset:36864
	ds_read_b128 v[232:235], v206 offset:38912
	global_load_lds_dwordx4 v188, s[34:35]
	s_mov_b32 m0, s53
	s_nop 0
	global_load_lds_dwordx4 v186, s[34:35]
	s_waitcnt vmcnt(8)
	s_waitcnt lgkmcnt(0)
	s_barrier
	v_mfma_f32_16x16x32_bf16 v[68:71], v[132:135], v[164:167], v[68:71]
	v_mfma_f32_16x16x32_bf16 v[72:75], v[140:143], v[164:167], v[72:75]
	v_mfma_f32_16x16x32_bf16 v[84:87], v[132:135], v[168:171], v[84:87]
	v_mfma_f32_16x16x32_bf16 v[88:91], v[140:143], v[168:171], v[88:91]
	v_mfma_f32_16x16x32_bf16 v[100:103], v[132:135], v[190:193], v[100:103]
	v_mfma_f32_16x16x32_bf16 v[104:107], v[140:143], v[190:193], v[104:107]
	v_mfma_f32_16x16x32_bf16 v[116:119], v[132:135], v[194:197], v[116:119]
	v_mfma_f32_16x16x32_bf16 v[120:123], v[140:143], v[194:197], v[120:123]
	v_mfma_f32_16x16x32_bf16 v[68:71], v[136:139], v[172:175], v[68:71]
	v_mfma_f32_16x16x32_bf16 v[72:75], v[144:147], v[172:175], v[72:75]
	v_mfma_f32_16x16x32_bf16 v[84:87], v[136:139], v[176:179], v[84:87]
	v_mfma_f32_16x16x32_bf16 v[88:91], v[144:147], v[176:179], v[88:91]
	v_mfma_f32_16x16x32_bf16 v[100:103], v[136:139], v[198:201], v[100:103]
	v_mfma_f32_16x16x32_bf16 v[104:107], v[144:147], v[198:201], v[104:107]
	v_mfma_f32_16x16x32_bf16 v[116:119], v[136:139], v[232:235], v[116:119]
	v_mfma_f32_16x16x32_bf16 v[120:123], v[144:147], v[232:235], v[120:123]
	v_mfma_f32_16x16x32_bf16 v[76:79], v[148:151], v[164:167], v[76:79]
	v_mfma_f32_16x16x32_bf16 v[80:83], v[156:159], v[164:167], v[80:83]
	v_mfma_f32_16x16x32_bf16 v[92:95], v[148:151], v[168:171], v[92:95]
	v_mfma_f32_16x16x32_bf16 v[96:99], v[156:159], v[168:171], v[96:99]
	v_mfma_f32_16x16x32_bf16 v[108:111], v[148:151], v[190:193], v[108:111]
	v_mfma_f32_16x16x32_bf16 v[112:115], v[156:159], v[190:193], v[112:115]
	v_mfma_f32_16x16x32_bf16 v[124:127], v[148:151], v[194:197], v[124:127]
	v_mfma_f32_16x16x32_bf16 v[128:131], v[156:159], v[194:197], v[128:131]
	v_mfma_f32_16x16x32_bf16 v[76:79], v[152:155], v[172:175], v[76:79]
	v_mfma_f32_16x16x32_bf16 v[80:83], v[160:163], v[172:175], v[80:83]
	v_mfma_f32_16x16x32_bf16 v[92:95], v[152:155], v[176:179], v[92:95]
	v_mfma_f32_16x16x32_bf16 v[96:99], v[160:163], v[176:179], v[96:99]
	v_mfma_f32_16x16x32_bf16 v[108:111], v[152:155], v[198:201], v[108:111]
	v_mfma_f32_16x16x32_bf16 v[112:115], v[160:163], v[198:201], v[112:115]
	v_mfma_f32_16x16x32_bf16 v[124:127], v[152:155], v[232:235], v[124:127]
	v_mfma_f32_16x16x32_bf16 v[128:131], v[160:163], v[232:235], v[128:131]
	s_barrier
	s_add_i32 s25, s25, s33
	s_add_i32 m0, s25, 0xffffff80
	ds_read_b128 v[164:167], v205 offset:49152
	ds_read_b128 v[168:171], v205 offset:51200
	ds_read_b128 v[172:175], v206 offset:49152
	ds_read_b128 v[176:179], v206 offset:51200
	ds_read_b128 v[190:193], v205 offset:53248
	ds_read_b128 v[194:197], v205 offset:55296
	ds_read_b128 v[198:201], v206 offset:53248
	ds_read_b128 v[232:235], v206 offset:55296
	global_load_lds_dwordx4 v34, s[28:29] offset:128
	s_add_i32 m0, s25, 0x1f80
	s_mov_b64 s[98:99], s[28:29]
	s_add_u32 s28, s28, 0x80080
	s_addc_u32 s29, s29, 0
	s_add_i32 s25, s31, s33
	global_load_lds_dwordx4 v184, s[98:99] offset:128
	s_mov_b32 m0, s25
	s_nop 0
	global_load_lds_dwordx4 v34, s[28:29]
	s_add_i32 m0, s25, 0x2000
	s_nop 0
	global_load_lds_dwordx4 v184, s[28:29]
	s_add_i32 m0, s54, 0xffffff80
	s_nop 0
	global_load_lds_dwordx4 v188, s[40:41] offset:128
	s_add_i32 m0, s55, 0xffffff80
	s_nop 0
	global_load_lds_dwordx4 v186, s[40:41] offset:128
	s_waitcnt vmcnt(8)
	s_waitcnt lgkmcnt(0)
	s_barrier
	v_mfma_f32_16x16x32_bf16 v[2:5], v[132:135], v[164:167], v[2:5]
	v_mfma_f32_16x16x32_bf16 v[6:9], v[140:143], v[164:167], v[6:9]
	v_mfma_f32_16x16x32_bf16 v[18:21], v[132:135], v[168:171], v[18:21]
	v_mfma_f32_16x16x32_bf16 v[22:25], v[140:143], v[168:171], v[22:25]
	v_mfma_f32_16x16x32_bf16 v[36:39], v[132:135], v[190:193], v[36:39]
	v_mfma_f32_16x16x32_bf16 v[40:43], v[140:143], v[190:193], v[40:43]
	v_mfma_f32_16x16x32_bf16 v[52:55], v[132:135], v[194:197], v[52:55]
	v_mfma_f32_16x16x32_bf16 v[56:59], v[140:143], v[194:197], v[56:59]
	v_mfma_f32_16x16x32_bf16 v[2:5], v[136:139], v[172:175], v[2:5]
	v_mfma_f32_16x16x32_bf16 v[6:9], v[144:147], v[172:175], v[6:9]
	v_mfma_f32_16x16x32_bf16 v[18:21], v[136:139], v[176:179], v[18:21]
	v_mfma_f32_16x16x32_bf16 v[22:25], v[144:147], v[176:179], v[22:25]
	v_mfma_f32_16x16x32_bf16 v[36:39], v[136:139], v[198:201], v[36:39]
	v_mfma_f32_16x16x32_bf16 v[40:43], v[144:147], v[198:201], v[40:43]
	v_mfma_f32_16x16x32_bf16 v[52:55], v[136:139], v[232:235], v[52:55]
	v_mfma_f32_16x16x32_bf16 v[56:59], v[144:147], v[232:235], v[56:59]
	v_mfma_f32_16x16x32_bf16 v[10:13], v[148:151], v[164:167], v[10:13]
	v_mfma_f32_16x16x32_bf16 v[14:17], v[156:159], v[164:167], v[14:17]
	v_mfma_f32_16x16x32_bf16 v[26:29], v[148:151], v[168:171], v[26:29]
	v_mfma_f32_16x16x32_bf16 v[30:33], v[156:159], v[168:171], v[30:33]
	v_mfma_f32_16x16x32_bf16 v[44:47], v[148:151], v[190:193], v[44:47]
	v_mfma_f32_16x16x32_bf16 v[48:51], v[156:159], v[190:193], v[48:51]
	v_mfma_f32_16x16x32_bf16 v[60:63], v[148:151], v[194:197], v[60:63]
	v_mfma_f32_16x16x32_bf16 v[64:67], v[156:159], v[194:197], v[64:67]
	v_mfma_f32_16x16x32_bf16 v[10:13], v[152:155], v[172:175], v[10:13]
	v_mfma_f32_16x16x32_bf16 v[14:17], v[160:163], v[172:175], v[14:17]
	v_mfma_f32_16x16x32_bf16 v[26:29], v[152:155], v[176:179], v[26:29]
	v_mfma_f32_16x16x32_bf16 v[30:33], v[160:163], v[176:179], v[30:33]
	v_mfma_f32_16x16x32_bf16 v[44:47], v[152:155], v[198:201], v[44:47]
	v_mfma_f32_16x16x32_bf16 v[48:51], v[160:163], v[198:201], v[48:51]
	v_mfma_f32_16x16x32_bf16 v[60:63], v[152:155], v[232:235], v[60:63]
	v_mfma_f32_16x16x32_bf16 v[64:67], v[160:163], v[232:235], v[64:67]
	s_barrier
	s_add_u32 s22, s22, 0x100
	s_addc_u32 s23, s23, 0
	s_add_u32 s21, s21, 0x100
	s_addc_u32 s24, s24, 0
	s_cmp_ge_u32 s30, s9
	s_mov_b32 s25, s30
	s_cbranch_scc1 .Lpeel_done_P3
.LBB0_908:
	s_add_i32 s30, s25, 2
	s_add_u32 s28, s22, 0xfff80080
	s_addc_u32 s29, s23, -1
	s_add_i32 s31, 0, 0x10000
	s_cmp_eq_u32 s20, s25
	s_cselect_b32 s41, s47, s29
	s_cselect_b32 s40, s46, s28
	s_cselect_b32 s29, s49, s24
	s_cselect_b32 s28, s48, s21
	s_add_i32 s25, 0, 0x14000
	ds_read_b128 v[132:135], v1
	ds_read_b128 v[136:139], v204
	ds_read_b128 v[140:143], v1 offset:2048
	ds_read_b128 v[144:147], v204 offset:2048
	ds_read_b128 v[148:151], v1 offset:16384
	ds_read_b128 v[152:155], v204 offset:16384
	ds_read_b128 v[156:159], v1 offset:18432
	ds_read_b128 v[160:163], v204 offset:18432
	s_add_i32 m0, s50, 0xc000
	ds_read_b128 v[164:167], v205
	ds_read_b128 v[168:171], v205 offset:2048
	ds_read_b128 v[172:175], v206
	ds_read_b128 v[176:179], v206 offset:2048
	ds_read_b128 v[190:193], v205 offset:4096
	ds_read_b128 v[194:197], v205 offset:6144
	ds_read_b128 v[198:201], v206 offset:4096
	ds_read_b128 v[232:235], v206 offset:6144
	global_load_lds_dwordx4 v188, s[22:23]
	s_add_i32 m0, s50, 0xe000
	s_nop 0
	global_load_lds_dwordx4 v186, s[22:23]
	s_waitcnt vmcnt(8)
	s_waitcnt lgkmcnt(0)
	s_barrier
	v_mfma_f32_16x16x32_bf16 v[68:71], v[132:135], v[164:167], v[68:71]
	v_mfma_f32_16x16x32_bf16 v[72:75], v[140:143], v[164:167], v[72:75]
	v_mfma_f32_16x16x32_bf16 v[84:87], v[132:135], v[168:171], v[84:87]
	v_mfma_f32_16x16x32_bf16 v[88:91], v[140:143], v[168:171], v[88:91]
	v_mfma_f32_16x16x32_bf16 v[100:103], v[132:135], v[190:193], v[100:103]
	v_mfma_f32_16x16x32_bf16 v[104:107], v[140:143], v[190:193], v[104:107]
	v_mfma_f32_16x16x32_bf16 v[116:119], v[132:135], v[194:197], v[116:119]
	v_mfma_f32_16x16x32_bf16 v[120:123], v[140:143], v[194:197], v[120:123]
	v_mfma_f32_16x16x32_bf16 v[68:71], v[136:139], v[172:175], v[68:71]
	v_mfma_f32_16x16x32_bf16 v[72:75], v[144:147], v[172:175], v[72:75]
	v_mfma_f32_16x16x32_bf16 v[84:87], v[136:139], v[176:179], v[84:87]
	v_mfma_f32_16x16x32_bf16 v[88:91], v[144:147], v[176:179], v[88:91]
	v_mfma_f32_16x16x32_bf16 v[100:103], v[136:139], v[198:201], v[100:103]
	v_mfma_f32_16x16x32_bf16 v[104:107], v[144:147], v[198:201], v[104:107]
	v_mfma_f32_16x16x32_bf16 v[116:119], v[136:139], v[232:235], v[116:119]
	v_mfma_f32_16x16x32_bf16 v[120:123], v[144:147], v[232:235], v[120:123]
	v_mfma_f32_16x16x32_bf16 v[76:79], v[148:151], v[164:167], v[76:79]
	v_mfma_f32_16x16x32_bf16 v[80:83], v[156:159], v[164:167], v[80:83]
	v_mfma_f32_16x16x32_bf16 v[92:95], v[148:151], v[168:171], v[92:95]
	v_mfma_f32_16x16x32_bf16 v[96:99], v[156:159], v[168:171], v[96:99]
	v_mfma_f32_16x16x32_bf16 v[108:111], v[148:151], v[190:193], v[108:111]
	v_mfma_f32_16x16x32_bf16 v[112:115], v[156:159], v[190:193], v[112:115]
	v_mfma_f32_16x16x32_bf16 v[124:127], v[148:151], v[194:197], v[124:127]
	v_mfma_f32_16x16x32_bf16 v[128:131], v[156:159], v[194:197], v[128:131]
	v_mfma_f32_16x16x32_bf16 v[76:79], v[152:155], v[172:175], v[76:79]
	v_mfma_f32_16x16x32_bf16 v[80:83], v[160:163], v[172:175], v[80:83]
	v_mfma_f32_16x16x32_bf16 v[92:95], v[152:155], v[176:179], v[92:95]
	v_mfma_f32_16x16x32_bf16 v[96:99], v[160:163], v[176:179], v[96:99]
	v_mfma_f32_16x16x32_bf16 v[108:111], v[152:155], v[198:201], v[108:111]
	v_mfma_f32_16x16x32_bf16 v[112:115], v[160:163], v[198:201], v[112:115]
	v_mfma_f32_16x16x32_bf16 v[124:127], v[152:155], v[232:235], v[124:127]
	v_mfma_f32_16x16x32_bf16 v[128:131], v[160:163], v[232:235], v[128:131]
	s_barrier
	s_add_i32 s31, s31, s33
	s_mov_b32 m0, s31
	ds_read_b128 v[164:167], v205 offset:16384
	ds_read_b128 v[168:171], v205 offset:18432
	ds_read_b128 v[172:175], v206 offset:16384
	ds_read_b128 v[176:179], v206 offset:18432
	ds_read_b128 v[190:193], v205 offset:20480
	ds_read_b128 v[194:197], v205 offset:22528
	ds_read_b128 v[198:201], v206 offset:20480
	ds_read_b128 v[232:235], v206 offset:22528
	global_load_lds_dwordx4 v34, s[28:29]
	s_add_i32 m0, s31, 0x2000
	s_add_u32 s34, s28, 0x80000
	s_addc_u32 s35, s29, 0
	s_add_i32 s25, s25, s33
	global_load_lds_dwordx4 v184, s[28:29]
	s_mov_b32 m0, s25
	s_nop 0
	global_load_lds_dwordx4 v34, s[34:35]
	s_add_i32 m0, s25, 0x2000
	s_nop 0
	global_load_lds_dwordx4 v184, s[34:35]
	s_mov_b32 m0, s50
	s_nop 0
	global_load_lds_dwordx4 v188, s[40:41]
	s_mov_b32 m0, s51
	s_nop 0
	global_load_lds_dwordx4 v186, s[40:41]
	s_waitcnt vmcnt(8)
	s_waitcnt lgkmcnt(0)
	s_barrier
	v_mfma_f32_16x16x32_bf16 v[2:5], v[132:135], v[164:167], v[2:5]
	v_mfma_f32_16x16x32_bf16 v[6:9], v[140:143], v[164:167], v[6:9]
	v_mfma_f32_16x16x32_bf16 v[18:21], v[132:135], v[168:171], v[18:21]
	v_mfma_f32_16x16x32_bf16 v[22:25], v[140:143], v[168:171], v[22:25]
	v_mfma_f32_16x16x32_bf16 v[36:39], v[132:135], v[190:193], v[36:39]
	v_mfma_f32_16x16x32_bf16 v[40:43], v[140:143], v[190:193], v[40:43]
	v_mfma_f32_16x16x32_bf16 v[52:55], v[132:135], v[194:197], v[52:55]
	v_mfma_f32_16x16x32_bf16 v[56:59], v[140:143], v[194:197], v[56:59]
	v_mfma_f32_16x16x32_bf16 v[2:5], v[136:139], v[172:175], v[2:5]
	v_mfma_f32_16x16x32_bf16 v[6:9], v[144:147], v[172:175], v[6:9]
	v_mfma_f32_16x16x32_bf16 v[18:21], v[136:139], v[176:179], v[18:21]
	v_mfma_f32_16x16x32_bf16 v[22:25], v[144:147], v[176:179], v[22:25]
	v_mfma_f32_16x16x32_bf16 v[36:39], v[136:139], v[198:201], v[36:39]
	v_mfma_f32_16x16x32_bf16 v[40:43], v[144:147], v[198:201], v[40:43]
	v_mfma_f32_16x16x32_bf16 v[52:55], v[136:139], v[232:235], v[52:55]
	v_mfma_f32_16x16x32_bf16 v[56:59], v[144:147], v[232:235], v[56:59]
	v_mfma_f32_16x16x32_bf16 v[10:13], v[148:151], v[164:167], v[10:13]
	v_mfma_f32_16x16x32_bf16 v[14:17], v[156:159], v[164:167], v[14:17]
	v_mfma_f32_16x16x32_bf16 v[26:29], v[148:151], v[168:171], v[26:29]
	v_mfma_f32_16x16x32_bf16 v[30:33], v[156:159], v[168:171], v[30:33]
	v_mfma_f32_16x16x32_bf16 v[44:47], v[148:151], v[190:193], v[44:47]
	v_mfma_f32_16x16x32_bf16 v[48:51], v[156:159], v[190:193], v[48:51]
	v_mfma_f32_16x16x32_bf16 v[60:63], v[148:151], v[194:197], v[60:63]
	v_mfma_f32_16x16x32_bf16 v[64:67], v[156:159], v[194:197], v[64:67]
	v_mfma_f32_16x16x32_bf16 v[10:13], v[152:155], v[172:175], v[10:13]
	v_mfma_f32_16x16x32_bf16 v[14:17], v[160:163], v[172:175], v[14:17]
	v_mfma_f32_16x16x32_bf16 v[26:29], v[152:155], v[176:179], v[26:29]
	v_mfma_f32_16x16x32_bf16 v[30:33], v[160:163], v[176:179], v[30:33]
	v_mfma_f32_16x16x32_bf16 v[44:47], v[152:155], v[198:201], v[44:47]
	v_mfma_f32_16x16x32_bf16 v[48:51], v[160:163], v[198:201], v[48:51]
	v_mfma_f32_16x16x32_bf16 v[60:63], v[152:155], v[232:235], v[60:63]
	v_mfma_f32_16x16x32_bf16 v[64:67], v[160:163], v[232:235], v[64:67]
	s_barrier
	s_add_i32 s25, 0, 0x18000
	s_add_i32 s31, 0, 0x1c000
	ds_read_b128 v[132:135], v1 offset:32768
	ds_read_b128 v[136:139], v204 offset:32768
	ds_read_b128 v[140:143], v1 offset:34816
	ds_read_b128 v[144:147], v204 offset:34816
	ds_read_b128 v[148:151], v1 offset:49152
	ds_read_b128 v[152:155], v204 offset:49152
	ds_read_b128 v[156:159], v1 offset:51200
	ds_read_b128 v[160:163], v204 offset:51200
	s_add_u32 s34, s40, 0x80000
	s_addc_u32 s35, s41, 0
	s_mov_b32 m0, s52
	ds_read_b128 v[164:167], v205 offset:32768
	ds_read_b128 v[168:171], v205 offset:34816
	ds_read_b128 v[172:175], v206 offset:32768
	ds_read_b128 v[176:179], v206 offset:34816
	ds_read_b128 v[190:193], v205 offset:36864
	ds_read_b128 v[194:197], v205 offset:38912
	ds_read_b128 v[198:201], v206 offset:36864
	ds_read_b128 v[232:235], v206 offset:38912
	global_load_lds_dwordx4 v188, s[34:35]
	s_mov_b32 m0, s53
	s_nop 0
	global_load_lds_dwordx4 v186, s[34:35]
	s_waitcnt vmcnt(8)
	s_waitcnt lgkmcnt(0)
	s_barrier
	v_mfma_f32_16x16x32_bf16 v[68:71], v[132:135], v[164:167], v[68:71]
	v_mfma_f32_16x16x32_bf16 v[72:75], v[140:143], v[164:167], v[72:75]
	v_mfma_f32_16x16x32_bf16 v[84:87], v[132:135], v[168:171], v[84:87]
	v_mfma_f32_16x16x32_bf16 v[88:91], v[140:143], v[168:171], v[88:91]
	v_mfma_f32_16x16x32_bf16 v[100:103], v[132:135], v[190:193], v[100:103]
	v_mfma_f32_16x16x32_bf16 v[104:107], v[140:143], v[190:193], v[104:107]
	v_mfma_f32_16x16x32_bf16 v[116:119], v[132:135], v[194:197], v[116:119]
	v_mfma_f32_16x16x32_bf16 v[120:123], v[140:143], v[194:197], v[120:123]
	v_mfma_f32_16x16x32_bf16 v[68:71], v[136:139], v[172:175], v[68:71]
	v_mfma_f32_16x16x32_bf16 v[72:75], v[144:147], v[172:175], v[72:75]
	v_mfma_f32_16x16x32_bf16 v[84:87], v[136:139], v[176:179], v[84:87]
	v_mfma_f32_16x16x32_bf16 v[88:91], v[144:147], v[176:179], v[88:91]
	v_mfma_f32_16x16x32_bf16 v[100:103], v[136:139], v[198:201], v[100:103]
	v_mfma_f32_16x16x32_bf16 v[104:107], v[144:147], v[198:201], v[104:107]
	v_mfma_f32_16x16x32_bf16 v[116:119], v[136:139], v[232:235], v[116:119]
	v_mfma_f32_16x16x32_bf16 v[120:123], v[144:147], v[232:235], v[120:123]
	v_mfma_f32_16x16x32_bf16 v[76:79], v[148:151], v[164:167], v[76:79]
	v_mfma_f32_16x16x32_bf16 v[80:83], v[156:159], v[164:167], v[80:83]
	v_mfma_f32_16x16x32_bf16 v[92:95], v[148:151], v[168:171], v[92:95]
	v_mfma_f32_16x16x32_bf16 v[96:99], v[156:159], v[168:171], v[96:99]
	v_mfma_f32_16x16x32_bf16 v[108:111], v[148:151], v[190:193], v[108:111]
	v_mfma_f32_16x16x32_bf16 v[112:115], v[156:159], v[190:193], v[112:115]
	v_mfma_f32_16x16x32_bf16 v[124:127], v[148:151], v[194:197], v[124:127]
	v_mfma_f32_16x16x32_bf16 v[128:131], v[156:159], v[194:197], v[128:131]
	v_mfma_f32_16x16x32_bf16 v[76:79], v[152:155], v[172:175], v[76:79]
	v_mfma_f32_16x16x32_bf16 v[80:83], v[160:163], v[172:175], v[80:83]
	v_mfma_f32_16x16x32_bf16 v[92:95], v[152:155], v[176:179], v[92:95]
	v_mfma_f32_16x16x32_bf16 v[96:99], v[160:163], v[176:179], v[96:99]
	v_mfma_f32_16x16x32_bf16 v[108:111], v[152:155], v[198:201], v[108:111]
	v_mfma_f32_16x16x32_bf16 v[112:115], v[160:163], v[198:201], v[112:115]
	v_mfma_f32_16x16x32_bf16 v[124:127], v[152:155], v[232:235], v[124:127]
	v_mfma_f32_16x16x32_bf16 v[128:131], v[160:163], v[232:235], v[128:131]
	s_barrier
	s_add_i32 s25, s25, s33
	s_add_i32 m0, s25, 0xffffff80
	ds_read_b128 v[164:167], v205 offset:49152
	ds_read_b128 v[168:171], v205 offset:51200
	ds_read_b128 v[172:175], v206 offset:49152
	ds_read_b128 v[176:179], v206 offset:51200
	ds_read_b128 v[190:193], v205 offset:53248
	ds_read_b128 v[194:197], v205 offset:55296
	ds_read_b128 v[198:201], v206 offset:53248
	ds_read_b128 v[232:235], v206 offset:55296
	global_load_lds_dwordx4 v34, s[28:29] offset:128
	s_add_i32 m0, s25, 0x1f80
	s_mov_b64 s[98:99], s[28:29]
	s_add_u32 s28, s28, 0x80080
	s_addc_u32 s29, s29, 0
	s_add_i32 s25, s31, s33
	global_load_lds_dwordx4 v184, s[98:99] offset:128
	s_mov_b32 m0, s25
	s_nop 0
	global_load_lds_dwordx4 v34, s[28:29]
	s_add_i32 m0, s25, 0x2000
	s_nop 0
	global_load_lds_dwordx4 v184, s[28:29]
	s_add_i32 m0, s54, 0xffffff80
	s_nop 0
	global_load_lds_dwordx4 v188, s[40:41] offset:128
	s_add_i32 m0, s55, 0xffffff80
	s_nop 0
	global_load_lds_dwordx4 v186, s[40:41] offset:128
	s_waitcnt vmcnt(8)
	s_waitcnt lgkmcnt(0)
	s_barrier
	v_mfma_f32_16x16x32_bf16 v[2:5], v[132:135], v[164:167], v[2:5]
	v_mfma_f32_16x16x32_bf16 v[6:9], v[140:143], v[164:167], v[6:9]
	v_mfma_f32_16x16x32_bf16 v[18:21], v[132:135], v[168:171], v[18:21]
	v_mfma_f32_16x16x32_bf16 v[22:25], v[140:143], v[168:171], v[22:25]
	v_mfma_f32_16x16x32_bf16 v[36:39], v[132:135], v[190:193], v[36:39]
	v_mfma_f32_16x16x32_bf16 v[40:43], v[140:143], v[190:193], v[40:43]
	v_mfma_f32_16x16x32_bf16 v[52:55], v[132:135], v[194:197], v[52:55]
	v_mfma_f32_16x16x32_bf16 v[56:59], v[140:143], v[194:197], v[56:59]
	v_mfma_f32_16x16x32_bf16 v[2:5], v[136:139], v[172:175], v[2:5]
	v_mfma_f32_16x16x32_bf16 v[6:9], v[144:147], v[172:175], v[6:9]
	v_mfma_f32_16x16x32_bf16 v[18:21], v[136:139], v[176:179], v[18:21]
	v_mfma_f32_16x16x32_bf16 v[22:25], v[144:147], v[176:179], v[22:25]
	v_mfma_f32_16x16x32_bf16 v[36:39], v[136:139], v[198:201], v[36:39]
	v_mfma_f32_16x16x32_bf16 v[40:43], v[144:147], v[198:201], v[40:43]
	v_mfma_f32_16x16x32_bf16 v[52:55], v[136:139], v[232:235], v[52:55]
	v_mfma_f32_16x16x32_bf16 v[56:59], v[144:147], v[232:235], v[56:59]
	v_mfma_f32_16x16x32_bf16 v[10:13], v[148:151], v[164:167], v[10:13]
	v_mfma_f32_16x16x32_bf16 v[14:17], v[156:159], v[164:167], v[14:17]
	v_mfma_f32_16x16x32_bf16 v[26:29], v[148:151], v[168:171], v[26:29]
	v_mfma_f32_16x16x32_bf16 v[30:33], v[156:159], v[168:171], v[30:33]
	v_mfma_f32_16x16x32_bf16 v[44:47], v[148:151], v[190:193], v[44:47]
	v_mfma_f32_16x16x32_bf16 v[48:51], v[156:159], v[190:193], v[48:51]
	v_mfma_f32_16x16x32_bf16 v[60:63], v[148:151], v[194:197], v[60:63]
	v_mfma_f32_16x16x32_bf16 v[64:67], v[156:159], v[194:197], v[64:67]
	v_mfma_f32_16x16x32_bf16 v[10:13], v[152:155], v[172:175], v[10:13]
	v_mfma_f32_16x16x32_bf16 v[14:17], v[160:163], v[172:175], v[14:17]
	v_mfma_f32_16x16x32_bf16 v[26:29], v[152:155], v[176:179], v[26:29]
	v_mfma_f32_16x16x32_bf16 v[30:33], v[160:163], v[176:179], v[30:33]
	v_mfma_f32_16x16x32_bf16 v[44:47], v[152:155], v[198:201], v[44:47]
	v_mfma_f32_16x16x32_bf16 v[48:51], v[160:163], v[198:201], v[48:51]
	v_mfma_f32_16x16x32_bf16 v[60:63], v[152:155], v[232:235], v[60:63]
	v_mfma_f32_16x16x32_bf16 v[64:67], v[160:163], v[232:235], v[64:67]
	s_barrier
	s_add_u32 s22, s22, 0x100
	s_addc_u32 s23, s23, 0
	s_add_u32 s21, s21, 0x100
	s_addc_u32 s24, s24, 0
	s_cmp_ge_u32 s30, s9
	s_mov_b32 s25, s30
	s_cbranch_scc0 .LBB0_908

.LBB0_1022:
	s_ashr_i32 s23, s22, 31
	s_lshl_b64 s[12:13], s[22:23], 20
	v_readlane_b32 s20, v254, 52
	v_readlane_b32 s21, v254, 53
	s_add_u32 s40, s20, s12
	s_addc_u32 s41, s21, s13
	s_and_b64 s[12:13], s[38:39], exec
	s_cselect_b32 s12, s41, s9
	s_cselect_b32 s13, s40, s8
	s_ashr_i32 s19, s18, 31
	s_lshl_b64 s[20:21], s[18:19], 20
	v_readlane_b32 s24, v254, 48
	v_readlane_b32 s25, v254, 49
	s_add_u32 s42, s24, s20
	s_addc_u32 s43, s25, s21
	s_and_b64 s[20:21], s[38:39], exec
	s_cselect_b32 s19, s43, s29
	s_cselect_b32 s20, s42, s28
	s_add_u32 s8, s8, 0x80080
	s_addc_u32 s9, s9, 0
	s_add_u32 s21, s28, 0x100
	s_addc_u32 s23, s29, 0
	s_mov_b32 s24, -2
	v_readlane_b32 s35, v255, 20
	v_readlane_b32 s57, v255, 21
	v_readlane_b32 s58, v255, 22
	v_readlane_b32 s59, v255, 23
	s_mov_b64 s[60:61], 0x80
	s_add_u32 s25, s8, 0xfff80080
	s_addc_u32 s28, s9, -1
	s_add_i32 s30, 0, 0x10000
	s_cmp_eq_u32 s24, 28
	s_cselect_b32 s45, s12, s28
	s_cselect_b32 s44, s13, s25
	s_cselect_b32 s29, s19, s23
	s_cselect_b32 s28, s20, s21
	s_add_i32 s25, 0, 0x14000
	ds_read_b128 v[138:141], v1
	ds_read_b128 v[142:145], v150
	ds_read_b128 v[146:149], v1 offset:2048
	ds_read_b128 v[154:157], v150 offset:2048
	ds_read_b128 v[158:161], v1 offset:16384
	ds_read_b128 v[162:165], v150 offset:16384
	ds_read_b128 v[166:169], v1 offset:18432
	ds_read_b128 v[170:173], v150 offset:18432
	s_add_i32 m0, s46, 0xc000
	ds_read_b128 v[174:177], v151
	ds_read_b128 v[184:187], v151 offset:2048
	ds_read_b128 v[188:191], v152
	ds_read_b128 v[192:195], v152 offset:2048
	ds_read_b128 v[196:199], v151 offset:4096
	ds_read_b128 v[200:203], v151 offset:6144
	ds_read_b128 v[204:207], v152 offset:4096
	ds_read_b128 v[208:211], v152 offset:6144
	global_load_lds_dwordx4 v136, s[8:9]
	s_add_i32 m0, s46, 0xe000
	s_nop 0
	global_load_lds_dwordx4 v134, s[8:9]
	s_waitcnt vmcnt(8)
	s_waitcnt lgkmcnt(0)
	s_barrier
	v_mfma_f32_16x16x32_bf16 v[128:131], v[138:141], v[174:177], 0
	v_mfma_f32_16x16x32_bf16 v[124:127], v[146:149], v[174:177], 0
	v_mfma_f32_16x16x32_bf16 v[112:115], v[138:141], v[184:187], 0
	v_mfma_f32_16x16x32_bf16 v[108:111], v[146:149], v[184:187], 0
	v_mfma_f32_16x16x32_bf16 v[96:99], v[138:141], v[196:199], 0
	v_mfma_f32_16x16x32_bf16 v[92:95], v[146:149], v[196:199], 0
	v_mfma_f32_16x16x32_bf16 v[80:83], v[138:141], v[200:203], 0
	v_mfma_f32_16x16x32_bf16 v[76:79], v[146:149], v[200:203], 0
	v_mfma_f32_16x16x32_bf16 v[128:131], v[142:145], v[188:191], v[128:131]
	v_mfma_f32_16x16x32_bf16 v[124:127], v[154:157], v[188:191], v[124:127]
	v_mfma_f32_16x16x32_bf16 v[112:115], v[142:145], v[192:195], v[112:115]
	v_mfma_f32_16x16x32_bf16 v[108:111], v[154:157], v[192:195], v[108:111]
	v_mfma_f32_16x16x32_bf16 v[96:99], v[142:145], v[204:207], v[96:99]
	v_mfma_f32_16x16x32_bf16 v[92:95], v[154:157], v[204:207], v[92:95]
	v_mfma_f32_16x16x32_bf16 v[80:83], v[142:145], v[208:211], v[80:83]
	v_mfma_f32_16x16x32_bf16 v[76:79], v[154:157], v[208:211], v[76:79]
	v_mfma_f32_16x16x32_bf16 v[120:123], v[158:161], v[174:177], 0
	v_mfma_f32_16x16x32_bf16 v[116:119], v[166:169], v[174:177], 0
	v_mfma_f32_16x16x32_bf16 v[104:107], v[158:161], v[184:187], 0
	v_mfma_f32_16x16x32_bf16 v[100:103], v[166:169], v[184:187], 0
	v_mfma_f32_16x16x32_bf16 v[88:91], v[158:161], v[196:199], 0
	v_mfma_f32_16x16x32_bf16 v[84:87], v[166:169], v[196:199], 0
	v_mfma_f32_16x16x32_bf16 v[72:75], v[158:161], v[200:203], 0
	v_mfma_f32_16x16x32_bf16 v[68:71], v[166:169], v[200:203], 0
	v_mfma_f32_16x16x32_bf16 v[120:123], v[162:165], v[188:191], v[120:123]
	v_mfma_f32_16x16x32_bf16 v[116:119], v[170:173], v[188:191], v[116:119]
	v_mfma_f32_16x16x32_bf16 v[104:107], v[162:165], v[192:195], v[104:107]
	v_mfma_f32_16x16x32_bf16 v[100:103], v[170:173], v[192:195], v[100:103]
	v_mfma_f32_16x16x32_bf16 v[88:91], v[162:165], v[204:207], v[88:91]
	v_mfma_f32_16x16x32_bf16 v[84:87], v[170:173], v[204:207], v[84:87]
	v_mfma_f32_16x16x32_bf16 v[72:75], v[162:165], v[208:211], v[72:75]
	v_mfma_f32_16x16x32_bf16 v[68:71], v[170:173], v[208:211], v[68:71]
	s_barrier
	s_add_i32 s30, s30, s33
	s_mov_b32 m0, s30
	ds_read_b128 v[174:177], v151 offset:16384
	ds_read_b128 v[184:187], v151 offset:18432
	ds_read_b128 v[188:191], v152 offset:16384
	ds_read_b128 v[192:195], v152 offset:18432
	ds_read_b128 v[196:199], v151 offset:20480
	ds_read_b128 v[200:203], v151 offset:22528
	ds_read_b128 v[204:207], v152 offset:20480
	ds_read_b128 v[208:211], v152 offset:22528
	global_load_lds_dwordx4 v34, s[28:29]
	s_add_i32 m0, s30, 0x2000
	s_add_u32 s30, s28, 0x80000
	s_addc_u32 s31, s29, 0
	s_add_i32 s25, s25, s33
	global_load_lds_dwordx4 v132, s[28:29]
	s_mov_b32 m0, s25
	s_nop 0
	global_load_lds_dwordx4 v34, s[30:31]
	s_add_i32 m0, s25, 0x2000
	s_nop 0
	global_load_lds_dwordx4 v132, s[30:31]
	s_mov_b32 m0, s46
	s_nop 0
	global_load_lds_dwordx4 v136, s[44:45]
	s_mov_b32 m0, s47
	s_nop 0
	global_load_lds_dwordx4 v134, s[44:45]
	s_waitcnt vmcnt(8)
	s_waitcnt lgkmcnt(0)
	s_barrier
	v_mfma_f32_16x16x32_bf16 v[64:67], v[138:141], v[174:177], 0
	v_mfma_f32_16x16x32_bf16 v[60:63], v[146:149], v[174:177], 0
	v_mfma_f32_16x16x32_bf16 v[48:51], v[138:141], v[184:187], 0
	v_mfma_f32_16x16x32_bf16 v[44:47], v[146:149], v[184:187], 0
	v_mfma_f32_16x16x32_bf16 v[30:33], v[138:141], v[196:199], 0
	v_mfma_f32_16x16x32_bf16 v[26:29], v[146:149], v[196:199], 0
	v_mfma_f32_16x16x32_bf16 v[14:17], v[138:141], v[200:203], 0
	v_mfma_f32_16x16x32_bf16 v[10:13], v[146:149], v[200:203], 0
	v_mfma_f32_16x16x32_bf16 v[64:67], v[142:145], v[188:191], v[64:67]
	v_mfma_f32_16x16x32_bf16 v[60:63], v[154:157], v[188:191], v[60:63]
	v_mfma_f32_16x16x32_bf16 v[48:51], v[142:145], v[192:195], v[48:51]
	v_mfma_f32_16x16x32_bf16 v[44:47], v[154:157], v[192:195], v[44:47]
	v_mfma_f32_16x16x32_bf16 v[30:33], v[142:145], v[204:207], v[30:33]
	v_mfma_f32_16x16x32_bf16 v[26:29], v[154:157], v[204:207], v[26:29]
	v_mfma_f32_16x16x32_bf16 v[14:17], v[142:145], v[208:211], v[14:17]
	v_mfma_f32_16x16x32_bf16 v[10:13], v[154:157], v[208:211], v[10:13]
	v_mfma_f32_16x16x32_bf16 v[56:59], v[158:161], v[174:177], 0
	v_mfma_f32_16x16x32_bf16 v[52:55], v[166:169], v[174:177], 0
	v_mfma_f32_16x16x32_bf16 v[40:43], v[158:161], v[184:187], 0
	v_mfma_f32_16x16x32_bf16 v[36:39], v[166:169], v[184:187], 0
	v_mfma_f32_16x16x32_bf16 v[22:25], v[158:161], v[196:199], 0
	v_mfma_f32_16x16x32_bf16 v[18:21], v[166:169], v[196:199], 0
	v_mfma_f32_16x16x32_bf16 v[6:9], v[158:161], v[200:203], 0
	v_mfma_f32_16x16x32_bf16 v[2:5], v[166:169], v[200:203], 0
	v_mfma_f32_16x16x32_bf16 v[56:59], v[162:165], v[188:191], v[56:59]
	v_mfma_f32_16x16x32_bf16 v[52:55], v[170:173], v[188:191], v[52:55]
	v_mfma_f32_16x16x32_bf16 v[40:43], v[162:165], v[192:195], v[40:43]
	v_mfma_f32_16x16x32_bf16 v[36:39], v[170:173], v[192:195], v[36:39]
	v_mfma_f32_16x16x32_bf16 v[22:25], v[162:165], v[204:207], v[22:25]
	v_mfma_f32_16x16x32_bf16 v[18:21], v[170:173], v[204:207], v[18:21]
	v_mfma_f32_16x16x32_bf16 v[6:9], v[162:165], v[208:211], v[6:9]
	v_mfma_f32_16x16x32_bf16 v[2:5], v[170:173], v[208:211], v[2:5]
	s_barrier
	s_add_i32 s25, 0, 0x18000
	s_add_i32 s34, 0, 0x1c000
	ds_read_b128 v[138:141], v1 offset:32768
	ds_read_b128 v[142:145], v150 offset:32768
	ds_read_b128 v[146:149], v1 offset:34816
	ds_read_b128 v[154:157], v150 offset:34816
	ds_read_b128 v[158:161], v1 offset:49152
	ds_read_b128 v[162:165], v150 offset:49152
	ds_read_b128 v[166:169], v1 offset:51200
	ds_read_b128 v[170:173], v150 offset:51200
	s_add_u32 s30, s44, 0x80000
	s_addc_u32 s31, s45, 0
	s_mov_b32 m0, s48
	ds_read_b128 v[174:177], v151 offset:32768
	ds_read_b128 v[184:187], v151 offset:34816
	ds_read_b128 v[188:191], v152 offset:32768
	ds_read_b128 v[192:195], v152 offset:34816
	ds_read_b128 v[196:199], v151 offset:36864
	ds_read_b128 v[200:203], v151 offset:38912
	ds_read_b128 v[204:207], v152 offset:36864
	ds_read_b128 v[208:211], v152 offset:38912
	global_load_lds_dwordx4 v136, s[30:31]
	s_mov_b32 m0, s49
	s_nop 0
	global_load_lds_dwordx4 v134, s[30:31]
	s_waitcnt vmcnt(8)
	s_waitcnt lgkmcnt(0)
	s_barrier
	v_mfma_f32_16x16x32_bf16 v[128:131], v[138:141], v[174:177], v[128:131]
	v_mfma_f32_16x16x32_bf16 v[124:127], v[146:149], v[174:177], v[124:127]
	v_mfma_f32_16x16x32_bf16 v[112:115], v[138:141], v[184:187], v[112:115]
	v_mfma_f32_16x16x32_bf16 v[108:111], v[146:149], v[184:187], v[108:111]
	v_mfma_f32_16x16x32_bf16 v[96:99], v[138:141], v[196:199], v[96:99]
	v_mfma_f32_16x16x32_bf16 v[92:95], v[146:149], v[196:199], v[92:95]
	v_mfma_f32_16x16x32_bf16 v[80:83], v[138:141], v[200:203], v[80:83]
	v_mfma_f32_16x16x32_bf16 v[76:79], v[146:149], v[200:203], v[76:79]
	v_mfma_f32_16x16x32_bf16 v[128:131], v[142:145], v[188:191], v[128:131]
	v_mfma_f32_16x16x32_bf16 v[124:127], v[154:157], v[188:191], v[124:127]
	v_mfma_f32_16x16x32_bf16 v[112:115], v[142:145], v[192:195], v[112:115]
	v_mfma_f32_16x16x32_bf16 v[108:111], v[154:157], v[192:195], v[108:111]
	v_mfma_f32_16x16x32_bf16 v[96:99], v[142:145], v[204:207], v[96:99]
	v_mfma_f32_16x16x32_bf16 v[92:95], v[154:157], v[204:207], v[92:95]
	v_mfma_f32_16x16x32_bf16 v[80:83], v[142:145], v[208:211], v[80:83]
	v_mfma_f32_16x16x32_bf16 v[76:79], v[154:157], v[208:211], v[76:79]
	v_mfma_f32_16x16x32_bf16 v[120:123], v[158:161], v[174:177], v[120:123]
	v_mfma_f32_16x16x32_bf16 v[116:119], v[166:169], v[174:177], v[116:119]
	v_mfma_f32_16x16x32_bf16 v[104:107], v[158:161], v[184:187], v[104:107]
	v_mfma_f32_16x16x32_bf16 v[100:103], v[166:169], v[184:187], v[100:103]
	v_mfma_f32_16x16x32_bf16 v[88:91], v[158:161], v[196:199], v[88:91]
	v_mfma_f32_16x16x32_bf16 v[84:87], v[166:169], v[196:199], v[84:87]
	v_mfma_f32_16x16x32_bf16 v[72:75], v[158:161], v[200:203], v[72:75]
	v_mfma_f32_16x16x32_bf16 v[68:71], v[166:169], v[200:203], v[68:71]
	v_mfma_f32_16x16x32_bf16 v[120:123], v[162:165], v[188:191], v[120:123]
	v_mfma_f32_16x16x32_bf16 v[116:119], v[170:173], v[188:191], v[116:119]
	v_mfma_f32_16x16x32_bf16 v[104:107], v[162:165], v[192:195], v[104:107]
	v_mfma_f32_16x16x32_bf16 v[100:103], v[170:173], v[192:195], v[100:103]
	v_mfma_f32_16x16x32_bf16 v[88:91], v[162:165], v[204:207], v[88:91]
	v_mfma_f32_16x16x32_bf16 v[84:87], v[170:173], v[204:207], v[84:87]
	v_mfma_f32_16x16x32_bf16 v[72:75], v[162:165], v[208:211], v[72:75]
	v_mfma_f32_16x16x32_bf16 v[68:71], v[170:173], v[208:211], v[68:71]
	s_barrier
	s_add_i32 s25, s25, s33
	s_add_i32 m0, s25, 0xffffff80
	ds_read_b128 v[174:177], v151 offset:49152
	ds_read_b128 v[184:187], v151 offset:51200
	ds_read_b128 v[188:191], v152 offset:49152
	ds_read_b128 v[192:195], v152 offset:51200
	ds_read_b128 v[196:199], v151 offset:53248
	ds_read_b128 v[200:203], v151 offset:55296
	ds_read_b128 v[204:207], v152 offset:53248
	ds_read_b128 v[208:211], v152 offset:55296
	global_load_lds_dwordx4 v34, s[28:29] offset:128
	s_add_i32 m0, s25, 0x1f80
	s_mov_b64 s[98:99], s[28:29]
	s_add_u32 s28, s28, 0x80080
	s_addc_u32 s29, s29, 0
	s_add_i32 s25, s34, s33
	global_load_lds_dwordx4 v132, s[98:99] offset:128
	s_mov_b32 m0, s25
	s_nop 0
	global_load_lds_dwordx4 v34, s[28:29]
	s_add_i32 m0, s25, 0x2000
	s_nop 0
	global_load_lds_dwordx4 v132, s[28:29]
	s_add_i32 m0, s52, 0xffffff80
	s_nop 0
	global_load_lds_dwordx4 v136, s[44:45] offset:128
	s_add_i32 m0, s53, 0xffffff80
	s_nop 0
	global_load_lds_dwordx4 v134, s[44:45] offset:128
	s_waitcnt vmcnt(8)
	s_waitcnt lgkmcnt(0)
	s_barrier
	v_mfma_f32_16x16x32_bf16 v[64:67], v[138:141], v[174:177], v[64:67]
	v_mfma_f32_16x16x32_bf16 v[60:63], v[146:149], v[174:177], v[60:63]
	v_mfma_f32_16x16x32_bf16 v[48:51], v[138:141], v[184:187], v[48:51]
	v_mfma_f32_16x16x32_bf16 v[44:47], v[146:149], v[184:187], v[44:47]
	v_mfma_f32_16x16x32_bf16 v[30:33], v[138:141], v[196:199], v[30:33]
	v_mfma_f32_16x16x32_bf16 v[26:29], v[146:149], v[196:199], v[26:29]
	v_mfma_f32_16x16x32_bf16 v[14:17], v[138:141], v[200:203], v[14:17]
	v_mfma_f32_16x16x32_bf16 v[10:13], v[146:149], v[200:203], v[10:13]
	v_mfma_f32_16x16x32_bf16 v[64:67], v[142:145], v[188:191], v[64:67]
	v_mfma_f32_16x16x32_bf16 v[60:63], v[154:157], v[188:191], v[60:63]
	v_mfma_f32_16x16x32_bf16 v[48:51], v[142:145], v[192:195], v[48:51]
	v_mfma_f32_16x16x32_bf16 v[44:47], v[154:157], v[192:195], v[44:47]
	v_mfma_f32_16x16x32_bf16 v[30:33], v[142:145], v[204:207], v[30:33]
	v_mfma_f32_16x16x32_bf16 v[26:29], v[154:157], v[204:207], v[26:29]
	v_mfma_f32_16x16x32_bf16 v[14:17], v[142:145], v[208:211], v[14:17]
	v_mfma_f32_16x16x32_bf16 v[10:13], v[154:157], v[208:211], v[10:13]
	v_mfma_f32_16x16x32_bf16 v[56:59], v[158:161], v[174:177], v[56:59]
	v_mfma_f32_16x16x32_bf16 v[52:55], v[166:169], v[174:177], v[52:55]
	v_mfma_f32_16x16x32_bf16 v[40:43], v[158:161], v[184:187], v[40:43]
	v_mfma_f32_16x16x32_bf16 v[36:39], v[166:169], v[184:187], v[36:39]
	v_mfma_f32_16x16x32_bf16 v[22:25], v[158:161], v[196:199], v[22:25]
	v_mfma_f32_16x16x32_bf16 v[18:21], v[166:169], v[196:199], v[18:21]
	v_mfma_f32_16x16x32_bf16 v[6:9], v[158:161], v[200:203], v[6:9]
	v_mfma_f32_16x16x32_bf16 v[2:5], v[166:169], v[200:203], v[2:5]
	v_mfma_f32_16x16x32_bf16 v[56:59], v[162:165], v[188:191], v[56:59]
	v_mfma_f32_16x16x32_bf16 v[52:55], v[170:173], v[188:191], v[52:55]
	v_mfma_f32_16x16x32_bf16 v[40:43], v[162:165], v[192:195], v[40:43]
	v_mfma_f32_16x16x32_bf16 v[36:39], v[170:173], v[192:195], v[36:39]
	v_mfma_f32_16x16x32_bf16 v[22:25], v[162:165], v[204:207], v[22:25]
	v_mfma_f32_16x16x32_bf16 v[18:21], v[170:173], v[204:207], v[18:21]
	v_mfma_f32_16x16x32_bf16 v[6:9], v[162:165], v[208:211], v[6:9]
	v_mfma_f32_16x16x32_bf16 v[2:5], v[170:173], v[208:211], v[2:5]
	s_barrier
	s_add_i32 s24, s24, 2
	s_add_u32 s8, s8, 0x100
	s_addc_u32 s9, s9, 0
	s_add_u32 s21, s21, 0x100
	s_addc_u32 s23, s23, 0
	s_cmp_gt_u32 s24, 29
	s_cbranch_scc1 .Lpeel_done_P4
.LBB0_1023:
	s_add_u32 s25, s8, 0xfff80080
	s_addc_u32 s28, s9, -1
	s_add_i32 s30, 0, 0x10000
	s_cmp_eq_u32 s24, 28
	s_cselect_b32 s45, s12, s28
	s_cselect_b32 s44, s13, s25
	s_cselect_b32 s29, s19, s23
	s_cselect_b32 s28, s20, s21
	s_add_i32 s25, 0, 0x14000
	ds_read_b128 v[138:141], v1
	ds_read_b128 v[142:145], v150
	ds_read_b128 v[146:149], v1 offset:2048
	ds_read_b128 v[154:157], v150 offset:2048
	ds_read_b128 v[158:161], v1 offset:16384
	ds_read_b128 v[162:165], v150 offset:16384
	ds_read_b128 v[166:169], v1 offset:18432
	ds_read_b128 v[170:173], v150 offset:18432
	s_add_i32 m0, s46, 0xc000
	ds_read_b128 v[174:177], v151
	ds_read_b128 v[184:187], v151 offset:2048
	ds_read_b128 v[188:191], v152
	ds_read_b128 v[192:195], v152 offset:2048
	ds_read_b128 v[196:199], v151 offset:4096
	ds_read_b128 v[200:203], v151 offset:6144
	ds_read_b128 v[204:207], v152 offset:4096
	ds_read_b128 v[208:211], v152 offset:6144
	global_load_lds_dwordx4 v136, s[8:9]
	s_add_i32 m0, s46, 0xe000
	s_nop 0
	global_load_lds_dwordx4 v134, s[8:9]
	s_waitcnt vmcnt(8)
	s_waitcnt lgkmcnt(0)
	s_barrier
	v_mfma_f32_16x16x32_bf16 v[128:131], v[138:141], v[174:177], v[128:131]
	v_mfma_f32_16x16x32_bf16 v[124:127], v[146:149], v[174:177], v[124:127]
	v_mfma_f32_16x16x32_bf16 v[112:115], v[138:141], v[184:187], v[112:115]
	v_mfma_f32_16x16x32_bf16 v[108:111], v[146:149], v[184:187], v[108:111]
	v_mfma_f32_16x16x32_bf16 v[96:99], v[138:141], v[196:199], v[96:99]
	v_mfma_f32_16x16x32_bf16 v[92:95], v[146:149], v[196:199], v[92:95]
	v_mfma_f32_16x16x32_bf16 v[80:83], v[138:141], v[200:203], v[80:83]
	v_mfma_f32_16x16x32_bf16 v[76:79], v[146:149], v[200:203], v[76:79]
	v_mfma_f32_16x16x32_bf16 v[128:131], v[142:145], v[188:191], v[128:131]
	v_mfma_f32_16x16x32_bf16 v[124:127], v[154:157], v[188:191], v[124:127]
	v_mfma_f32_16x16x32_bf16 v[112:115], v[142:145], v[192:195], v[112:115]
	v_mfma_f32_16x16x32_bf16 v[108:111], v[154:157], v[192:195], v[108:111]
	v_mfma_f32_16x16x32_bf16 v[96:99], v[142:145], v[204:207], v[96:99]
	v_mfma_f32_16x16x32_bf16 v[92:95], v[154:157], v[204:207], v[92:95]
	v_mfma_f32_16x16x32_bf16 v[80:83], v[142:145], v[208:211], v[80:83]
	v_mfma_f32_16x16x32_bf16 v[76:79], v[154:157], v[208:211], v[76:79]
	v_mfma_f32_16x16x32_bf16 v[120:123], v[158:161], v[174:177], v[120:123]
	v_mfma_f32_16x16x32_bf16 v[116:119], v[166:169], v[174:177], v[116:119]
	v_mfma_f32_16x16x32_bf16 v[104:107], v[158:161], v[184:187], v[104:107]
	v_mfma_f32_16x16x32_bf16 v[100:103], v[166:169], v[184:187], v[100:103]
	v_mfma_f32_16x16x32_bf16 v[88:91], v[158:161], v[196:199], v[88:91]
	v_mfma_f32_16x16x32_bf16 v[84:87], v[166:169], v[196:199], v[84:87]
	v_mfma_f32_16x16x32_bf16 v[72:75], v[158:161], v[200:203], v[72:75]
	v_mfma_f32_16x16x32_bf16 v[68:71], v[166:169], v[200:203], v[68:71]
	v_mfma_f32_16x16x32_bf16 v[120:123], v[162:165], v[188:191], v[120:123]
	v_mfma_f32_16x16x32_bf16 v[116:119], v[170:173], v[188:191], v[116:119]
	v_mfma_f32_16x16x32_bf16 v[104:107], v[162:165], v[192:195], v[104:107]
	v_mfma_f32_16x16x32_bf16 v[100:103], v[170:173], v[192:195], v[100:103]
	v_mfma_f32_16x16x32_bf16 v[88:91], v[162:165], v[204:207], v[88:91]
	v_mfma_f32_16x16x32_bf16 v[84:87], v[170:173], v[204:207], v[84:87]
	v_mfma_f32_16x16x32_bf16 v[72:75], v[162:165], v[208:211], v[72:75]
	v_mfma_f32_16x16x32_bf16 v[68:71], v[170:173], v[208:211], v[68:71]
	s_barrier
	s_add_i32 s30, s30, s33
	s_mov_b32 m0, s30
	ds_read_b128 v[174:177], v151 offset:16384
	ds_read_b128 v[184:187], v151 offset:18432
	ds_read_b128 v[188:191], v152 offset:16384
	ds_read_b128 v[192:195], v152 offset:18432
	ds_read_b128 v[196:199], v151 offset:20480
	ds_read_b128 v[200:203], v151 offset:22528
	ds_read_b128 v[204:207], v152 offset:20480
	ds_read_b128 v[208:211], v152 offset:22528
	global_load_lds_dwordx4 v34, s[28:29]
	s_add_i32 m0, s30, 0x2000
	s_add_u32 s30, s28, 0x80000
	s_addc_u32 s31, s29, 0
	s_add_i32 s25, s25, s33
	global_load_lds_dwordx4 v132, s[28:29]
	s_mov_b32 m0, s25
	s_nop 0
	global_load_lds_dwordx4 v34, s[30:31]
	s_add_i32 m0, s25, 0x2000
	s_nop 0
	global_load_lds_dwordx4 v132, s[30:31]
	s_mov_b32 m0, s46
	s_nop 0
	global_load_lds_dwordx4 v136, s[44:45]
	s_mov_b32 m0, s47
	s_nop 0
	global_load_lds_dwordx4 v134, s[44:45]
	s_waitcnt vmcnt(8)
	s_waitcnt lgkmcnt(0)
	s_barrier
	v_mfma_f32_16x16x32_bf16 v[64:67], v[138:141], v[174:177], v[64:67]
	v_mfma_f32_16x16x32_bf16 v[60:63], v[146:149], v[174:177], v[60:63]
	v_mfma_f32_16x16x32_bf16 v[48:51], v[138:141], v[184:187], v[48:51]
	v_mfma_f32_16x16x32_bf16 v[44:47], v[146:149], v[184:187], v[44:47]
	v_mfma_f32_16x16x32_bf16 v[30:33], v[138:141], v[196:199], v[30:33]
	v_mfma_f32_16x16x32_bf16 v[26:29], v[146:149], v[196:199], v[26:29]
	v_mfma_f32_16x16x32_bf16 v[14:17], v[138:141], v[200:203], v[14:17]
	v_mfma_f32_16x16x32_bf16 v[10:13], v[146:149], v[200:203], v[10:13]
	v_mfma_f32_16x16x32_bf16 v[64:67], v[142:145], v[188:191], v[64:67]
	v_mfma_f32_16x16x32_bf16 v[60:63], v[154:157], v[188:191], v[60:63]
	v_mfma_f32_16x16x32_bf16 v[48:51], v[142:145], v[192:195], v[48:51]
	v_mfma_f32_16x16x32_bf16 v[44:47], v[154:157], v[192:195], v[44:47]
	v_mfma_f32_16x16x32_bf16 v[30:33], v[142:145], v[204:207], v[30:33]
	v_mfma_f32_16x16x32_bf16 v[26:29], v[154:157], v[204:207], v[26:29]
	v_mfma_f32_16x16x32_bf16 v[14:17], v[142:145], v[208:211], v[14:17]
	v_mfma_f32_16x16x32_bf16 v[10:13], v[154:157], v[208:211], v[10:13]
	v_mfma_f32_16x16x32_bf16 v[56:59], v[158:161], v[174:177], v[56:59]
	v_mfma_f32_16x16x32_bf16 v[52:55], v[166:169], v[174:177], v[52:55]
	v_mfma_f32_16x16x32_bf16 v[40:43], v[158:161], v[184:187], v[40:43]
	v_mfma_f32_16x16x32_bf16 v[36:39], v[166:169], v[184:187], v[36:39]
	v_mfma_f32_16x16x32_bf16 v[22:25], v[158:161], v[196:199], v[22:25]
	v_mfma_f32_16x16x32_bf16 v[18:21], v[166:169], v[196:199], v[18:21]
	v_mfma_f32_16x16x32_bf16 v[6:9], v[158:161], v[200:203], v[6:9]
	v_mfma_f32_16x16x32_bf16 v[2:5], v[166:169], v[200:203], v[2:5]
	v_mfma_f32_16x16x32_bf16 v[56:59], v[162:165], v[188:191], v[56:59]
	v_mfma_f32_16x16x32_bf16 v[52:55], v[170:173], v[188:191], v[52:55]
	v_mfma_f32_16x16x32_bf16 v[40:43], v[162:165], v[192:195], v[40:43]
	v_mfma_f32_16x16x32_bf16 v[36:39], v[170:173], v[192:195], v[36:39]
	v_mfma_f32_16x16x32_bf16 v[22:25], v[162:165], v[204:207], v[22:25]
	v_mfma_f32_16x16x32_bf16 v[18:21], v[170:173], v[204:207], v[18:21]
	v_mfma_f32_16x16x32_bf16 v[6:9], v[162:165], v[208:211], v[6:9]
	v_mfma_f32_16x16x32_bf16 v[2:5], v[170:173], v[208:211], v[2:5]
	s_barrier
	s_add_i32 s25, 0, 0x18000
	s_add_i32 s34, 0, 0x1c000
	ds_read_b128 v[138:141], v1 offset:32768
	ds_read_b128 v[142:145], v150 offset:32768
	ds_read_b128 v[146:149], v1 offset:34816
	ds_read_b128 v[154:157], v150 offset:34816
	ds_read_b128 v[158:161], v1 offset:49152
	ds_read_b128 v[162:165], v150 offset:49152
	ds_read_b128 v[166:169], v1 offset:51200
	ds_read_b128 v[170:173], v150 offset:51200
	s_add_u32 s30, s44, 0x80000
	s_addc_u32 s31, s45, 0
	s_mov_b32 m0, s48
	ds_read_b128 v[174:177], v151 offset:32768
	ds_read_b128 v[184:187], v151 offset:34816
	ds_read_b128 v[188:191], v152 offset:32768
	ds_read_b128 v[192:195], v152 offset:34816
	ds_read_b128 v[196:199], v151 offset:36864
	ds_read_b128 v[200:203], v151 offset:38912
	ds_read_b128 v[204:207], v152 offset:36864
	ds_read_b128 v[208:211], v152 offset:38912
	global_load_lds_dwordx4 v136, s[30:31]
	s_mov_b32 m0, s49
	s_nop 0
	global_load_lds_dwordx4 v134, s[30:31]
	s_waitcnt vmcnt(8)
	s_waitcnt lgkmcnt(0)
	s_barrier
	v_mfma_f32_16x16x32_bf16 v[128:131], v[138:141], v[174:177], v[128:131]
	v_mfma_f32_16x16x32_bf16 v[124:127], v[146:149], v[174:177], v[124:127]
	v_mfma_f32_16x16x32_bf16 v[112:115], v[138:141], v[184:187], v[112:115]
	v_mfma_f32_16x16x32_bf16 v[108:111], v[146:149], v[184:187], v[108:111]
	v_mfma_f32_16x16x32_bf16 v[96:99], v[138:141], v[196:199], v[96:99]
	v_mfma_f32_16x16x32_bf16 v[92:95], v[146:149], v[196:199], v[92:95]
	v_mfma_f32_16x16x32_bf16 v[80:83], v[138:141], v[200:203], v[80:83]
	v_mfma_f32_16x16x32_bf16 v[76:79], v[146:149], v[200:203], v[76:79]
	v_mfma_f32_16x16x32_bf16 v[128:131], v[142:145], v[188:191], v[128:131]
	v_mfma_f32_16x16x32_bf16 v[124:127], v[154:157], v[188:191], v[124:127]
	v_mfma_f32_16x16x32_bf16 v[112:115], v[142:145], v[192:195], v[112:115]
	v_mfma_f32_16x16x32_bf16 v[108:111], v[154:157], v[192:195], v[108:111]
	v_mfma_f32_16x16x32_bf16 v[96:99], v[142:145], v[204:207], v[96:99]
	v_mfma_f32_16x16x32_bf16 v[92:95], v[154:157], v[204:207], v[92:95]
	v_mfma_f32_16x16x32_bf16 v[80:83], v[142:145], v[208:211], v[80:83]
	v_mfma_f32_16x16x32_bf16 v[76:79], v[154:157], v[208:211], v[76:79]
	v_mfma_f32_16x16x32_bf16 v[120:123], v[158:161], v[174:177], v[120:123]
	v_mfma_f32_16x16x32_bf16 v[116:119], v[166:169], v[174:177], v[116:119]
	v_mfma_f32_16x16x32_bf16 v[104:107], v[158:161], v[184:187], v[104:107]
	v_mfma_f32_16x16x32_bf16 v[100:103], v[166:169], v[184:187], v[100:103]
	v_mfma_f32_16x16x32_bf16 v[88:91], v[158:161], v[196:199], v[88:91]
	v_mfma_f32_16x16x32_bf16 v[84:87], v[166:169], v[196:199], v[84:87]
	v_mfma_f32_16x16x32_bf16 v[72:75], v[158:161], v[200:203], v[72:75]
	v_mfma_f32_16x16x32_bf16 v[68:71], v[166:169], v[200:203], v[68:71]
	v_mfma_f32_16x16x32_bf16 v[120:123], v[162:165], v[188:191], v[120:123]
	v_mfma_f32_16x16x32_bf16 v[116:119], v[170:173], v[188:191], v[116:119]
	v_mfma_f32_16x16x32_bf16 v[104:107], v[162:165], v[192:195], v[104:107]
	v_mfma_f32_16x16x32_bf16 v[100:103], v[170:173], v[192:195], v[100:103]
	v_mfma_f32_16x16x32_bf16 v[88:91], v[162:165], v[204:207], v[88:91]
	v_mfma_f32_16x16x32_bf16 v[84:87], v[170:173], v[204:207], v[84:87]
	v_mfma_f32_16x16x32_bf16 v[72:75], v[162:165], v[208:211], v[72:75]
	v_mfma_f32_16x16x32_bf16 v[68:71], v[170:173], v[208:211], v[68:71]
	s_barrier
	s_add_i32 s25, s25, s33
	s_add_i32 m0, s25, 0xffffff80
	ds_read_b128 v[174:177], v151 offset:49152
	ds_read_b128 v[184:187], v151 offset:51200
	ds_read_b128 v[188:191], v152 offset:49152
	ds_read_b128 v[192:195], v152 offset:51200
	ds_read_b128 v[196:199], v151 offset:53248
	ds_read_b128 v[200:203], v151 offset:55296
	ds_read_b128 v[204:207], v152 offset:53248
	ds_read_b128 v[208:211], v152 offset:55296
	global_load_lds_dwordx4 v34, s[28:29] offset:128
	s_add_i32 m0, s25, 0x1f80
	s_mov_b64 s[98:99], s[28:29]
	s_add_u32 s28, s28, 0x80080
	s_addc_u32 s29, s29, 0
	s_add_i32 s25, s34, s33
	global_load_lds_dwordx4 v132, s[98:99] offset:128
	s_mov_b32 m0, s25
	s_nop 0
	global_load_lds_dwordx4 v34, s[28:29]
	s_add_i32 m0, s25, 0x2000
	s_nop 0
	global_load_lds_dwordx4 v132, s[28:29]
	s_add_i32 m0, s52, 0xffffff80
	s_nop 0
	global_load_lds_dwordx4 v136, s[44:45] offset:128
	s_add_i32 m0, s53, 0xffffff80
	s_nop 0
	global_load_lds_dwordx4 v134, s[44:45] offset:128
	s_waitcnt vmcnt(8)
	s_waitcnt lgkmcnt(0)
	s_barrier
	v_mfma_f32_16x16x32_bf16 v[64:67], v[138:141], v[174:177], v[64:67]
	v_mfma_f32_16x16x32_bf16 v[60:63], v[146:149], v[174:177], v[60:63]
	v_mfma_f32_16x16x32_bf16 v[48:51], v[138:141], v[184:187], v[48:51]
	v_mfma_f32_16x16x32_bf16 v[44:47], v[146:149], v[184:187], v[44:47]
	v_mfma_f32_16x16x32_bf16 v[30:33], v[138:141], v[196:199], v[30:33]
	v_mfma_f32_16x16x32_bf16 v[26:29], v[146:149], v[196:199], v[26:29]
	v_mfma_f32_16x16x32_bf16 v[14:17], v[138:141], v[200:203], v[14:17]
	v_mfma_f32_16x16x32_bf16 v[10:13], v[146:149], v[200:203], v[10:13]
	v_mfma_f32_16x16x32_bf16 v[64:67], v[142:145], v[188:191], v[64:67]
	v_mfma_f32_16x16x32_bf16 v[60:63], v[154:157], v[188:191], v[60:63]
	v_mfma_f32_16x16x32_bf16 v[48:51], v[142:145], v[192:195], v[48:51]
	v_mfma_f32_16x16x32_bf16 v[44:47], v[154:157], v[192:195], v[44:47]
	v_mfma_f32_16x16x32_bf16 v[30:33], v[142:145], v[204:207], v[30:33]
	v_mfma_f32_16x16x32_bf16 v[26:29], v[154:157], v[204:207], v[26:29]
	v_mfma_f32_16x16x32_bf16 v[14:17], v[142:145], v[208:211], v[14:17]
	v_mfma_f32_16x16x32_bf16 v[10:13], v[154:157], v[208:211], v[10:13]
	v_mfma_f32_16x16x32_bf16 v[56:59], v[158:161], v[174:177], v[56:59]
	v_mfma_f32_16x16x32_bf16 v[52:55], v[166:169], v[174:177], v[52:55]
	v_mfma_f32_16x16x32_bf16 v[40:43], v[158:161], v[184:187], v[40:43]
	v_mfma_f32_16x16x32_bf16 v[36:39], v[166:169], v[184:187], v[36:39]
	v_mfma_f32_16x16x32_bf16 v[22:25], v[158:161], v[196:199], v[22:25]
	v_mfma_f32_16x16x32_bf16 v[18:21], v[166:169], v[196:199], v[18:21]
	v_mfma_f32_16x16x32_bf16 v[6:9], v[158:161], v[200:203], v[6:9]
	v_mfma_f32_16x16x32_bf16 v[2:5], v[166:169], v[200:203], v[2:5]
	v_mfma_f32_16x16x32_bf16 v[56:59], v[162:165], v[188:191], v[56:59]
	v_mfma_f32_16x16x32_bf16 v[52:55], v[170:173], v[188:191], v[52:55]
	v_mfma_f32_16x16x32_bf16 v[40:43], v[162:165], v[192:195], v[40:43]
	v_mfma_f32_16x16x32_bf16 v[36:39], v[170:173], v[192:195], v[36:39]
	v_mfma_f32_16x16x32_bf16 v[22:25], v[162:165], v[204:207], v[22:25]
	v_mfma_f32_16x16x32_bf16 v[18:21], v[170:173], v[204:207], v[18:21]
	v_mfma_f32_16x16x32_bf16 v[6:9], v[162:165], v[208:211], v[6:9]
	v_mfma_f32_16x16x32_bf16 v[2:5], v[170:173], v[208:211], v[2:5]
	s_barrier
	s_add_i32 s24, s24, 2
	s_add_u32 s8, s8, 0x100
	s_addc_u32 s9, s9, 0
	s_add_u32 s21, s21, 0x100
	s_addc_u32 s23, s23, 0
	s_cmp_gt_u32 s24, 29
	s_cbranch_scc0 .LBB0_1023

.LBB0_1113:
	s_ashr_i32 s19, s18, 31
	s_lshl_b64 s[20:21], s[18:19], 20
	v_readlane_b32 s22, v254, 38
	v_readlane_b32 s23, v254, 39
	s_add_u32 s22, s22, s20
	s_addc_u32 s23, s23, s21
	s_and_b64 s[20:21], s[38:39], exec
	s_cselect_b32 s13, s23, s9
	s_cselect_b32 s19, s22, s8
	s_ashr_i32 s11, s10, 31
	s_lshl_b64 s[20:21], s[10:11], 20
	v_readlane_b32 s30, v254, 8
	v_readlane_b32 s31, v254, 9
	s_add_u32 s40, s30, s20
	s_addc_u32 s41, s31, s21
	v_mov_b32_e32 v2, v0
	s_and_b64 s[20:21], s[38:39], exec
	s_cselect_b32 s20, s41, s29
	s_cselect_b32 s21, s40, s28
	s_lshl_b32 s11, s24, 8
	v_and_or_b32 v2, v2, 63, s50
	v_or_b32_e32 v2, s11, v2
	v_ashrrev_i32_e32 v3, 31, v2
	v_readlane_b32 s24, v252, 61
	v_lshlrev_b64 v[2:3], 5, v[2:3]
	v_readlane_b32 s25, v252, 62
	s_add_u32 s8, s8, 0x80080
	s_addc_u32 s9, s9, 0
	v_lshl_add_u64 v[2:3], s[24:25], 0, v[2:3]
	global_load_dwordx4 v[116:119], v[2:3], off offset:16
	global_load_dwordx4 v[120:123], v[2:3], off
	s_add_u32 s24, s28, 0x100
	s_addc_u32 s25, s29, 0
	s_mov_b32 s30, -2
	v_readlane_b32 s57, v255, 20
	v_readlane_b32 s58, v255, 21
	v_readlane_b32 s59, v255, 22
	v_readlane_b32 s60, v255, 23
	s_mov_b64 s[62:63], 0x80
	s_add_u32 s28, s8, 0xfff80080
	s_addc_u32 s29, s9, -1
	s_add_i32 s31, 0, 0x10000
	s_cmp_eq_u32 s30, 28
	s_cselect_b32 s43, s13, s29
	s_cselect_b32 s42, s19, s28
	ds_read_b128 v[150:153], v1
	ds_read_b128 v[154:157], v146
	s_cselect_b32 s29, s20, s25
	s_cselect_b32 s28, s21, s24
	s_add_i32 s56, 0, 0x14000
	ds_read_b128 v[158:161], v1 offset:2048
	ds_read_b128 v[162:165], v146 offset:2048
	ds_read_b128 v[166:169], v1 offset:16384
	ds_read_b128 v[170:173], v146 offset:16384
	ds_read_b128 v[174:177], v1 offset:18432
	ds_read_b128 v[184:187], v146 offset:18432
	s_add_i32 m0, s34, 0xc000
	ds_read_b128 v[188:191], v147
	ds_read_b128 v[192:195], v147 offset:2048
	ds_read_b128 v[196:199], v148
	ds_read_b128 v[200:203], v148 offset:2048
	ds_read_b128 v[204:207], v147 offset:4096
	ds_read_b128 v[208:211], v147 offset:6144
	ds_read_b128 v[224:227], v148 offset:4096
	ds_read_b128 v[228:231], v148 offset:6144
	global_load_lds_dwordx4 v144, s[8:9]
	s_add_i32 m0, s34, 0xe000
	s_nop 0
	global_load_lds_dwordx4 v142, s[8:9]
	s_waitcnt vmcnt(8)
	s_waitcnt lgkmcnt(0)
	s_barrier
	v_mfma_f32_16x16x32_bf16 v[132:135], v[150:153], v[188:191], 0
	v_mfma_f32_16x16x32_bf16 v[124:127], v[158:161], v[188:191], 0
	v_mfma_f32_16x16x32_bf16 v[108:111], v[150:153], v[192:195], 0
	v_mfma_f32_16x16x32_bf16 v[100:103], v[158:161], v[192:195], 0
	v_mfma_f32_16x16x32_bf16 v[92:95], v[150:153], v[204:207], 0
	v_mfma_f32_16x16x32_bf16 v[84:87], v[158:161], v[204:207], 0
	v_mfma_f32_16x16x32_bf16 v[76:79], v[150:153], v[208:211], 0
	v_mfma_f32_16x16x32_bf16 v[68:71], v[158:161], v[208:211], 0
	v_mfma_f32_16x16x32_bf16 v[132:135], v[154:157], v[196:199], v[132:135]
	v_mfma_f32_16x16x32_bf16 v[124:127], v[162:165], v[196:199], v[124:127]
	v_mfma_f32_16x16x32_bf16 v[108:111], v[154:157], v[200:203], v[108:111]
	v_mfma_f32_16x16x32_bf16 v[100:103], v[162:165], v[200:203], v[100:103]
	v_mfma_f32_16x16x32_bf16 v[92:95], v[154:157], v[224:227], v[92:95]
	v_mfma_f32_16x16x32_bf16 v[84:87], v[162:165], v[224:227], v[84:87]
	v_mfma_f32_16x16x32_bf16 v[76:79], v[154:157], v[228:231], v[76:79]
	v_mfma_f32_16x16x32_bf16 v[68:71], v[162:165], v[228:231], v[68:71]
	v_mfma_f32_16x16x32_bf16 v[136:139], v[166:169], v[188:191], 0
	v_mfma_f32_16x16x32_bf16 v[128:131], v[174:177], v[188:191], 0
	v_mfma_f32_16x16x32_bf16 v[112:115], v[166:169], v[192:195], 0
	v_mfma_f32_16x16x32_bf16 v[104:107], v[174:177], v[192:195], 0
	v_mfma_f32_16x16x32_bf16 v[96:99], v[166:169], v[204:207], 0
	v_mfma_f32_16x16x32_bf16 v[88:91], v[174:177], v[204:207], 0
	v_mfma_f32_16x16x32_bf16 v[80:83], v[166:169], v[208:211], 0
	v_mfma_f32_16x16x32_bf16 v[72:75], v[174:177], v[208:211], 0
	v_mfma_f32_16x16x32_bf16 v[136:139], v[170:173], v[196:199], v[136:139]
	v_mfma_f32_16x16x32_bf16 v[128:131], v[184:187], v[196:199], v[128:131]
	v_mfma_f32_16x16x32_bf16 v[112:115], v[170:173], v[200:203], v[112:115]
	v_mfma_f32_16x16x32_bf16 v[104:107], v[184:187], v[200:203], v[104:107]
	v_mfma_f32_16x16x32_bf16 v[96:99], v[170:173], v[224:227], v[96:99]
	v_mfma_f32_16x16x32_bf16 v[88:91], v[184:187], v[224:227], v[88:91]
	v_mfma_f32_16x16x32_bf16 v[80:83], v[170:173], v[228:231], v[80:83]
	v_mfma_f32_16x16x32_bf16 v[72:75], v[184:187], v[228:231], v[72:75]
	s_barrier
	s_add_i32 s31, s31, s33
	s_mov_b32 m0, s31
	ds_read_b128 v[188:191], v147 offset:16384
	ds_read_b128 v[192:195], v147 offset:18432
	ds_read_b128 v[196:199], v148 offset:16384
	ds_read_b128 v[200:203], v148 offset:18432
	ds_read_b128 v[204:207], v147 offset:20480
	ds_read_b128 v[208:211], v147 offset:22528
	ds_read_b128 v[224:227], v148 offset:20480
	ds_read_b128 v[228:231], v148 offset:22528
	global_load_lds_dwordx4 v34, s[28:29]
	s_add_i32 m0, s31, 0x2000
	s_add_u32 s54, s28, 0x80000
	s_addc_u32 s55, s29, 0
	s_add_i32 s31, s56, s33
	global_load_lds_dwordx4 v140, s[28:29]
	s_mov_b32 m0, s31
	s_nop 0
	global_load_lds_dwordx4 v34, s[54:55]
	s_add_i32 m0, s31, 0x2000
	s_nop 0
	global_load_lds_dwordx4 v140, s[54:55]
	s_mov_b32 m0, s34
	s_nop 0
	global_load_lds_dwordx4 v144, s[42:43]
	s_mov_b32 m0, s35
	s_nop 0
	global_load_lds_dwordx4 v142, s[42:43]
	s_waitcnt vmcnt(8)
	s_waitcnt lgkmcnt(0)
	s_barrier
	v_mfma_f32_16x16x32_bf16 v[60:63], v[150:153], v[188:191], 0
	v_mfma_f32_16x16x32_bf16 v[52:55], v[158:161], v[188:191], 0
	v_mfma_f32_16x16x32_bf16 v[44:47], v[150:153], v[192:195], 0
	v_mfma_f32_16x16x32_bf16 v[36:39], v[158:161], v[192:195], 0
	v_mfma_f32_16x16x32_bf16 v[26:29], v[150:153], v[204:207], 0
	v_mfma_f32_16x16x32_bf16 v[18:21], v[158:161], v[204:207], 0
	v_mfma_f32_16x16x32_bf16 v[10:13], v[150:153], v[208:211], 0
	v_mfma_f32_16x16x32_bf16 v[6:9], v[158:161], v[208:211], 0
	v_mfma_f32_16x16x32_bf16 v[60:63], v[154:157], v[196:199], v[60:63]
	v_mfma_f32_16x16x32_bf16 v[52:55], v[162:165], v[196:199], v[52:55]
	v_mfma_f32_16x16x32_bf16 v[44:47], v[154:157], v[200:203], v[44:47]
	v_mfma_f32_16x16x32_bf16 v[36:39], v[162:165], v[200:203], v[36:39]
	v_mfma_f32_16x16x32_bf16 v[26:29], v[154:157], v[224:227], v[26:29]
	v_mfma_f32_16x16x32_bf16 v[18:21], v[162:165], v[224:227], v[18:21]
	v_mfma_f32_16x16x32_bf16 v[10:13], v[154:157], v[228:231], v[10:13]
	v_mfma_f32_16x16x32_bf16 v[6:9], v[162:165], v[228:231], v[6:9]
	v_mfma_f32_16x16x32_bf16 v[64:67], v[166:169], v[188:191], 0
	v_mfma_f32_16x16x32_bf16 v[56:59], v[174:177], v[188:191], 0
	v_mfma_f32_16x16x32_bf16 v[48:51], v[166:169], v[192:195], 0
	v_mfma_f32_16x16x32_bf16 v[40:43], v[174:177], v[192:195], 0
	v_mfma_f32_16x16x32_bf16 v[30:33], v[166:169], v[204:207], 0
	v_mfma_f32_16x16x32_bf16 v[22:25], v[174:177], v[204:207], 0
	v_mfma_f32_16x16x32_bf16 v[14:17], v[166:169], v[208:211], 0
	v_mfma_f32_16x16x32_bf16 v[2:5], v[174:177], v[208:211], 0
	v_mfma_f32_16x16x32_bf16 v[64:67], v[170:173], v[196:199], v[64:67]
	v_mfma_f32_16x16x32_bf16 v[56:59], v[184:187], v[196:199], v[56:59]
	v_mfma_f32_16x16x32_bf16 v[48:51], v[170:173], v[200:203], v[48:51]
	v_mfma_f32_16x16x32_bf16 v[40:43], v[184:187], v[200:203], v[40:43]
	v_mfma_f32_16x16x32_bf16 v[30:33], v[170:173], v[224:227], v[30:33]
	v_mfma_f32_16x16x32_bf16 v[22:25], v[184:187], v[224:227], v[22:25]
	v_mfma_f32_16x16x32_bf16 v[14:17], v[170:173], v[228:231], v[14:17]
	v_mfma_f32_16x16x32_bf16 v[2:5], v[184:187], v[228:231], v[2:5]
	s_barrier
	s_add_i32 s31, 0, 0x18000
	ds_read_b128 v[150:153], v1 offset:32768
	ds_read_b128 v[154:157], v146 offset:32768
	s_add_i32 s54, 0, 0x1c000
	ds_read_b128 v[158:161], v1 offset:34816
	ds_read_b128 v[162:165], v146 offset:34816
	ds_read_b128 v[166:169], v1 offset:49152
	ds_read_b128 v[170:173], v146 offset:49152
	ds_read_b128 v[174:177], v1 offset:51200
	ds_read_b128 v[184:187], v146 offset:51200
	s_mov_b64 s[100:101], s[42:43]
	s_add_u32 s42, s42, 0x80000
	s_addc_u32 s43, s43, 0
	s_mov_b32 m0, s44
	ds_read_b128 v[188:191], v147 offset:32768
	ds_read_b128 v[192:195], v147 offset:34816
	ds_read_b128 v[196:199], v148 offset:32768
	ds_read_b128 v[200:203], v148 offset:34816
	ds_read_b128 v[204:207], v147 offset:36864
	ds_read_b128 v[208:211], v147 offset:38912
	ds_read_b128 v[224:227], v148 offset:36864
	ds_read_b128 v[228:231], v148 offset:38912
	global_load_lds_dwordx4 v144, s[42:43]
	s_mov_b32 m0, s45
	s_nop 0
	global_load_lds_dwordx4 v142, s[42:43]
	s_waitcnt vmcnt(8)
	s_waitcnt lgkmcnt(0)
	s_barrier
	v_mfma_f32_16x16x32_bf16 v[132:135], v[150:153], v[188:191], v[132:135]
	v_mfma_f32_16x16x32_bf16 v[124:127], v[158:161], v[188:191], v[124:127]
	v_mfma_f32_16x16x32_bf16 v[108:111], v[150:153], v[192:195], v[108:111]
	v_mfma_f32_16x16x32_bf16 v[100:103], v[158:161], v[192:195], v[100:103]
	v_mfma_f32_16x16x32_bf16 v[92:95], v[150:153], v[204:207], v[92:95]
	v_mfma_f32_16x16x32_bf16 v[84:87], v[158:161], v[204:207], v[84:87]
	v_mfma_f32_16x16x32_bf16 v[76:79], v[150:153], v[208:211], v[76:79]
	v_mfma_f32_16x16x32_bf16 v[68:71], v[158:161], v[208:211], v[68:71]
	v_mfma_f32_16x16x32_bf16 v[132:135], v[154:157], v[196:199], v[132:135]
	v_mfma_f32_16x16x32_bf16 v[124:127], v[162:165], v[196:199], v[124:127]
	v_mfma_f32_16x16x32_bf16 v[108:111], v[154:157], v[200:203], v[108:111]
	v_mfma_f32_16x16x32_bf16 v[100:103], v[162:165], v[200:203], v[100:103]
	v_mfma_f32_16x16x32_bf16 v[92:95], v[154:157], v[224:227], v[92:95]
	v_mfma_f32_16x16x32_bf16 v[84:87], v[162:165], v[224:227], v[84:87]
	v_mfma_f32_16x16x32_bf16 v[76:79], v[154:157], v[228:231], v[76:79]
	v_mfma_f32_16x16x32_bf16 v[68:71], v[162:165], v[228:231], v[68:71]
	v_mfma_f32_16x16x32_bf16 v[136:139], v[166:169], v[188:191], v[136:139]
	v_mfma_f32_16x16x32_bf16 v[128:131], v[174:177], v[188:191], v[128:131]
	v_mfma_f32_16x16x32_bf16 v[112:115], v[166:169], v[192:195], v[112:115]
	v_mfma_f32_16x16x32_bf16 v[104:107], v[174:177], v[192:195], v[104:107]
	v_mfma_f32_16x16x32_bf16 v[96:99], v[166:169], v[204:207], v[96:99]
	v_mfma_f32_16x16x32_bf16 v[88:91], v[174:177], v[204:207], v[88:91]
	v_mfma_f32_16x16x32_bf16 v[80:83], v[166:169], v[208:211], v[80:83]
	v_mfma_f32_16x16x32_bf16 v[72:75], v[174:177], v[208:211], v[72:75]
	v_mfma_f32_16x16x32_bf16 v[136:139], v[170:173], v[196:199], v[136:139]
	v_mfma_f32_16x16x32_bf16 v[128:131], v[184:187], v[196:199], v[128:131]
	v_mfma_f32_16x16x32_bf16 v[112:115], v[170:173], v[200:203], v[112:115]
	v_mfma_f32_16x16x32_bf16 v[104:107], v[184:187], v[200:203], v[104:107]
	v_mfma_f32_16x16x32_bf16 v[96:99], v[170:173], v[224:227], v[96:99]
	v_mfma_f32_16x16x32_bf16 v[88:91], v[184:187], v[224:227], v[88:91]
	v_mfma_f32_16x16x32_bf16 v[80:83], v[170:173], v[228:231], v[80:83]
	v_mfma_f32_16x16x32_bf16 v[72:75], v[184:187], v[228:231], v[72:75]
	s_barrier
	s_add_i32 s31, s31, s33
	s_add_i32 m0, s31, 0xffffff80
	ds_read_b128 v[188:191], v147 offset:49152
	ds_read_b128 v[192:195], v147 offset:51200
	ds_read_b128 v[196:199], v148 offset:49152
	ds_read_b128 v[200:203], v148 offset:51200
	ds_read_b128 v[204:207], v147 offset:53248
	ds_read_b128 v[208:211], v147 offset:55296
	ds_read_b128 v[224:227], v148 offset:53248
	ds_read_b128 v[228:231], v148 offset:55296
	global_load_lds_dwordx4 v34, s[28:29] offset:128
	s_add_i32 m0, s31, 0x1f80
	s_mov_b64 s[98:99], s[28:29]
	s_add_u32 s28, s28, 0x80080
	s_addc_u32 s29, s29, 0
	s_add_i32 s31, s54, s33
	global_load_lds_dwordx4 v140, s[98:99] offset:128
	s_mov_b32 m0, s31
	s_nop 0
	global_load_lds_dwordx4 v34, s[28:29]
	s_add_i32 m0, s31, 0x2000
	s_nop 0
	global_load_lds_dwordx4 v140, s[28:29]
	s_add_i32 m0, s48, 0xffffff80
	s_nop 0
	global_load_lds_dwordx4 v144, s[100:101] offset:128
	s_add_i32 m0, s49, 0xffffff80
	s_nop 0
	global_load_lds_dwordx4 v142, s[100:101] offset:128
	s_waitcnt vmcnt(8)
	s_waitcnt lgkmcnt(0)
	s_barrier
	v_mfma_f32_16x16x32_bf16 v[60:63], v[150:153], v[188:191], v[60:63]
	v_mfma_f32_16x16x32_bf16 v[52:55], v[158:161], v[188:191], v[52:55]
	v_mfma_f32_16x16x32_bf16 v[44:47], v[150:153], v[192:195], v[44:47]
	v_mfma_f32_16x16x32_bf16 v[36:39], v[158:161], v[192:195], v[36:39]
	v_mfma_f32_16x16x32_bf16 v[26:29], v[150:153], v[204:207], v[26:29]
	v_mfma_f32_16x16x32_bf16 v[18:21], v[158:161], v[204:207], v[18:21]
	v_mfma_f32_16x16x32_bf16 v[10:13], v[150:153], v[208:211], v[10:13]
	v_mfma_f32_16x16x32_bf16 v[6:9], v[158:161], v[208:211], v[6:9]
	v_mfma_f32_16x16x32_bf16 v[60:63], v[154:157], v[196:199], v[60:63]
	v_mfma_f32_16x16x32_bf16 v[52:55], v[162:165], v[196:199], v[52:55]
	v_mfma_f32_16x16x32_bf16 v[44:47], v[154:157], v[200:203], v[44:47]
	v_mfma_f32_16x16x32_bf16 v[36:39], v[162:165], v[200:203], v[36:39]
	v_mfma_f32_16x16x32_bf16 v[26:29], v[154:157], v[224:227], v[26:29]
	v_mfma_f32_16x16x32_bf16 v[18:21], v[162:165], v[224:227], v[18:21]
	v_mfma_f32_16x16x32_bf16 v[10:13], v[154:157], v[228:231], v[10:13]
	v_mfma_f32_16x16x32_bf16 v[6:9], v[162:165], v[228:231], v[6:9]
	v_mfma_f32_16x16x32_bf16 v[64:67], v[166:169], v[188:191], v[64:67]
	v_mfma_f32_16x16x32_bf16 v[56:59], v[174:177], v[188:191], v[56:59]
	v_mfma_f32_16x16x32_bf16 v[48:51], v[166:169], v[192:195], v[48:51]
	v_mfma_f32_16x16x32_bf16 v[40:43], v[174:177], v[192:195], v[40:43]
	v_mfma_f32_16x16x32_bf16 v[30:33], v[166:169], v[204:207], v[30:33]
	v_mfma_f32_16x16x32_bf16 v[22:25], v[174:177], v[204:207], v[22:25]
	v_mfma_f32_16x16x32_bf16 v[14:17], v[166:169], v[208:211], v[14:17]
	v_mfma_f32_16x16x32_bf16 v[2:5], v[174:177], v[208:211], v[2:5]
	v_mfma_f32_16x16x32_bf16 v[64:67], v[170:173], v[196:199], v[64:67]
	v_mfma_f32_16x16x32_bf16 v[56:59], v[184:187], v[196:199], v[56:59]
	v_mfma_f32_16x16x32_bf16 v[48:51], v[170:173], v[200:203], v[48:51]
	v_mfma_f32_16x16x32_bf16 v[40:43], v[184:187], v[200:203], v[40:43]
	v_mfma_f32_16x16x32_bf16 v[30:33], v[170:173], v[224:227], v[30:33]
	v_mfma_f32_16x16x32_bf16 v[22:25], v[184:187], v[224:227], v[22:25]
	v_mfma_f32_16x16x32_bf16 v[14:17], v[170:173], v[228:231], v[14:17]
	v_mfma_f32_16x16x32_bf16 v[2:5], v[184:187], v[228:231], v[2:5]
	s_barrier
	s_add_i32 s30, s30, 2
	s_add_u32 s8, s8, 0x100
	s_addc_u32 s9, s9, 0
	s_add_u32 s24, s24, 0x100
	s_addc_u32 s25, s25, 0
	s_cmp_gt_u32 s30, 29
	s_cbranch_scc1 .Lpeel_done_P6
.LBB0_1114:
	s_add_u32 s28, s8, 0xfff80080
	s_addc_u32 s29, s9, -1
	s_add_i32 s31, 0, 0x10000
	s_cmp_eq_u32 s30, 28
	s_cselect_b32 s43, s13, s29
	s_cselect_b32 s42, s19, s28
	ds_read_b128 v[150:153], v1
	ds_read_b128 v[154:157], v146
	s_cselect_b32 s29, s20, s25
	s_cselect_b32 s28, s21, s24
	s_add_i32 s56, 0, 0x14000
	ds_read_b128 v[158:161], v1 offset:2048
	ds_read_b128 v[162:165], v146 offset:2048
	ds_read_b128 v[166:169], v1 offset:16384
	ds_read_b128 v[170:173], v146 offset:16384
	ds_read_b128 v[174:177], v1 offset:18432
	ds_read_b128 v[184:187], v146 offset:18432
	s_add_i32 m0, s34, 0xc000
	ds_read_b128 v[188:191], v147
	ds_read_b128 v[192:195], v147 offset:2048
	ds_read_b128 v[196:199], v148
	ds_read_b128 v[200:203], v148 offset:2048
	ds_read_b128 v[204:207], v147 offset:4096
	ds_read_b128 v[208:211], v147 offset:6144
	ds_read_b128 v[224:227], v148 offset:4096
	ds_read_b128 v[228:231], v148 offset:6144
	global_load_lds_dwordx4 v144, s[8:9]
	s_add_i32 m0, s34, 0xe000
	s_nop 0
	global_load_lds_dwordx4 v142, s[8:9]
	s_waitcnt vmcnt(8)
	s_waitcnt lgkmcnt(0)
	s_barrier
	v_mfma_f32_16x16x32_bf16 v[132:135], v[150:153], v[188:191], v[132:135]
	v_mfma_f32_16x16x32_bf16 v[124:127], v[158:161], v[188:191], v[124:127]
	v_mfma_f32_16x16x32_bf16 v[108:111], v[150:153], v[192:195], v[108:111]
	v_mfma_f32_16x16x32_bf16 v[100:103], v[158:161], v[192:195], v[100:103]
	v_mfma_f32_16x16x32_bf16 v[92:95], v[150:153], v[204:207], v[92:95]
	v_mfma_f32_16x16x32_bf16 v[84:87], v[158:161], v[204:207], v[84:87]
	v_mfma_f32_16x16x32_bf16 v[76:79], v[150:153], v[208:211], v[76:79]
	v_mfma_f32_16x16x32_bf16 v[68:71], v[158:161], v[208:211], v[68:71]
	v_mfma_f32_16x16x32_bf16 v[132:135], v[154:157], v[196:199], v[132:135]
	v_mfma_f32_16x16x32_bf16 v[124:127], v[162:165], v[196:199], v[124:127]
	v_mfma_f32_16x16x32_bf16 v[108:111], v[154:157], v[200:203], v[108:111]
	v_mfma_f32_16x16x32_bf16 v[100:103], v[162:165], v[200:203], v[100:103]
	v_mfma_f32_16x16x32_bf16 v[92:95], v[154:157], v[224:227], v[92:95]
	v_mfma_f32_16x16x32_bf16 v[84:87], v[162:165], v[224:227], v[84:87]
	v_mfma_f32_16x16x32_bf16 v[76:79], v[154:157], v[228:231], v[76:79]
	v_mfma_f32_16x16x32_bf16 v[68:71], v[162:165], v[228:231], v[68:71]
	v_mfma_f32_16x16x32_bf16 v[136:139], v[166:169], v[188:191], v[136:139]
	v_mfma_f32_16x16x32_bf16 v[128:131], v[174:177], v[188:191], v[128:131]
	v_mfma_f32_16x16x32_bf16 v[112:115], v[166:169], v[192:195], v[112:115]
	v_mfma_f32_16x16x32_bf16 v[104:107], v[174:177], v[192:195], v[104:107]
	v_mfma_f32_16x16x32_bf16 v[96:99], v[166:169], v[204:207], v[96:99]
	v_mfma_f32_16x16x32_bf16 v[88:91], v[174:177], v[204:207], v[88:91]
	v_mfma_f32_16x16x32_bf16 v[80:83], v[166:169], v[208:211], v[80:83]
	v_mfma_f32_16x16x32_bf16 v[72:75], v[174:177], v[208:211], v[72:75]
	v_mfma_f32_16x16x32_bf16 v[136:139], v[170:173], v[196:199], v[136:139]
	v_mfma_f32_16x16x32_bf16 v[128:131], v[184:187], v[196:199], v[128:131]
	v_mfma_f32_16x16x32_bf16 v[112:115], v[170:173], v[200:203], v[112:115]
	v_mfma_f32_16x16x32_bf16 v[104:107], v[184:187], v[200:203], v[104:107]
	v_mfma_f32_16x16x32_bf16 v[96:99], v[170:173], v[224:227], v[96:99]
	v_mfma_f32_16x16x32_bf16 v[88:91], v[184:187], v[224:227], v[88:91]
	v_mfma_f32_16x16x32_bf16 v[80:83], v[170:173], v[228:231], v[80:83]
	v_mfma_f32_16x16x32_bf16 v[72:75], v[184:187], v[228:231], v[72:75]
	s_barrier
	s_add_i32 s31, s31, s33
	s_mov_b32 m0, s31
	ds_read_b128 v[188:191], v147 offset:16384
	ds_read_b128 v[192:195], v147 offset:18432
	ds_read_b128 v[196:199], v148 offset:16384
	ds_read_b128 v[200:203], v148 offset:18432
	ds_read_b128 v[204:207], v147 offset:20480
	ds_read_b128 v[208:211], v147 offset:22528
	ds_read_b128 v[224:227], v148 offset:20480
	ds_read_b128 v[228:231], v148 offset:22528
	global_load_lds_dwordx4 v34, s[28:29]
	s_add_i32 m0, s31, 0x2000
	s_add_u32 s54, s28, 0x80000
	s_addc_u32 s55, s29, 0
	s_add_i32 s31, s56, s33
	global_load_lds_dwordx4 v140, s[28:29]
	s_mov_b32 m0, s31
	s_nop 0
	global_load_lds_dwordx4 v34, s[54:55]
	s_add_i32 m0, s31, 0x2000
	s_nop 0
	global_load_lds_dwordx4 v140, s[54:55]
	s_mov_b32 m0, s34
	s_nop 0
	global_load_lds_dwordx4 v144, s[42:43]
	s_mov_b32 m0, s35
	s_nop 0
	global_load_lds_dwordx4 v142, s[42:43]
	s_waitcnt vmcnt(8)
	s_waitcnt lgkmcnt(0)
	s_barrier
	v_mfma_f32_16x16x32_bf16 v[60:63], v[150:153], v[188:191], v[60:63]
	v_mfma_f32_16x16x32_bf16 v[52:55], v[158:161], v[188:191], v[52:55]
	v_mfma_f32_16x16x32_bf16 v[44:47], v[150:153], v[192:195], v[44:47]
	v_mfma_f32_16x16x32_bf16 v[36:39], v[158:161], v[192:195], v[36:39]
	v_mfma_f32_16x16x32_bf16 v[26:29], v[150:153], v[204:207], v[26:29]
	v_mfma_f32_16x16x32_bf16 v[18:21], v[158:161], v[204:207], v[18:21]
	v_mfma_f32_16x16x32_bf16 v[10:13], v[150:153], v[208:211], v[10:13]
	v_mfma_f32_16x16x32_bf16 v[6:9], v[158:161], v[208:211], v[6:9]
	v_mfma_f32_16x16x32_bf16 v[60:63], v[154:157], v[196:199], v[60:63]
	v_mfma_f32_16x16x32_bf16 v[52:55], v[162:165], v[196:199], v[52:55]
	v_mfma_f32_16x16x32_bf16 v[44:47], v[154:157], v[200:203], v[44:47]
	v_mfma_f32_16x16x32_bf16 v[36:39], v[162:165], v[200:203], v[36:39]
	v_mfma_f32_16x16x32_bf16 v[26:29], v[154:157], v[224:227], v[26:29]
	v_mfma_f32_16x16x32_bf16 v[18:21], v[162:165], v[224:227], v[18:21]
	v_mfma_f32_16x16x32_bf16 v[10:13], v[154:157], v[228:231], v[10:13]
	v_mfma_f32_16x16x32_bf16 v[6:9], v[162:165], v[228:231], v[6:9]
	v_mfma_f32_16x16x32_bf16 v[64:67], v[166:169], v[188:191], v[64:67]
	v_mfma_f32_16x16x32_bf16 v[56:59], v[174:177], v[188:191], v[56:59]
	v_mfma_f32_16x16x32_bf16 v[48:51], v[166:169], v[192:195], v[48:51]
	v_mfma_f32_16x16x32_bf16 v[40:43], v[174:177], v[192:195], v[40:43]
	v_mfma_f32_16x16x32_bf16 v[30:33], v[166:169], v[204:207], v[30:33]
	v_mfma_f32_16x16x32_bf16 v[22:25], v[174:177], v[204:207], v[22:25]
	v_mfma_f32_16x16x32_bf16 v[14:17], v[166:169], v[208:211], v[14:17]
	v_mfma_f32_16x16x32_bf16 v[2:5], v[174:177], v[208:211], v[2:5]
	v_mfma_f32_16x16x32_bf16 v[64:67], v[170:173], v[196:199], v[64:67]
	v_mfma_f32_16x16x32_bf16 v[56:59], v[184:187], v[196:199], v[56:59]
	v_mfma_f32_16x16x32_bf16 v[48:51], v[170:173], v[200:203], v[48:51]
	v_mfma_f32_16x16x32_bf16 v[40:43], v[184:187], v[200:203], v[40:43]
	v_mfma_f32_16x16x32_bf16 v[30:33], v[170:173], v[224:227], v[30:33]
	v_mfma_f32_16x16x32_bf16 v[22:25], v[184:187], v[224:227], v[22:25]
	v_mfma_f32_16x16x32_bf16 v[14:17], v[170:173], v[228:231], v[14:17]
	v_mfma_f32_16x16x32_bf16 v[2:5], v[184:187], v[228:231], v[2:5]
	s_barrier
	s_add_i32 s31, 0, 0x18000
	ds_read_b128 v[150:153], v1 offset:32768
	ds_read_b128 v[154:157], v146 offset:32768
	s_add_i32 s54, 0, 0x1c000
	ds_read_b128 v[158:161], v1 offset:34816
	ds_read_b128 v[162:165], v146 offset:34816
	ds_read_b128 v[166:169], v1 offset:49152
	ds_read_b128 v[170:173], v146 offset:49152
	ds_read_b128 v[174:177], v1 offset:51200
	ds_read_b128 v[184:187], v146 offset:51200
	s_mov_b64 s[100:101], s[42:43]
	s_add_u32 s42, s42, 0x80000
	s_addc_u32 s43, s43, 0
	s_mov_b32 m0, s44
	ds_read_b128 v[188:191], v147 offset:32768
	ds_read_b128 v[192:195], v147 offset:34816
	ds_read_b128 v[196:199], v148 offset:32768
	ds_read_b128 v[200:203], v148 offset:34816
	ds_read_b128 v[204:207], v147 offset:36864
	ds_read_b128 v[208:211], v147 offset:38912
	ds_read_b128 v[224:227], v148 offset:36864
	ds_read_b128 v[228:231], v148 offset:38912
	global_load_lds_dwordx4 v144, s[42:43]
	s_mov_b32 m0, s45
	s_nop 0
	global_load_lds_dwordx4 v142, s[42:43]
	s_waitcnt vmcnt(8)
	s_waitcnt lgkmcnt(0)
	s_barrier
	v_mfma_f32_16x16x32_bf16 v[132:135], v[150:153], v[188:191], v[132:135]
	v_mfma_f32_16x16x32_bf16 v[124:127], v[158:161], v[188:191], v[124:127]
	v_mfma_f32_16x16x32_bf16 v[108:111], v[150:153], v[192:195], v[108:111]
	v_mfma_f32_16x16x32_bf16 v[100:103], v[158:161], v[192:195], v[100:103]
	v_mfma_f32_16x16x32_bf16 v[92:95], v[150:153], v[204:207], v[92:95]
	v_mfma_f32_16x16x32_bf16 v[84:87], v[158:161], v[204:207], v[84:87]
	v_mfma_f32_16x16x32_bf16 v[76:79], v[150:153], v[208:211], v[76:79]
	v_mfma_f32_16x16x32_bf16 v[68:71], v[158:161], v[208:211], v[68:71]
	v_mfma_f32_16x16x32_bf16 v[132:135], v[154:157], v[196:199], v[132:135]
	v_mfma_f32_16x16x32_bf16 v[124:127], v[162:165], v[196:199], v[124:127]
	v_mfma_f32_16x16x32_bf16 v[108:111], v[154:157], v[200:203], v[108:111]
	v_mfma_f32_16x16x32_bf16 v[100:103], v[162:165], v[200:203], v[100:103]
	v_mfma_f32_16x16x32_bf16 v[92:95], v[154:157], v[224:227], v[92:95]
	v_mfma_f32_16x16x32_bf16 v[84:87], v[162:165], v[224:227], v[84:87]
	v_mfma_f32_16x16x32_bf16 v[76:79], v[154:157], v[228:231], v[76:79]
	v_mfma_f32_16x16x32_bf16 v[68:71], v[162:165], v[228:231], v[68:71]
	v_mfma_f32_16x16x32_bf16 v[136:139], v[166:169], v[188:191], v[136:139]
	v_mfma_f32_16x16x32_bf16 v[128:131], v[174:177], v[188:191], v[128:131]
	v_mfma_f32_16x16x32_bf16 v[112:115], v[166:169], v[192:195], v[112:115]
	v_mfma_f32_16x16x32_bf16 v[104:107], v[174:177], v[192:195], v[104:107]
	v_mfma_f32_16x16x32_bf16 v[96:99], v[166:169], v[204:207], v[96:99]
	v_mfma_f32_16x16x32_bf16 v[88:91], v[174:177], v[204:207], v[88:91]
	v_mfma_f32_16x16x32_bf16 v[80:83], v[166:169], v[208:211], v[80:83]
	v_mfma_f32_16x16x32_bf16 v[72:75], v[174:177], v[208:211], v[72:75]
	v_mfma_f32_16x16x32_bf16 v[136:139], v[170:173], v[196:199], v[136:139]
	v_mfma_f32_16x16x32_bf16 v[128:131], v[184:187], v[196:199], v[128:131]
	v_mfma_f32_16x16x32_bf16 v[112:115], v[170:173], v[200:203], v[112:115]
	v_mfma_f32_16x16x32_bf16 v[104:107], v[184:187], v[200:203], v[104:107]
	v_mfma_f32_16x16x32_bf16 v[96:99], v[170:173], v[224:227], v[96:99]
	v_mfma_f32_16x16x32_bf16 v[88:91], v[184:187], v[224:227], v[88:91]
	v_mfma_f32_16x16x32_bf16 v[80:83], v[170:173], v[228:231], v[80:83]
	v_mfma_f32_16x16x32_bf16 v[72:75], v[184:187], v[228:231], v[72:75]
	s_barrier
	s_add_i32 s31, s31, s33
	s_add_i32 m0, s31, 0xffffff80
	ds_read_b128 v[188:191], v147 offset:49152
	ds_read_b128 v[192:195], v147 offset:51200
	ds_read_b128 v[196:199], v148 offset:49152
	ds_read_b128 v[200:203], v148 offset:51200
	ds_read_b128 v[204:207], v147 offset:53248
	ds_read_b128 v[208:211], v147 offset:55296
	ds_read_b128 v[224:227], v148 offset:53248
	ds_read_b128 v[228:231], v148 offset:55296
	global_load_lds_dwordx4 v34, s[28:29] offset:128
	s_add_i32 m0, s31, 0x1f80
	s_mov_b64 s[98:99], s[28:29]
	s_add_u32 s28, s28, 0x80080
	s_addc_u32 s29, s29, 0
	s_add_i32 s31, s54, s33
	global_load_lds_dwordx4 v140, s[98:99] offset:128
	s_mov_b32 m0, s31
	s_nop 0
	global_load_lds_dwordx4 v34, s[28:29]
	s_add_i32 m0, s31, 0x2000
	s_nop 0
	global_load_lds_dwordx4 v140, s[28:29]
	s_add_i32 m0, s48, 0xffffff80
	s_nop 0
	global_load_lds_dwordx4 v144, s[100:101] offset:128
	s_add_i32 m0, s49, 0xffffff80
	s_nop 0
	global_load_lds_dwordx4 v142, s[100:101] offset:128
	s_waitcnt vmcnt(8)
	s_waitcnt lgkmcnt(0)
	s_barrier
	v_mfma_f32_16x16x32_bf16 v[60:63], v[150:153], v[188:191], v[60:63]
	v_mfma_f32_16x16x32_bf16 v[52:55], v[158:161], v[188:191], v[52:55]
	v_mfma_f32_16x16x32_bf16 v[44:47], v[150:153], v[192:195], v[44:47]
	v_mfma_f32_16x16x32_bf16 v[36:39], v[158:161], v[192:195], v[36:39]
	v_mfma_f32_16x16x32_bf16 v[26:29], v[150:153], v[204:207], v[26:29]
	v_mfma_f32_16x16x32_bf16 v[18:21], v[158:161], v[204:207], v[18:21]
	v_mfma_f32_16x16x32_bf16 v[10:13], v[150:153], v[208:211], v[10:13]
	v_mfma_f32_16x16x32_bf16 v[6:9], v[158:161], v[208:211], v[6:9]
	v_mfma_f32_16x16x32_bf16 v[60:63], v[154:157], v[196:199], v[60:63]
	v_mfma_f32_16x16x32_bf16 v[52:55], v[162:165], v[196:199], v[52:55]
	v_mfma_f32_16x16x32_bf16 v[44:47], v[154:157], v[200:203], v[44:47]
	v_mfma_f32_16x16x32_bf16 v[36:39], v[162:165], v[200:203], v[36:39]
	v_mfma_f32_16x16x32_bf16 v[26:29], v[154:157], v[224:227], v[26:29]
	v_mfma_f32_16x16x32_bf16 v[18:21], v[162:165], v[224:227], v[18:21]
	v_mfma_f32_16x16x32_bf16 v[10:13], v[154:157], v[228:231], v[10:13]
	v_mfma_f32_16x16x32_bf16 v[6:9], v[162:165], v[228:231], v[6:9]
	v_mfma_f32_16x16x32_bf16 v[64:67], v[166:169], v[188:191], v[64:67]
	v_mfma_f32_16x16x32_bf16 v[56:59], v[174:177], v[188:191], v[56:59]
	v_mfma_f32_16x16x32_bf16 v[48:51], v[166:169], v[192:195], v[48:51]
	v_mfma_f32_16x16x32_bf16 v[40:43], v[174:177], v[192:195], v[40:43]
	v_mfma_f32_16x16x32_bf16 v[30:33], v[166:169], v[204:207], v[30:33]
	v_mfma_f32_16x16x32_bf16 v[22:25], v[174:177], v[204:207], v[22:25]
	v_mfma_f32_16x16x32_bf16 v[14:17], v[166:169], v[208:211], v[14:17]
	v_mfma_f32_16x16x32_bf16 v[2:5], v[174:177], v[208:211], v[2:5]
	v_mfma_f32_16x16x32_bf16 v[64:67], v[170:173], v[196:199], v[64:67]
	v_mfma_f32_16x16x32_bf16 v[56:59], v[184:187], v[196:199], v[56:59]
	v_mfma_f32_16x16x32_bf16 v[48:51], v[170:173], v[200:203], v[48:51]
	v_mfma_f32_16x16x32_bf16 v[40:43], v[184:187], v[200:203], v[40:43]
	v_mfma_f32_16x16x32_bf16 v[30:33], v[170:173], v[224:227], v[30:33]
	v_mfma_f32_16x16x32_bf16 v[22:25], v[184:187], v[224:227], v[22:25]
	v_mfma_f32_16x16x32_bf16 v[14:17], v[170:173], v[228:231], v[14:17]
	v_mfma_f32_16x16x32_bf16 v[2:5], v[184:187], v[228:231], v[2:5]
	s_barrier
	s_add_i32 s30, s30, 2
	s_add_u32 s8, s8, 0x100
	s_addc_u32 s9, s9, 0
	s_add_u32 s24, s24, 0x100
	s_addc_u32 s25, s25, 0
	s_cmp_gt_u32 s30, 29
	s_cbranch_scc0 .LBB0_1114

.LBB0_1194:
	s_add_u32 s8, s8, 0x160080
	s_addc_u32 s9, s9, 0
	s_add_u32 s20, s18, 0x100
	s_addc_u32 s21, s19, 0
	s_mov_b32 s24, -2
	v_readlane_b32 s35, v255, 20
	v_readlane_b32 s40, v255, 21
	v_readlane_b32 s41, v255, 22
	v_readlane_b32 s57, v255, 23
	s_mov_b64 s[58:59], 0x80
	s_add_u32 s18, s8, 0xffea0080
	s_addc_u32 s19, s9, -1
	s_add_i32 s25, 0, 0x10000
	s_cmpk_eq_i32 s24, 0x54
	s_cselect_b32 s23, s45, s19
	s_cselect_b32 s22, s44, s18
	s_cselect_b32 s19, s47, s21
	s_cselect_b32 s18, s46, s20
	s_add_i32 s34, 0, 0x14000
	ds_read_b128 v[138:141], v1
	ds_read_b128 v[142:145], v160
	ds_read_b128 v[146:149], v1 offset:2048
	ds_read_b128 v[150:153], v160 offset:2048
	ds_read_b128 v[154:157], v1 offset:16384
	ds_read_b128 v[164:167], v160 offset:16384
	ds_read_b128 v[168:171], v1 offset:18432
	ds_read_b128 v[172:175], v160 offset:18432
	s_add_i32 m0, s29, 0xc000
	ds_read_b128 v[176:179], v161
	ds_read_b128 v[184:187], v161 offset:2048
	ds_read_b128 v[188:191], v162
	ds_read_b128 v[192:195], v162 offset:2048
	ds_read_b128 v[196:199], v161 offset:4096
	ds_read_b128 v[200:203], v161 offset:6144
	ds_read_b128 v[204:207], v162 offset:4096
	ds_read_b128 v[208:211], v162 offset:6144
	global_load_lds_dwordx4 v136, s[8:9]
	s_add_i32 m0, s29, 0xe000
	s_nop 0
	global_load_lds_dwordx4 v134, s[8:9]
	s_waitcnt vmcnt(8)
	s_waitcnt lgkmcnt(0)
	s_barrier
	v_mfma_f32_16x16x32_bf16 v[128:131], v[138:141], v[176:179], 0
	v_mfma_f32_16x16x32_bf16 v[124:127], v[146:149], v[176:179], 0
	v_mfma_f32_16x16x32_bf16 v[112:115], v[138:141], v[184:187], 0
	v_mfma_f32_16x16x32_bf16 v[108:111], v[146:149], v[184:187], 0
	v_mfma_f32_16x16x32_bf16 v[96:99], v[138:141], v[196:199], 0
	v_mfma_f32_16x16x32_bf16 v[92:95], v[146:149], v[196:199], 0
	v_mfma_f32_16x16x32_bf16 v[80:83], v[138:141], v[200:203], 0
	v_mfma_f32_16x16x32_bf16 v[76:79], v[146:149], v[200:203], 0
	v_mfma_f32_16x16x32_bf16 v[128:131], v[142:145], v[188:191], v[128:131]
	v_mfma_f32_16x16x32_bf16 v[124:127], v[150:153], v[188:191], v[124:127]
	v_mfma_f32_16x16x32_bf16 v[112:115], v[142:145], v[192:195], v[112:115]
	v_mfma_f32_16x16x32_bf16 v[108:111], v[150:153], v[192:195], v[108:111]
	v_mfma_f32_16x16x32_bf16 v[96:99], v[142:145], v[204:207], v[96:99]
	v_mfma_f32_16x16x32_bf16 v[92:95], v[150:153], v[204:207], v[92:95]
	v_mfma_f32_16x16x32_bf16 v[80:83], v[142:145], v[208:211], v[80:83]
	v_mfma_f32_16x16x32_bf16 v[76:79], v[150:153], v[208:211], v[76:79]
	v_mfma_f32_16x16x32_bf16 v[120:123], v[154:157], v[176:179], 0
	v_mfma_f32_16x16x32_bf16 v[116:119], v[168:171], v[176:179], 0
	v_mfma_f32_16x16x32_bf16 v[104:107], v[154:157], v[184:187], 0
	v_mfma_f32_16x16x32_bf16 v[100:103], v[168:171], v[184:187], 0
	v_mfma_f32_16x16x32_bf16 v[88:91], v[154:157], v[196:199], 0
	v_mfma_f32_16x16x32_bf16 v[84:87], v[168:171], v[196:199], 0
	v_mfma_f32_16x16x32_bf16 v[72:75], v[154:157], v[200:203], 0
	v_mfma_f32_16x16x32_bf16 v[68:71], v[168:171], v[200:203], 0
	v_mfma_f32_16x16x32_bf16 v[120:123], v[164:167], v[188:191], v[120:123]
	v_mfma_f32_16x16x32_bf16 v[116:119], v[172:175], v[188:191], v[116:119]
	v_mfma_f32_16x16x32_bf16 v[104:107], v[164:167], v[192:195], v[104:107]
	v_mfma_f32_16x16x32_bf16 v[100:103], v[172:175], v[192:195], v[100:103]
	v_mfma_f32_16x16x32_bf16 v[88:91], v[164:167], v[204:207], v[88:91]
	v_mfma_f32_16x16x32_bf16 v[84:87], v[172:175], v[204:207], v[84:87]
	v_mfma_f32_16x16x32_bf16 v[72:75], v[164:167], v[208:211], v[72:75]
	v_mfma_f32_16x16x32_bf16 v[68:71], v[172:175], v[208:211], v[68:71]
	s_barrier
	s_add_i32 s25, s25, s28
	s_mov_b32 m0, s25
	ds_read_b128 v[176:179], v161 offset:16384
	ds_read_b128 v[184:187], v161 offset:18432
	ds_read_b128 v[188:191], v162 offset:16384
	ds_read_b128 v[192:195], v162 offset:18432
	ds_read_b128 v[196:199], v161 offset:20480
	ds_read_b128 v[200:203], v161 offset:22528
	ds_read_b128 v[204:207], v162 offset:20480
	ds_read_b128 v[208:211], v162 offset:22528
	global_load_lds_dwordx4 v34, s[18:19]
	s_add_i32 m0, s25, 0x2000
	s_add_u32 s30, s18, 0x160000
	s_addc_u32 s31, s19, 0
	s_add_i32 s25, s34, s28
	global_load_lds_dwordx4 v132, s[18:19]
	s_mov_b32 m0, s25
	s_nop 0
	global_load_lds_dwordx4 v34, s[30:31]
	s_add_i32 m0, s25, 0x2000
	s_nop 0
	global_load_lds_dwordx4 v132, s[30:31]
	s_mov_b32 m0, s29
	s_nop 0
	global_load_lds_dwordx4 v136, s[22:23]
	s_mov_b32 m0, s33
	s_nop 0
	global_load_lds_dwordx4 v134, s[22:23]
	s_waitcnt vmcnt(8)
	s_waitcnt lgkmcnt(0)
	s_barrier
	v_mfma_f32_16x16x32_bf16 v[64:67], v[138:141], v[176:179], 0
	v_mfma_f32_16x16x32_bf16 v[60:63], v[146:149], v[176:179], 0
	v_mfma_f32_16x16x32_bf16 v[48:51], v[138:141], v[184:187], 0
	v_mfma_f32_16x16x32_bf16 v[44:47], v[146:149], v[184:187], 0
	v_mfma_f32_16x16x32_bf16 v[30:33], v[138:141], v[196:199], 0
	v_mfma_f32_16x16x32_bf16 v[26:29], v[146:149], v[196:199], 0
	v_mfma_f32_16x16x32_bf16 v[14:17], v[138:141], v[200:203], 0
	v_mfma_f32_16x16x32_bf16 v[10:13], v[146:149], v[200:203], 0
	v_mfma_f32_16x16x32_bf16 v[64:67], v[142:145], v[188:191], v[64:67]
	v_mfma_f32_16x16x32_bf16 v[60:63], v[150:153], v[188:191], v[60:63]
	v_mfma_f32_16x16x32_bf16 v[48:51], v[142:145], v[192:195], v[48:51]
	v_mfma_f32_16x16x32_bf16 v[44:47], v[150:153], v[192:195], v[44:47]
	v_mfma_f32_16x16x32_bf16 v[30:33], v[142:145], v[204:207], v[30:33]
	v_mfma_f32_16x16x32_bf16 v[26:29], v[150:153], v[204:207], v[26:29]
	v_mfma_f32_16x16x32_bf16 v[14:17], v[142:145], v[208:211], v[14:17]
	v_mfma_f32_16x16x32_bf16 v[10:13], v[150:153], v[208:211], v[10:13]
	v_mfma_f32_16x16x32_bf16 v[56:59], v[154:157], v[176:179], 0
	v_mfma_f32_16x16x32_bf16 v[52:55], v[168:171], v[176:179], 0
	v_mfma_f32_16x16x32_bf16 v[40:43], v[154:157], v[184:187], 0
	v_mfma_f32_16x16x32_bf16 v[36:39], v[168:171], v[184:187], 0
	v_mfma_f32_16x16x32_bf16 v[22:25], v[154:157], v[196:199], 0
	v_mfma_f32_16x16x32_bf16 v[18:21], v[168:171], v[196:199], 0
	v_mfma_f32_16x16x32_bf16 v[6:9], v[154:157], v[200:203], 0
	v_mfma_f32_16x16x32_bf16 v[2:5], v[168:171], v[200:203], 0
	v_mfma_f32_16x16x32_bf16 v[56:59], v[164:167], v[188:191], v[56:59]
	v_mfma_f32_16x16x32_bf16 v[52:55], v[172:175], v[188:191], v[52:55]
	v_mfma_f32_16x16x32_bf16 v[40:43], v[164:167], v[192:195], v[40:43]
	v_mfma_f32_16x16x32_bf16 v[36:39], v[172:175], v[192:195], v[36:39]
	v_mfma_f32_16x16x32_bf16 v[22:25], v[164:167], v[204:207], v[22:25]
	v_mfma_f32_16x16x32_bf16 v[18:21], v[172:175], v[204:207], v[18:21]
	v_mfma_f32_16x16x32_bf16 v[6:9], v[164:167], v[208:211], v[6:9]
	v_mfma_f32_16x16x32_bf16 v[2:5], v[172:175], v[208:211], v[2:5]
	s_barrier
	s_add_i32 s25, 0, 0x18000
	s_add_i32 s30, 0, 0x1c000
	ds_read_b128 v[138:141], v1 offset:32768
	ds_read_b128 v[142:145], v160 offset:32768
	ds_read_b128 v[146:149], v1 offset:34816
	ds_read_b128 v[150:153], v160 offset:34816
	ds_read_b128 v[154:157], v1 offset:49152
	ds_read_b128 v[164:167], v160 offset:49152
	ds_read_b128 v[168:171], v1 offset:51200
	ds_read_b128 v[172:175], v160 offset:51200
	s_mov_b64 s[100:101], s[22:23]
	s_add_u32 s22, s22, 0x160000
	s_addc_u32 s23, s23, 0
	s_mov_b32 m0, s48
	ds_read_b128 v[176:179], v161 offset:32768
	ds_read_b128 v[184:187], v161 offset:34816
	ds_read_b128 v[188:191], v162 offset:32768
	ds_read_b128 v[192:195], v162 offset:34816
	ds_read_b128 v[196:199], v161 offset:36864
	ds_read_b128 v[200:203], v161 offset:38912
	ds_read_b128 v[204:207], v162 offset:36864
	ds_read_b128 v[208:211], v162 offset:38912
	global_load_lds_dwordx4 v136, s[22:23]
	s_mov_b32 m0, s49
	s_nop 0
	global_load_lds_dwordx4 v134, s[22:23]
	s_waitcnt vmcnt(8)
	s_waitcnt lgkmcnt(0)
	s_barrier
	v_mfma_f32_16x16x32_bf16 v[128:131], v[138:141], v[176:179], v[128:131]
	v_mfma_f32_16x16x32_bf16 v[124:127], v[146:149], v[176:179], v[124:127]
	v_mfma_f32_16x16x32_bf16 v[112:115], v[138:141], v[184:187], v[112:115]
	v_mfma_f32_16x16x32_bf16 v[108:111], v[146:149], v[184:187], v[108:111]
	v_mfma_f32_16x16x32_bf16 v[96:99], v[138:141], v[196:199], v[96:99]
	v_mfma_f32_16x16x32_bf16 v[92:95], v[146:149], v[196:199], v[92:95]
	v_mfma_f32_16x16x32_bf16 v[80:83], v[138:141], v[200:203], v[80:83]
	v_mfma_f32_16x16x32_bf16 v[76:79], v[146:149], v[200:203], v[76:79]
	v_mfma_f32_16x16x32_bf16 v[128:131], v[142:145], v[188:191], v[128:131]
	v_mfma_f32_16x16x32_bf16 v[124:127], v[150:153], v[188:191], v[124:127]
	v_mfma_f32_16x16x32_bf16 v[112:115], v[142:145], v[192:195], v[112:115]
	v_mfma_f32_16x16x32_bf16 v[108:111], v[150:153], v[192:195], v[108:111]
	v_mfma_f32_16x16x32_bf16 v[96:99], v[142:145], v[204:207], v[96:99]
	v_mfma_f32_16x16x32_bf16 v[92:95], v[150:153], v[204:207], v[92:95]
	v_mfma_f32_16x16x32_bf16 v[80:83], v[142:145], v[208:211], v[80:83]
	v_mfma_f32_16x16x32_bf16 v[76:79], v[150:153], v[208:211], v[76:79]
	v_mfma_f32_16x16x32_bf16 v[120:123], v[154:157], v[176:179], v[120:123]
	v_mfma_f32_16x16x32_bf16 v[116:119], v[168:171], v[176:179], v[116:119]
	v_mfma_f32_16x16x32_bf16 v[104:107], v[154:157], v[184:187], v[104:107]
	v_mfma_f32_16x16x32_bf16 v[100:103], v[168:171], v[184:187], v[100:103]
	v_mfma_f32_16x16x32_bf16 v[88:91], v[154:157], v[196:199], v[88:91]
	v_mfma_f32_16x16x32_bf16 v[84:87], v[168:171], v[196:199], v[84:87]
	v_mfma_f32_16x16x32_bf16 v[72:75], v[154:157], v[200:203], v[72:75]
	v_mfma_f32_16x16x32_bf16 v[68:71], v[168:171], v[200:203], v[68:71]
	v_mfma_f32_16x16x32_bf16 v[120:123], v[164:167], v[188:191], v[120:123]
	v_mfma_f32_16x16x32_bf16 v[116:119], v[172:175], v[188:191], v[116:119]
	v_mfma_f32_16x16x32_bf16 v[104:107], v[164:167], v[192:195], v[104:107]
	v_mfma_f32_16x16x32_bf16 v[100:103], v[172:175], v[192:195], v[100:103]
	v_mfma_f32_16x16x32_bf16 v[88:91], v[164:167], v[204:207], v[88:91]
	v_mfma_f32_16x16x32_bf16 v[84:87], v[172:175], v[204:207], v[84:87]
	v_mfma_f32_16x16x32_bf16 v[72:75], v[164:167], v[208:211], v[72:75]
	v_mfma_f32_16x16x32_bf16 v[68:71], v[172:175], v[208:211], v[68:71]
	s_barrier
	s_add_i32 s22, s25, s28
	s_add_i32 m0, s22, 0xffffff80
	ds_read_b128 v[176:179], v161 offset:49152
	ds_read_b128 v[184:187], v161 offset:51200
	ds_read_b128 v[188:191], v162 offset:49152
	ds_read_b128 v[192:195], v162 offset:51200
	ds_read_b128 v[196:199], v161 offset:53248
	ds_read_b128 v[200:203], v161 offset:55296
	ds_read_b128 v[204:207], v162 offset:53248
	ds_read_b128 v[208:211], v162 offset:55296
	global_load_lds_dwordx4 v34, s[18:19] offset:128
	s_add_i32 m0, s22, 0x1f80
	s_mov_b64 s[98:99], s[18:19]
	s_add_u32 s18, s18, 0x160080
	s_addc_u32 s19, s19, 0
	s_add_i32 s22, s30, s28
	global_load_lds_dwordx4 v132, s[98:99] offset:128
	s_mov_b32 m0, s22
	s_nop 0
	global_load_lds_dwordx4 v34, s[18:19]
	s_add_i32 m0, s22, 0x2000
	s_nop 0
	global_load_lds_dwordx4 v132, s[18:19]
	s_add_i32 m0, s53, 0xffffff80
	s_nop 0
	global_load_lds_dwordx4 v136, s[100:101] offset:128
	s_add_i32 m0, s54, 0xffffff80
	s_nop 0
	global_load_lds_dwordx4 v134, s[100:101] offset:128
	s_waitcnt vmcnt(8)
	s_waitcnt lgkmcnt(0)
	s_barrier
	v_mfma_f32_16x16x32_bf16 v[64:67], v[138:141], v[176:179], v[64:67]
	v_mfma_f32_16x16x32_bf16 v[60:63], v[146:149], v[176:179], v[60:63]
	v_mfma_f32_16x16x32_bf16 v[48:51], v[138:141], v[184:187], v[48:51]
	v_mfma_f32_16x16x32_bf16 v[44:47], v[146:149], v[184:187], v[44:47]
	v_mfma_f32_16x16x32_bf16 v[30:33], v[138:141], v[196:199], v[30:33]
	v_mfma_f32_16x16x32_bf16 v[26:29], v[146:149], v[196:199], v[26:29]
	v_mfma_f32_16x16x32_bf16 v[14:17], v[138:141], v[200:203], v[14:17]
	v_mfma_f32_16x16x32_bf16 v[10:13], v[146:149], v[200:203], v[10:13]
	v_mfma_f32_16x16x32_bf16 v[64:67], v[142:145], v[188:191], v[64:67]
	v_mfma_f32_16x16x32_bf16 v[60:63], v[150:153], v[188:191], v[60:63]
	v_mfma_f32_16x16x32_bf16 v[48:51], v[142:145], v[192:195], v[48:51]
	v_mfma_f32_16x16x32_bf16 v[44:47], v[150:153], v[192:195], v[44:47]
	v_mfma_f32_16x16x32_bf16 v[30:33], v[142:145], v[204:207], v[30:33]
	v_mfma_f32_16x16x32_bf16 v[26:29], v[150:153], v[204:207], v[26:29]
	v_mfma_f32_16x16x32_bf16 v[14:17], v[142:145], v[208:211], v[14:17]
	v_mfma_f32_16x16x32_bf16 v[10:13], v[150:153], v[208:211], v[10:13]
	v_mfma_f32_16x16x32_bf16 v[56:59], v[154:157], v[176:179], v[56:59]
	v_mfma_f32_16x16x32_bf16 v[52:55], v[168:171], v[176:179], v[52:55]
	v_mfma_f32_16x16x32_bf16 v[40:43], v[154:157], v[184:187], v[40:43]
	v_mfma_f32_16x16x32_bf16 v[36:39], v[168:171], v[184:187], v[36:39]
	v_mfma_f32_16x16x32_bf16 v[22:25], v[154:157], v[196:199], v[22:25]
	v_mfma_f32_16x16x32_bf16 v[18:21], v[168:171], v[196:199], v[18:21]
	v_mfma_f32_16x16x32_bf16 v[6:9], v[154:157], v[200:203], v[6:9]
	v_mfma_f32_16x16x32_bf16 v[2:5], v[168:171], v[200:203], v[2:5]
	v_mfma_f32_16x16x32_bf16 v[56:59], v[164:167], v[188:191], v[56:59]
	v_mfma_f32_16x16x32_bf16 v[52:55], v[172:175], v[188:191], v[52:55]
	v_mfma_f32_16x16x32_bf16 v[40:43], v[164:167], v[192:195], v[40:43]
	v_mfma_f32_16x16x32_bf16 v[36:39], v[172:175], v[192:195], v[36:39]
	v_mfma_f32_16x16x32_bf16 v[22:25], v[164:167], v[204:207], v[22:25]
	v_mfma_f32_16x16x32_bf16 v[18:21], v[172:175], v[204:207], v[18:21]
	v_mfma_f32_16x16x32_bf16 v[6:9], v[164:167], v[208:211], v[6:9]
	v_mfma_f32_16x16x32_bf16 v[2:5], v[172:175], v[208:211], v[2:5]
	s_barrier
	s_add_i32 s24, s24, 2
	s_add_u32 s8, s8, 0x100
	s_addc_u32 s9, s9, 0
	s_add_u32 s20, s20, 0x100
	s_addc_u32 s21, s21, 0
	s_cmpk_gt_u32 s24, 0x55
	s_cbranch_scc1 .Lpeel_done_P7
.LBB0_1195:
	s_add_u32 s18, s8, 0xffea0080
	s_addc_u32 s19, s9, -1
	s_add_i32 s25, 0, 0x10000
	s_cmpk_eq_i32 s24, 0x54
	s_cselect_b32 s23, s45, s19
	s_cselect_b32 s22, s44, s18
	s_cselect_b32 s19, s47, s21
	s_cselect_b32 s18, s46, s20
	s_add_i32 s34, 0, 0x14000
	ds_read_b128 v[138:141], v1
	ds_read_b128 v[142:145], v160
	ds_read_b128 v[146:149], v1 offset:2048
	ds_read_b128 v[150:153], v160 offset:2048
	ds_read_b128 v[154:157], v1 offset:16384
	ds_read_b128 v[164:167], v160 offset:16384
	ds_read_b128 v[168:171], v1 offset:18432
	ds_read_b128 v[172:175], v160 offset:18432
	s_add_i32 m0, s29, 0xc000
	ds_read_b128 v[176:179], v161
	ds_read_b128 v[184:187], v161 offset:2048
	ds_read_b128 v[188:191], v162
	ds_read_b128 v[192:195], v162 offset:2048
	ds_read_b128 v[196:199], v161 offset:4096
	ds_read_b128 v[200:203], v161 offset:6144
	ds_read_b128 v[204:207], v162 offset:4096
	ds_read_b128 v[208:211], v162 offset:6144
	global_load_lds_dwordx4 v136, s[8:9]
	s_add_i32 m0, s29, 0xe000
	s_nop 0
	global_load_lds_dwordx4 v134, s[8:9]
	s_waitcnt vmcnt(8)
	s_waitcnt lgkmcnt(0)
	s_barrier
	v_mfma_f32_16x16x32_bf16 v[128:131], v[138:141], v[176:179], v[128:131]
	v_mfma_f32_16x16x32_bf16 v[124:127], v[146:149], v[176:179], v[124:127]
	v_mfma_f32_16x16x32_bf16 v[112:115], v[138:141], v[184:187], v[112:115]
	v_mfma_f32_16x16x32_bf16 v[108:111], v[146:149], v[184:187], v[108:111]
	v_mfma_f32_16x16x32_bf16 v[96:99], v[138:141], v[196:199], v[96:99]
	v_mfma_f32_16x16x32_bf16 v[92:95], v[146:149], v[196:199], v[92:95]
	v_mfma_f32_16x16x32_bf16 v[80:83], v[138:141], v[200:203], v[80:83]
	v_mfma_f32_16x16x32_bf16 v[76:79], v[146:149], v[200:203], v[76:79]
	v_mfma_f32_16x16x32_bf16 v[128:131], v[142:145], v[188:191], v[128:131]
	v_mfma_f32_16x16x32_bf16 v[124:127], v[150:153], v[188:191], v[124:127]
	v_mfma_f32_16x16x32_bf16 v[112:115], v[142:145], v[192:195], v[112:115]
	v_mfma_f32_16x16x32_bf16 v[108:111], v[150:153], v[192:195], v[108:111]
	v_mfma_f32_16x16x32_bf16 v[96:99], v[142:145], v[204:207], v[96:99]
	v_mfma_f32_16x16x32_bf16 v[92:95], v[150:153], v[204:207], v[92:95]
	v_mfma_f32_16x16x32_bf16 v[80:83], v[142:145], v[208:211], v[80:83]
	v_mfma_f32_16x16x32_bf16 v[76:79], v[150:153], v[208:211], v[76:79]
	v_mfma_f32_16x16x32_bf16 v[120:123], v[154:157], v[176:179], v[120:123]
	v_mfma_f32_16x16x32_bf16 v[116:119], v[168:171], v[176:179], v[116:119]
	v_mfma_f32_16x16x32_bf16 v[104:107], v[154:157], v[184:187], v[104:107]
	v_mfma_f32_16x16x32_bf16 v[100:103], v[168:171], v[184:187], v[100:103]
	v_mfma_f32_16x16x32_bf16 v[88:91], v[154:157], v[196:199], v[88:91]
	v_mfma_f32_16x16x32_bf16 v[84:87], v[168:171], v[196:199], v[84:87]
	v_mfma_f32_16x16x32_bf16 v[72:75], v[154:157], v[200:203], v[72:75]
	v_mfma_f32_16x16x32_bf16 v[68:71], v[168:171], v[200:203], v[68:71]
	v_mfma_f32_16x16x32_bf16 v[120:123], v[164:167], v[188:191], v[120:123]
	v_mfma_f32_16x16x32_bf16 v[116:119], v[172:175], v[188:191], v[116:119]
	v_mfma_f32_16x16x32_bf16 v[104:107], v[164:167], v[192:195], v[104:107]
	v_mfma_f32_16x16x32_bf16 v[100:103], v[172:175], v[192:195], v[100:103]
	v_mfma_f32_16x16x32_bf16 v[88:91], v[164:167], v[204:207], v[88:91]
	v_mfma_f32_16x16x32_bf16 v[84:87], v[172:175], v[204:207], v[84:87]
	v_mfma_f32_16x16x32_bf16 v[72:75], v[164:167], v[208:211], v[72:75]
	v_mfma_f32_16x16x32_bf16 v[68:71], v[172:175], v[208:211], v[68:71]
	s_barrier
	s_add_i32 s25, s25, s28
	s_mov_b32 m0, s25
	ds_read_b128 v[176:179], v161 offset:16384
	ds_read_b128 v[184:187], v161 offset:18432
	ds_read_b128 v[188:191], v162 offset:16384
	ds_read_b128 v[192:195], v162 offset:18432
	ds_read_b128 v[196:199], v161 offset:20480
	ds_read_b128 v[200:203], v161 offset:22528
	ds_read_b128 v[204:207], v162 offset:20480
	ds_read_b128 v[208:211], v162 offset:22528
	global_load_lds_dwordx4 v34, s[18:19]
	s_add_i32 m0, s25, 0x2000
	s_add_u32 s30, s18, 0x160000
	s_addc_u32 s31, s19, 0
	s_add_i32 s25, s34, s28
	global_load_lds_dwordx4 v132, s[18:19]
	s_mov_b32 m0, s25
	s_nop 0
	global_load_lds_dwordx4 v34, s[30:31]
	s_add_i32 m0, s25, 0x2000
	s_nop 0
	global_load_lds_dwordx4 v132, s[30:31]
	s_mov_b32 m0, s29
	s_nop 0
	global_load_lds_dwordx4 v136, s[22:23]
	s_mov_b32 m0, s33
	s_nop 0
	global_load_lds_dwordx4 v134, s[22:23]
	s_waitcnt vmcnt(8)
	s_waitcnt lgkmcnt(0)
	s_barrier
	v_mfma_f32_16x16x32_bf16 v[64:67], v[138:141], v[176:179], v[64:67]
	v_mfma_f32_16x16x32_bf16 v[60:63], v[146:149], v[176:179], v[60:63]
	v_mfma_f32_16x16x32_bf16 v[48:51], v[138:141], v[184:187], v[48:51]
	v_mfma_f32_16x16x32_bf16 v[44:47], v[146:149], v[184:187], v[44:47]
	v_mfma_f32_16x16x32_bf16 v[30:33], v[138:141], v[196:199], v[30:33]
	v_mfma_f32_16x16x32_bf16 v[26:29], v[146:149], v[196:199], v[26:29]
	v_mfma_f32_16x16x32_bf16 v[14:17], v[138:141], v[200:203], v[14:17]
	v_mfma_f32_16x16x32_bf16 v[10:13], v[146:149], v[200:203], v[10:13]
	v_mfma_f32_16x16x32_bf16 v[64:67], v[142:145], v[188:191], v[64:67]
	v_mfma_f32_16x16x32_bf16 v[60:63], v[150:153], v[188:191], v[60:63]
	v_mfma_f32_16x16x32_bf16 v[48:51], v[142:145], v[192:195], v[48:51]
	v_mfma_f32_16x16x32_bf16 v[44:47], v[150:153], v[192:195], v[44:47]
	v_mfma_f32_16x16x32_bf16 v[30:33], v[142:145], v[204:207], v[30:33]
	v_mfma_f32_16x16x32_bf16 v[26:29], v[150:153], v[204:207], v[26:29]
	v_mfma_f32_16x16x32_bf16 v[14:17], v[142:145], v[208:211], v[14:17]
	v_mfma_f32_16x16x32_bf16 v[10:13], v[150:153], v[208:211], v[10:13]
	v_mfma_f32_16x16x32_bf16 v[56:59], v[154:157], v[176:179], v[56:59]
	v_mfma_f32_16x16x32_bf16 v[52:55], v[168:171], v[176:179], v[52:55]
	v_mfma_f32_16x16x32_bf16 v[40:43], v[154:157], v[184:187], v[40:43]
	v_mfma_f32_16x16x32_bf16 v[36:39], v[168:171], v[184:187], v[36:39]
	v_mfma_f32_16x16x32_bf16 v[22:25], v[154:157], v[196:199], v[22:25]
	v_mfma_f32_16x16x32_bf16 v[18:21], v[168:171], v[196:199], v[18:21]
	v_mfma_f32_16x16x32_bf16 v[6:9], v[154:157], v[200:203], v[6:9]
	v_mfma_f32_16x16x32_bf16 v[2:5], v[168:171], v[200:203], v[2:5]
	v_mfma_f32_16x16x32_bf16 v[56:59], v[164:167], v[188:191], v[56:59]
	v_mfma_f32_16x16x32_bf16 v[52:55], v[172:175], v[188:191], v[52:55]
	v_mfma_f32_16x16x32_bf16 v[40:43], v[164:167], v[192:195], v[40:43]
	v_mfma_f32_16x16x32_bf16 v[36:39], v[172:175], v[192:195], v[36:39]
	v_mfma_f32_16x16x32_bf16 v[22:25], v[164:167], v[204:207], v[22:25]
	v_mfma_f32_16x16x32_bf16 v[18:21], v[172:175], v[204:207], v[18:21]
	v_mfma_f32_16x16x32_bf16 v[6:9], v[164:167], v[208:211], v[6:9]
	v_mfma_f32_16x16x32_bf16 v[2:5], v[172:175], v[208:211], v[2:5]
	s_barrier
	s_add_i32 s25, 0, 0x18000
	s_add_i32 s30, 0, 0x1c000
	ds_read_b128 v[138:141], v1 offset:32768
	ds_read_b128 v[142:145], v160 offset:32768
	ds_read_b128 v[146:149], v1 offset:34816
	ds_read_b128 v[150:153], v160 offset:34816
	ds_read_b128 v[154:157], v1 offset:49152
	ds_read_b128 v[164:167], v160 offset:49152
	ds_read_b128 v[168:171], v1 offset:51200
	ds_read_b128 v[172:175], v160 offset:51200
	s_mov_b64 s[100:101], s[22:23]
	s_add_u32 s22, s22, 0x160000
	s_addc_u32 s23, s23, 0
	s_mov_b32 m0, s48
	ds_read_b128 v[176:179], v161 offset:32768
	ds_read_b128 v[184:187], v161 offset:34816
	ds_read_b128 v[188:191], v162 offset:32768
	ds_read_b128 v[192:195], v162 offset:34816
	ds_read_b128 v[196:199], v161 offset:36864
	ds_read_b128 v[200:203], v161 offset:38912
	ds_read_b128 v[204:207], v162 offset:36864
	ds_read_b128 v[208:211], v162 offset:38912
	global_load_lds_dwordx4 v136, s[22:23]
	s_mov_b32 m0, s49
	s_nop 0
	global_load_lds_dwordx4 v134, s[22:23]
	s_waitcnt vmcnt(8)
	s_waitcnt lgkmcnt(0)
	s_barrier
	v_mfma_f32_16x16x32_bf16 v[128:131], v[138:141], v[176:179], v[128:131]
	v_mfma_f32_16x16x32_bf16 v[124:127], v[146:149], v[176:179], v[124:127]
	v_mfma_f32_16x16x32_bf16 v[112:115], v[138:141], v[184:187], v[112:115]
	v_mfma_f32_16x16x32_bf16 v[108:111], v[146:149], v[184:187], v[108:111]
	v_mfma_f32_16x16x32_bf16 v[96:99], v[138:141], v[196:199], v[96:99]
	v_mfma_f32_16x16x32_bf16 v[92:95], v[146:149], v[196:199], v[92:95]
	v_mfma_f32_16x16x32_bf16 v[80:83], v[138:141], v[200:203], v[80:83]
	v_mfma_f32_16x16x32_bf16 v[76:79], v[146:149], v[200:203], v[76:79]
	v_mfma_f32_16x16x32_bf16 v[128:131], v[142:145], v[188:191], v[128:131]
	v_mfma_f32_16x16x32_bf16 v[124:127], v[150:153], v[188:191], v[124:127]
	v_mfma_f32_16x16x32_bf16 v[112:115], v[142:145], v[192:195], v[112:115]
	v_mfma_f32_16x16x32_bf16 v[108:111], v[150:153], v[192:195], v[108:111]
	v_mfma_f32_16x16x32_bf16 v[96:99], v[142:145], v[204:207], v[96:99]
	v_mfma_f32_16x16x32_bf16 v[92:95], v[150:153], v[204:207], v[92:95]
	v_mfma_f32_16x16x32_bf16 v[80:83], v[142:145], v[208:211], v[80:83]
	v_mfma_f32_16x16x32_bf16 v[76:79], v[150:153], v[208:211], v[76:79]
	v_mfma_f32_16x16x32_bf16 v[120:123], v[154:157], v[176:179], v[120:123]
	v_mfma_f32_16x16x32_bf16 v[116:119], v[168:171], v[176:179], v[116:119]
	v_mfma_f32_16x16x32_bf16 v[104:107], v[154:157], v[184:187], v[104:107]
	v_mfma_f32_16x16x32_bf16 v[100:103], v[168:171], v[184:187], v[100:103]
	v_mfma_f32_16x16x32_bf16 v[88:91], v[154:157], v[196:199], v[88:91]
	v_mfma_f32_16x16x32_bf16 v[84:87], v[168:171], v[196:199], v[84:87]
	v_mfma_f32_16x16x32_bf16 v[72:75], v[154:157], v[200:203], v[72:75]
	v_mfma_f32_16x16x32_bf16 v[68:71], v[168:171], v[200:203], v[68:71]
	v_mfma_f32_16x16x32_bf16 v[120:123], v[164:167], v[188:191], v[120:123]
	v_mfma_f32_16x16x32_bf16 v[116:119], v[172:175], v[188:191], v[116:119]
	v_mfma_f32_16x16x32_bf16 v[104:107], v[164:167], v[192:195], v[104:107]
	v_mfma_f32_16x16x32_bf16 v[100:103], v[172:175], v[192:195], v[100:103]
	v_mfma_f32_16x16x32_bf16 v[88:91], v[164:167], v[204:207], v[88:91]
	v_mfma_f32_16x16x32_bf16 v[84:87], v[172:175], v[204:207], v[84:87]
	v_mfma_f32_16x16x32_bf16 v[72:75], v[164:167], v[208:211], v[72:75]
	v_mfma_f32_16x16x32_bf16 v[68:71], v[172:175], v[208:211], v[68:71]
	s_barrier
	s_add_i32 s22, s25, s28
	s_add_i32 m0, s22, 0xffffff80
	ds_read_b128 v[176:179], v161 offset:49152
	ds_read_b128 v[184:187], v161 offset:51200
	ds_read_b128 v[188:191], v162 offset:49152
	ds_read_b128 v[192:195], v162 offset:51200
	ds_read_b128 v[196:199], v161 offset:53248
	ds_read_b128 v[200:203], v161 offset:55296
	ds_read_b128 v[204:207], v162 offset:53248
	ds_read_b128 v[208:211], v162 offset:55296
	global_load_lds_dwordx4 v34, s[18:19] offset:128
	s_add_i32 m0, s22, 0x1f80
	s_mov_b64 s[98:99], s[18:19]
	s_add_u32 s18, s18, 0x160080
	s_addc_u32 s19, s19, 0
	s_add_i32 s22, s30, s28
	global_load_lds_dwordx4 v132, s[98:99] offset:128
	s_mov_b32 m0, s22
	s_nop 0
	global_load_lds_dwordx4 v34, s[18:19]
	s_add_i32 m0, s22, 0x2000
	s_nop 0
	global_load_lds_dwordx4 v132, s[18:19]
	s_add_i32 m0, s53, 0xffffff80
	s_nop 0
	global_load_lds_dwordx4 v136, s[100:101] offset:128
	s_add_i32 m0, s54, 0xffffff80
	s_nop 0
	global_load_lds_dwordx4 v134, s[100:101] offset:128
	s_waitcnt vmcnt(8)
	s_waitcnt lgkmcnt(0)
	s_barrier
	v_mfma_f32_16x16x32_bf16 v[64:67], v[138:141], v[176:179], v[64:67]
	v_mfma_f32_16x16x32_bf16 v[60:63], v[146:149], v[176:179], v[60:63]
	v_mfma_f32_16x16x32_bf16 v[48:51], v[138:141], v[184:187], v[48:51]
	v_mfma_f32_16x16x32_bf16 v[44:47], v[146:149], v[184:187], v[44:47]
	v_mfma_f32_16x16x32_bf16 v[30:33], v[138:141], v[196:199], v[30:33]
	v_mfma_f32_16x16x32_bf16 v[26:29], v[146:149], v[196:199], v[26:29]
	v_mfma_f32_16x16x32_bf16 v[14:17], v[138:141], v[200:203], v[14:17]
	v_mfma_f32_16x16x32_bf16 v[10:13], v[146:149], v[200:203], v[10:13]
	v_mfma_f32_16x16x32_bf16 v[64:67], v[142:145], v[188:191], v[64:67]
	v_mfma_f32_16x16x32_bf16 v[60:63], v[150:153], v[188:191], v[60:63]
	v_mfma_f32_16x16x32_bf16 v[48:51], v[142:145], v[192:195], v[48:51]
	v_mfma_f32_16x16x32_bf16 v[44:47], v[150:153], v[192:195], v[44:47]
	v_mfma_f32_16x16x32_bf16 v[30:33], v[142:145], v[204:207], v[30:33]
	v_mfma_f32_16x16x32_bf16 v[26:29], v[150:153], v[204:207], v[26:29]
	v_mfma_f32_16x16x32_bf16 v[14:17], v[142:145], v[208:211], v[14:17]
	v_mfma_f32_16x16x32_bf16 v[10:13], v[150:153], v[208:211], v[10:13]
	v_mfma_f32_16x16x32_bf16 v[56:59], v[154:157], v[176:179], v[56:59]
	v_mfma_f32_16x16x32_bf16 v[52:55], v[168:171], v[176:179], v[52:55]
	v_mfma_f32_16x16x32_bf16 v[40:43], v[154:157], v[184:187], v[40:43]
	v_mfma_f32_16x16x32_bf16 v[36:39], v[168:171], v[184:187], v[36:39]
	v_mfma_f32_16x16x32_bf16 v[22:25], v[154:157], v[196:199], v[22:25]
	v_mfma_f32_16x16x32_bf16 v[18:21], v[168:171], v[196:199], v[18:21]
	v_mfma_f32_16x16x32_bf16 v[6:9], v[154:157], v[200:203], v[6:9]
	v_mfma_f32_16x16x32_bf16 v[2:5], v[168:171], v[200:203], v[2:5]
	v_mfma_f32_16x16x32_bf16 v[56:59], v[164:167], v[188:191], v[56:59]
	v_mfma_f32_16x16x32_bf16 v[52:55], v[172:175], v[188:191], v[52:55]
	v_mfma_f32_16x16x32_bf16 v[40:43], v[164:167], v[192:195], v[40:43]
	v_mfma_f32_16x16x32_bf16 v[36:39], v[172:175], v[192:195], v[36:39]
	v_mfma_f32_16x16x32_bf16 v[22:25], v[164:167], v[204:207], v[22:25]
	v_mfma_f32_16x16x32_bf16 v[18:21], v[172:175], v[204:207], v[18:21]
	v_mfma_f32_16x16x32_bf16 v[6:9], v[164:167], v[208:211], v[6:9]
	v_mfma_f32_16x16x32_bf16 v[2:5], v[172:175], v[208:211], v[2:5]
	s_barrier
	s_add_i32 s24, s24, 2
	s_add_u32 s8, s8, 0x100
	s_addc_u32 s9, s9, 0
	s_add_u32 s20, s20, 0x100
	s_addc_u32 s21, s21, 0
	s_cmpk_gt_u32 s24, 0x55
	s_cbranch_scc0 .LBB0_1195
